# stack_i + loop-invariant B-fragment LDS base register (per-segment v_add_u32 removed from the K-loops)
# baseline (speedup 1.0000x reference)
;     __host__ __device__ bool next(int i, Unit& u) const { const int t = i / 3, b = i - 3 * t; Unit v; if (!StaticOrder::next(t, v)) return false; u.pm = v.pm; u.pn = 8 * b + v.pn; return true; }
; #define PG8_STAGE(bufoff, gbase, voff) do { const int so_ = (int)(unsigned)((const char*)(gbase) - base_##voff); _Pragma("unroll") for (int _i = 0; _i < 2; ++_i) \
;         __builtin_amdgcn_raw_ptr_buffer_load_lds(rs_##voff, (PG8_LAS unsigned*)(lds + (bufoff) + ldsw + _i * 8192), 16, (int)(voff)[_i], so_, 0, 0); } while (0)
; #define PG8_LDA(dst, b, h) do { _Pragma("unroll") for (int m = 0; m < 4; ++m) _Pragma("unroll") for (int k = 0; k < 2; ++k) dst[m][k] = *(const PG8_LAS bf16x8*)(lds + PG8_SA(b, h) + aoff + m * 2048 + k * 1024); } while (0)
; #define PG8_LDB(dst, b, h) do { _Pragma("unroll") for (int n = 0; n < 2; ++n) _Pragma("unroll") for (int k = 0; k < 2; ++k) dst[n][k] = *(const PG8_LAS bf16x8*)(lds + PG8_SB(b, h) + boff + n * 2048 + k * 1024); } while (0)
; #define PG8_SCHED __builtin_amdgcn_sched_barrier(0)
; template <class Epi, class Sched, bool ALIGN_EPI = false, bool SP2 = false>
; __device__ __forceinline__ void gemm_phase(PG8_LAS unsigned char* lds, const Gemm g, const Sched& S, const Epi& E, int tid_in) {
;     ...
;         const bool has_next = S.next(ui + 1, nxt);
;         const char* nA = has_next ? (const char*)g.A + (size_t)nxt.pm * tstepA + (g.grp ? (size_t)(nxt.pn / g.grp) * g.agrp : (size_t)0) : cA; const char* nB = has_next ? (const char*)g.Bt + (size_t)nxt.pn * tstepB : cB;
;         for (int t = 0; t < nt; t += 2) {
;             const bool last = (t == nt - 2);
;             const char* a1 = cA + (size_t)(t + 1) * kstep;
;             const char* a2 = last ? nA : cA + (size_t)(t + 2) * kstep; const char* b2 = last ? nB : cB + (size_t)(t + 2) * kstep;
;             const char* a3 = a2 + kstep; const char* b3 = b2 + kstep;
;             if (last && has_next) S.a_ready(nxt);
;             if constexpr (SP2) {
;             PG8_LDB(B0, 0, 0); PG8_LDB(B1, 0, 1); PG8_SCHED; PG8_LDA(At, 0, 0); PG8_STAGE(PG8_SA(1, 1), a1 + hstepA, voffA);
.LBB0_311:
	s_ashr_i32 s23, s22, 31
	s_lshl_b64 s[10:11], s[22:23], 20
	s_add_u32 s24, s4, s10
	s_addc_u32 s25, s26, s11
	s_and_b64 s[10:11], s[34:35], exec
	s_cselect_b32 s19, s24, s12
	s_ashr_i32 s15, s14, 31
	s_lshl_b64 s[10:11], s[14:15], 20
	s_add_u32 s10, s40, s10
	s_addc_u32 s11, s60, s11
	s_and_b64 s[20:21], s[34:35], exec
	s_cselect_b32 s15, s10, s16
	s_add_u32 s20, s16, 0x100
	v_mov_b32_e32 v2, 0
	s_addc_u32 s21, s17, 0
	s_mov_b32 s23, -2
	v_add_u32_e32 v251, 0x10000, v237

; #define PG8_STAGE(bufoff, gbase, voff) do { const int so_ = (int)(unsigned)((const char*)(gbase) - base_##voff); _Pragma("unroll") for (int _i = 0; _i < 2; ++_i) \
;         __builtin_amdgcn_raw_ptr_buffer_load_lds(rs_##voff, (PG8_LAS unsigned*)(lds + (bufoff) + ldsw + _i * 8192), 16, (int)(voff)[_i], so_, 0, 0); } while (0)
; #define PG8_LDA(dst, b, h) do { _Pragma("unroll") for (int m = 0; m < 4; ++m) _Pragma("unroll") for (int k = 0; k < 2; ++k) dst[m][k] = *(const PG8_LAS bf16x8*)(lds + PG8_SA(b, h) + aoff + m * 2048 + k * 1024); } while (0)
; #define PG8_LDB(dst, b, h) do { _Pragma("unroll") for (int n = 0; n < 2; ++n) _Pragma("unroll") for (int k = 0; k < 2; ++k) dst[n][k] = *(const PG8_LAS bf16x8*)(lds + PG8_SB(b, h) + boff + n * 2048 + k * 1024); } while (0)
; #define PG8_MMA(ai, bj, At, Bt) do { __builtin_amdgcn_s_setprio(1); _Pragma("unroll") for (int m = 0; m < 4; ++m) _Pragma("unroll") for (int n = 0; n < 2; ++n) _Pragma("unroll") for (int k = 0; k < 2; ++k) \
;         acc[ai][bj][m][n] = __builtin_amdgcn_mfma_f32_16x16x32_bf16(Bt[n][k], At[m][k], acc[ai][bj][m][n], 0, 0, 0); __builtin_amdgcn_s_setprio(0); } while (0)
; #define PG8_WAIT_V(n) asm volatile("s_waitcnt vmcnt(" #n ")" ::: "memory")
; #define PG8_WAIT_L(n) asm volatile("s_waitcnt lgkmcnt(" #n ")" ::: "memory")
; #define PG8_BAR __builtin_amdgcn_s_barrier()
; #define PG8_SCHED __builtin_amdgcn_sched_barrier(0)
; template <class Epi, class Sched, bool ALIGN_EPI = false, bool SP2 = false>
; __device__ __forceinline__ void gemm_phase(PG8_LAS unsigned char* lds, const Gemm g, const Sched& S, const Epi& E, int tid_in) {
;     ...
;             PG8_LDB(B0, 0, 0); PG8_LDB(B1, 0, 1); PG8_SCHED; PG8_LDA(At, 0, 0); PG8_STAGE(PG8_SA(1, 1), a1 + hstepA, voffA);
;             PG8_WAIT_V(8); PG8_WAIT_L(0); PG8_BAR; PG8_MMA(0, 0, At, B0); PG8_MMA(0, 1, At, B1); PG8_BAR; PG8_SCHED;
;             PG8_LDA(At, 0, 1); PG8_STAGE(PG8_SB(0, 0), b2, voffB); PG8_STAGE(PG8_SB(0, 1), b2 + hstepB, voffB); PG8_STAGE(PG8_SA(0, 0), a2, voffA);
;             PG8_WAIT_V(8); PG8_WAIT_L(0); PG8_BAR; PG8_MMA(1, 0, At, B0); PG8_MMA(1, 1, At, B1); PG8_BAR; PG8_SCHED;
	ds_read_b128 v[130:133], v251
	ds_read_b128 v[134:137], v251 offset:1024
	ds_read_b128 v[138:141], v251 offset:2048
	ds_read_b128 v[142:145], v251 offset:3072
	ds_read_b128 v[146:149], v251 offset:16384
	ds_read_b128 v[150:153], v251 offset:17408
	ds_read_b128 v[154:157], v251 offset:18432
	ds_read_b128 v[158:161], v251 offset:19456
	s_add_u32 s16, s12, 0x100
	s_addc_u32 s17, s13, 0
	s_sub_i32 s12, s12, s4
	s_add_i32 s12, s12, 0x80080
	s_sub_i32 s36, s12, 0x80000
	s_cmp_eq_u32 s23, 28
	s_cselect_b32 s13, s19, s16
	s_mov_b32 m0, s69
	ds_read_b128 v[162:165], v238
	ds_read_b128 v[166:169], v238 offset:1024
	ds_read_b128 v[170:173], v238 offset:2048
	ds_read_b128 v[174:177], v238 offset:3072
	ds_read_b128 v[178:181], v238 offset:4096
	ds_read_b128 v[182:185], v238 offset:5120
	ds_read_b128 v[186:189], v238 offset:6144
	ds_read_b128 v[190:193], v238 offset:7168
	s_mov_b32 m0, s78
	s_nop 0
	buffer_load_dwordx4 v211, s[4:7], s36 offen lds
	s_mov_b32 m0, s69
	s_nop 0
	buffer_load_dwordx4 v195, s[4:7], s12 offen lds
	s_mov_b32 m0, s67
	s_nop 0
	buffer_load_dwordx4 v211, s[4:7], s12 offen lds
	s_waitcnt vmcnt(8)
	s_waitcnt lgkmcnt(0)
	s_setprio 1
	s_barrier
	v_mfma_f32_16x16x32_bf16 v[126:129], v[130:133], v[162:165], 0
	v_mfma_f32_16x16x32_bf16 v[122:125], v[138:141], v[162:165], 0
	v_mfma_f32_16x16x32_bf16 v[106:109], v[138:141], v[170:173], 0
	v_mfma_f32_16x16x32_bf16 v[110:113], v[130:133], v[170:173], 0
	v_mfma_f32_16x16x32_bf16 v[94:97], v[130:133], v[178:181], 0
	v_mfma_f32_16x16x32_bf16 v[90:93], v[138:141], v[178:181], 0
	v_mfma_f32_16x16x32_bf16 v[74:77], v[138:141], v[186:189], 0
	v_mfma_f32_16x16x32_bf16 v[78:81], v[130:133], v[186:189], 0
	v_mfma_f32_16x16x32_bf16 v[126:129], v[134:137], v[166:169], v[126:129]
	v_mfma_f32_16x16x32_bf16 v[122:125], v[142:145], v[166:169], v[122:125]
	v_mfma_f32_16x16x32_bf16 v[106:109], v[142:145], v[174:177], v[106:109]
	v_mfma_f32_16x16x32_bf16 v[110:113], v[134:137], v[174:177], v[110:113]
	v_mfma_f32_16x16x32_bf16 v[94:97], v[134:137], v[182:185], v[94:97]
	v_mfma_f32_16x16x32_bf16 v[90:93], v[142:145], v[182:185], v[90:93]
	v_mfma_f32_16x16x32_bf16 v[74:77], v[142:145], v[190:193], v[74:77]
	v_mfma_f32_16x16x32_bf16 v[78:81], v[134:137], v[190:193], v[78:81]
	v_mfma_f32_16x16x32_bf16 v[118:121], v[146:149], v[162:165], 0
	v_mfma_f32_16x16x32_bf16 v[114:117], v[154:157], v[162:165], 0
	v_mfma_f32_16x16x32_bf16 v[98:101], v[154:157], v[170:173], 0
	v_mfma_f32_16x16x32_bf16 v[102:105], v[146:149], v[170:173], 0
	v_mfma_f32_16x16x32_bf16 v[86:89], v[146:149], v[178:181], 0
	v_mfma_f32_16x16x32_bf16 v[82:85], v[154:157], v[178:181], 0
	v_mfma_f32_16x16x32_bf16 v[66:69], v[154:157], v[186:189], 0
	v_mfma_f32_16x16x32_bf16 v[70:73], v[146:149], v[186:189], 0
	v_mfma_f32_16x16x32_bf16 v[118:121], v[150:153], v[166:169], v[118:121]
	v_mfma_f32_16x16x32_bf16 v[114:117], v[158:161], v[166:169], v[114:117]
	v_mfma_f32_16x16x32_bf16 v[98:101], v[158:161], v[174:177], v[98:101]
	v_mfma_f32_16x16x32_bf16 v[102:105], v[150:153], v[174:177], v[102:105]
	v_mfma_f32_16x16x32_bf16 v[86:89], v[150:153], v[182:185], v[86:89]
	v_mfma_f32_16x16x32_bf16 v[82:85], v[158:161], v[182:185], v[82:85]
	v_mfma_f32_16x16x32_bf16 v[66:69], v[158:161], v[190:193], v[66:69]
	v_mfma_f32_16x16x32_bf16 v[70:73], v[150:153], v[190:193], v[70:73]
	s_barrier
	s_setprio 0
	s_cselect_b32 s12, s15, s20
	s_mov_b32 m0, s61
	s_mov_b32 s42, s6
	s_mov_b32 s43, s7
	s_sub_i32 s12, s12, s40
	ds_read_b128 v[162:165], v238 offset:16384
	ds_read_b128 v[166:169], v238 offset:17408
	ds_read_b128 v[170:173], v238 offset:18432
	ds_read_b128 v[174:177], v238 offset:19456
	ds_read_b128 v[178:181], v238 offset:20480
	ds_read_b128 v[182:185], v238 offset:21504
	ds_read_b128 v[186:189], v238 offset:22528
	ds_read_b128 v[190:193], v238 offset:23552
	buffer_load_dwordx4 v207, s[40:43], s12 offen lds
	s_mov_b32 m0, s62
	s_add_i32 s36, s12, 0x80000
	buffer_load_dwordx4 v224, s[40:43], s12 offen lds
	s_mov_b32 m0, s63
	s_sub_i32 s13, s13, s4
	buffer_load_dwordx4 v207, s[40:43], s36 offen lds
	s_mov_b32 m0, s71
	s_nop 0
	buffer_load_dwordx4 v224, s[40:43], s36 offen lds
	s_mov_b32 m0, s53
	s_nop 0
	buffer_load_dwordx4 v195, s[4:7], s13 offen lds
	s_waitcnt vmcnt(7)
	s_waitcnt lgkmcnt(0)
	s_setprio 1
	s_barrier
	v_mfma_f32_16x16x32_bf16 v[62:65], v[130:133], v[162:165], 0
	v_mfma_f32_16x16x32_bf16 v[58:61], v[138:141], v[162:165], 0
	v_mfma_f32_16x16x32_bf16 v[42:45], v[138:141], v[170:173], 0
	v_mfma_f32_16x16x32_bf16 v[46:49], v[130:133], v[170:173], 0
	v_mfma_f32_16x16x32_bf16 v[30:33], v[130:133], v[178:181], 0
	v_mfma_f32_16x16x32_bf16 v[26:29], v[138:141], v[178:181], 0
	v_mfma_f32_16x16x32_bf16 v[10:13], v[138:141], v[186:189], 0
	v_mfma_f32_16x16x32_bf16 v[14:17], v[130:133], v[186:189], 0
	v_mfma_f32_16x16x32_bf16 v[62:65], v[134:137], v[166:169], v[62:65]
	v_mfma_f32_16x16x32_bf16 v[58:61], v[142:145], v[166:169], v[58:61]
	v_mfma_f32_16x16x32_bf16 v[42:45], v[142:145], v[174:177], v[42:45]
	v_mfma_f32_16x16x32_bf16 v[46:49], v[134:137], v[174:177], v[46:49]
	v_mfma_f32_16x16x32_bf16 v[30:33], v[134:137], v[182:185], v[30:33]
	v_mfma_f32_16x16x32_bf16 v[26:29], v[142:145], v[182:185], v[26:29]
	v_mfma_f32_16x16x32_bf16 v[10:13], v[142:145], v[190:193], v[10:13]
	v_mfma_f32_16x16x32_bf16 v[14:17], v[134:137], v[190:193], v[14:17]
	v_mfma_f32_16x16x32_bf16 v[54:57], v[146:149], v[162:165], 0
	v_mfma_f32_16x16x32_bf16 v[50:53], v[154:157], v[162:165], 0
	v_mfma_f32_16x16x32_bf16 v[34:37], v[154:157], v[170:173], 0
	v_mfma_f32_16x16x32_bf16 v[38:41], v[146:149], v[170:173], 0
	v_mfma_f32_16x16x32_bf16 v[22:25], v[146:149], v[178:181], 0
	v_mfma_f32_16x16x32_bf16 v[18:21], v[154:157], v[178:181], 0
	v_mfma_f32_16x16x32_bf16 v[2:5], v[154:157], v[186:189], 0
	v_mfma_f32_16x16x32_bf16 v[6:9], v[146:149], v[186:189], 0
	v_mfma_f32_16x16x32_bf16 v[54:57], v[150:153], v[166:169], v[54:57]
	v_mfma_f32_16x16x32_bf16 v[50:53], v[158:161], v[166:169], v[50:53]
	v_mfma_f32_16x16x32_bf16 v[34:37], v[158:161], v[174:177], v[34:37]
	v_mfma_f32_16x16x32_bf16 v[38:41], v[150:153], v[174:177], v[38:41]
	v_mfma_f32_16x16x32_bf16 v[22:25], v[150:153], v[182:185], v[22:25]
	v_mfma_f32_16x16x32_bf16 v[18:21], v[158:161], v[182:185], v[18:21]
	v_mfma_f32_16x16x32_bf16 v[2:5], v[158:161], v[190:193], v[2:5]
	v_mfma_f32_16x16x32_bf16 v[6:9], v[150:153], v[190:193], v[6:9]
	s_barrier
; #define PG8_STAGE(bufoff, gbase, voff) do { const int so_ = (int)(unsigned)((const char*)(gbase) - base_##voff); _Pragma("unroll") for (int _i = 0; _i < 2; ++_i) \
;         __builtin_amdgcn_raw_ptr_buffer_load_lds(rs_##voff, (PG8_LAS unsigned*)(lds + (bufoff) + ldsw + _i * 8192), 16, (int)(voff)[_i], so_, 0, 0); } while (0)
; #define PG8_LDA(dst, b, h) do { _Pragma("unroll") for (int m = 0; m < 4; ++m) _Pragma("unroll") for (int k = 0; k < 2; ++k) dst[m][k] = *(const PG8_LAS bf16x8*)(lds + PG8_SA(b, h) + aoff + m * 2048 + k * 1024); } while (0)
; #define PG8_LDB(dst, b, h) do { _Pragma("unroll") for (int n = 0; n < 2; ++n) _Pragma("unroll") for (int k = 0; k < 2; ++k) dst[n][k] = *(const PG8_LAS bf16x8*)(lds + PG8_SB(b, h) + boff + n * 2048 + k * 1024); } while (0)
; #define PG8_MMA(ai, bj, At, Bt) do { __builtin_amdgcn_s_setprio(1); _Pragma("unroll") for (int m = 0; m < 4; ++m) _Pragma("unroll") for (int n = 0; n < 2; ++n) _Pragma("unroll") for (int k = 0; k < 2; ++k) \
;         acc[ai][bj][m][n] = __builtin_amdgcn_mfma_f32_16x16x32_bf16(Bt[n][k], At[m][k], acc[ai][bj][m][n], 0, 0, 0); __builtin_amdgcn_s_setprio(0); } while (0)
; #define PG8_WAIT_V(n) asm volatile("s_waitcnt vmcnt(" #n ")" ::: "memory")
; #define PG8_WAIT_L(n) asm volatile("s_waitcnt lgkmcnt(" #n ")" ::: "memory")
; #define PG8_BAR __builtin_amdgcn_s_barrier()
; #define PG8_SCHED __builtin_amdgcn_sched_barrier(0)
; template <class Epi, class Sched, bool ALIGN_EPI = false, bool SP2 = false>
; __device__ __forceinline__ void gemm_phase(PG8_LAS unsigned char* lds, const Gemm g, const Sched& S, const Epi& E, int tid_in) {
;     ...
;             PG8_LDB(B0, 1, 0); PG8_LDB(B1, 1, 1); PG8_SCHED; PG8_LDA(At, 1, 0); PG8_STAGE(PG8_SA(0, 1), a2 + hstepA, voffA);
;             PG8_WAIT_V(8); PG8_WAIT_L(0); PG8_BAR; PG8_MMA(0, 0, At, B0); PG8_MMA(0, 1, At, B1); PG8_BAR; PG8_SCHED;
;             PG8_LDA(At, 1, 1); PG8_STAGE(PG8_SB(1, 0), b3, voffB); PG8_STAGE(PG8_SB(1, 1), b3 + hstepB, voffB); PG8_STAGE(PG8_SA(1, 0), a3, voffA);
;             PG8_WAIT_V(8); PG8_WAIT_L(0); PG8_BAR; PG8_MMA(1, 0, At, B0); PG8_MMA(1, 1, At, B1); PG8_BAR; PG8_SCHED;
	s_setprio 0
	ds_read_b128 v[130:133], v251 offset:32768
	ds_read_b128 v[134:137], v251 offset:33792
	ds_read_b128 v[138:141], v251 offset:34816
	ds_read_b128 v[142:145], v251 offset:35840
	ds_read_b128 v[146:149], v251 offset:49152
	ds_read_b128 v[150:153], v251 offset:50176
	ds_read_b128 v[154:157], v251 offset:51200
	ds_read_b128 v[158:161], v251 offset:52224
	s_add_i32 s36, s13, 0x80000
	s_mov_b32 m0, s73
	ds_read_b128 v[162:165], v238 offset:32768
	ds_read_b128 v[166:169], v238 offset:33792
	ds_read_b128 v[170:173], v238 offset:34816
	ds_read_b128 v[174:177], v238 offset:35840
	ds_read_b128 v[178:181], v238 offset:36864
	ds_read_b128 v[182:185], v238 offset:37888
	ds_read_b128 v[186:189], v238 offset:38912
	ds_read_b128 v[190:193], v238 offset:39936
	s_mov_b32 m0, s72
	s_nop 0
	buffer_load_dwordx4 v211, s[4:7], s13 offen lds
	s_mov_b32 m0, s73
	s_nop 0
	buffer_load_dwordx4 v195, s[4:7], s36 offen lds
	s_mov_b32 m0, s74
	s_nop 0
	buffer_load_dwordx4 v211, s[4:7], s36 offen lds
	s_waitcnt vmcnt(8)
	s_waitcnt lgkmcnt(0)
	s_setprio 1
	s_barrier
	v_mfma_f32_16x16x32_bf16 v[126:129], v[130:133], v[162:165], v[126:129]
	v_mfma_f32_16x16x32_bf16 v[122:125], v[138:141], v[162:165], v[122:125]
	v_mfma_f32_16x16x32_bf16 v[106:109], v[138:141], v[170:173], v[106:109]
	v_mfma_f32_16x16x32_bf16 v[110:113], v[130:133], v[170:173], v[110:113]
	v_mfma_f32_16x16x32_bf16 v[94:97], v[130:133], v[178:181], v[94:97]
	v_mfma_f32_16x16x32_bf16 v[90:93], v[138:141], v[178:181], v[90:93]
	v_mfma_f32_16x16x32_bf16 v[74:77], v[138:141], v[186:189], v[74:77]
	v_mfma_f32_16x16x32_bf16 v[78:81], v[130:133], v[186:189], v[78:81]
	v_mfma_f32_16x16x32_bf16 v[126:129], v[134:137], v[166:169], v[126:129]
	v_mfma_f32_16x16x32_bf16 v[122:125], v[142:145], v[166:169], v[122:125]
	v_mfma_f32_16x16x32_bf16 v[106:109], v[142:145], v[174:177], v[106:109]
	v_mfma_f32_16x16x32_bf16 v[110:113], v[134:137], v[174:177], v[110:113]
	v_mfma_f32_16x16x32_bf16 v[94:97], v[134:137], v[182:185], v[94:97]
	v_mfma_f32_16x16x32_bf16 v[90:93], v[142:145], v[182:185], v[90:93]
	v_mfma_f32_16x16x32_bf16 v[74:77], v[142:145], v[190:193], v[74:77]
	v_mfma_f32_16x16x32_bf16 v[78:81], v[134:137], v[190:193], v[78:81]
	v_mfma_f32_16x16x32_bf16 v[118:121], v[146:149], v[162:165], v[118:121]
	v_mfma_f32_16x16x32_bf16 v[114:117], v[154:157], v[162:165], v[114:117]
	v_mfma_f32_16x16x32_bf16 v[98:101], v[154:157], v[170:173], v[98:101]
	v_mfma_f32_16x16x32_bf16 v[102:105], v[146:149], v[170:173], v[102:105]
	v_mfma_f32_16x16x32_bf16 v[86:89], v[146:149], v[178:181], v[86:89]
	v_mfma_f32_16x16x32_bf16 v[82:85], v[154:157], v[178:181], v[82:85]
	v_mfma_f32_16x16x32_bf16 v[66:69], v[154:157], v[186:189], v[66:69]
	v_mfma_f32_16x16x32_bf16 v[70:73], v[146:149], v[186:189], v[70:73]
	v_mfma_f32_16x16x32_bf16 v[118:121], v[150:153], v[166:169], v[118:121]
	v_mfma_f32_16x16x32_bf16 v[114:117], v[158:161], v[166:169], v[114:117]
	v_mfma_f32_16x16x32_bf16 v[98:101], v[158:161], v[174:177], v[98:101]
	v_mfma_f32_16x16x32_bf16 v[102:105], v[150:153], v[174:177], v[102:105]
	v_mfma_f32_16x16x32_bf16 v[86:89], v[150:153], v[182:185], v[86:89]
	v_mfma_f32_16x16x32_bf16 v[82:85], v[158:161], v[182:185], v[82:85]
	v_mfma_f32_16x16x32_bf16 v[66:69], v[158:161], v[190:193], v[66:69]
	v_mfma_f32_16x16x32_bf16 v[70:73], v[150:153], v[190:193], v[70:73]
	s_barrier
	s_setprio 0
	s_mov_b32 m0, s75
	s_add_i32 s36, s12, 0x80
	ds_read_b128 v[162:165], v238 offset:49152
	ds_read_b128 v[166:169], v238 offset:50176
	ds_read_b128 v[170:173], v238 offset:51200
	ds_read_b128 v[174:177], v238 offset:52224
	ds_read_b128 v[178:181], v238 offset:53248
	ds_read_b128 v[182:185], v238 offset:54272
	ds_read_b128 v[186:189], v238 offset:55296
	ds_read_b128 v[190:193], v238 offset:56320
	buffer_load_dwordx4 v207, s[40:43], s36 offen lds
	s_mov_b32 m0, s76
	s_add_i32 s12, s12, 0x80080
	buffer_load_dwordx4 v224, s[40:43], s36 offen lds
	s_mov_b32 m0, s79
	s_addk_i32 s13, 0x80
	buffer_load_dwordx4 v207, s[40:43], s12 offen lds
	s_mov_b32 m0, s68
	s_nop 0
	buffer_load_dwordx4 v224, s[40:43], s12 offen lds
	s_mov_b32 m0, s77
	s_nop 0
	buffer_load_dwordx4 v195, s[4:7], s13 offen lds
	s_waitcnt vmcnt(7)
	s_waitcnt lgkmcnt(0)
	s_setprio 1
	s_barrier
	v_mfma_f32_16x16x32_bf16 v[62:65], v[130:133], v[162:165], v[62:65]
	v_mfma_f32_16x16x32_bf16 v[58:61], v[138:141], v[162:165], v[58:61]
	v_mfma_f32_16x16x32_bf16 v[42:45], v[138:141], v[170:173], v[42:45]
	v_mfma_f32_16x16x32_bf16 v[46:49], v[130:133], v[170:173], v[46:49]
	v_mfma_f32_16x16x32_bf16 v[30:33], v[130:133], v[178:181], v[30:33]
	v_mfma_f32_16x16x32_bf16 v[26:29], v[138:141], v[178:181], v[26:29]
	v_mfma_f32_16x16x32_bf16 v[10:13], v[138:141], v[186:189], v[10:13]
	v_mfma_f32_16x16x32_bf16 v[14:17], v[130:133], v[186:189], v[14:17]
	v_mfma_f32_16x16x32_bf16 v[62:65], v[134:137], v[166:169], v[62:65]
	v_mfma_f32_16x16x32_bf16 v[58:61], v[142:145], v[166:169], v[58:61]
	v_mfma_f32_16x16x32_bf16 v[42:45], v[142:145], v[174:177], v[42:45]
	v_mfma_f32_16x16x32_bf16 v[46:49], v[134:137], v[174:177], v[46:49]
	v_mfma_f32_16x16x32_bf16 v[30:33], v[134:137], v[182:185], v[30:33]
	v_mfma_f32_16x16x32_bf16 v[26:29], v[142:145], v[182:185], v[26:29]
	v_mfma_f32_16x16x32_bf16 v[10:13], v[142:145], v[190:193], v[10:13]
	v_mfma_f32_16x16x32_bf16 v[14:17], v[134:137], v[190:193], v[14:17]
	v_mfma_f32_16x16x32_bf16 v[54:57], v[146:149], v[162:165], v[54:57]
	v_mfma_f32_16x16x32_bf16 v[50:53], v[154:157], v[162:165], v[50:53]
	v_mfma_f32_16x16x32_bf16 v[34:37], v[154:157], v[170:173], v[34:37]
	v_mfma_f32_16x16x32_bf16 v[38:41], v[146:149], v[170:173], v[38:41]
	v_mfma_f32_16x16x32_bf16 v[22:25], v[146:149], v[178:181], v[22:25]
	v_mfma_f32_16x16x32_bf16 v[18:21], v[154:157], v[178:181], v[18:21]
	v_mfma_f32_16x16x32_bf16 v[2:5], v[154:157], v[186:189], v[2:5]
	v_mfma_f32_16x16x32_bf16 v[6:9], v[146:149], v[186:189], v[6:9]
	v_mfma_f32_16x16x32_bf16 v[54:57], v[150:153], v[166:169], v[54:57]
	v_mfma_f32_16x16x32_bf16 v[50:53], v[158:161], v[166:169], v[50:53]
	v_mfma_f32_16x16x32_bf16 v[34:37], v[158:161], v[174:177], v[34:37]
	v_mfma_f32_16x16x32_bf16 v[38:41], v[150:153], v[174:177], v[38:41]
	v_mfma_f32_16x16x32_bf16 v[22:25], v[150:153], v[182:185], v[22:25]
	v_mfma_f32_16x16x32_bf16 v[18:21], v[158:161], v[182:185], v[18:21]
	v_mfma_f32_16x16x32_bf16 v[2:5], v[158:161], v[190:193], v[2:5]
	v_mfma_f32_16x16x32_bf16 v[6:9], v[150:153], v[190:193], v[6:9]
	s_barrier
	s_setprio 0
	s_add_i32 s23, s23, 2
	s_add_u32 s20, s20, 0x100
	s_addc_u32 s21, s21, 0
	s_cmp_gt_u32 s23, 29
	s_mov_b64 s[12:13], s[16:17]
; #define PG8_STAGE(bufoff, gbase, voff) do { const int so_ = (int)(unsigned)((const char*)(gbase) - base_##voff); _Pragma("unroll") for (int _i = 0; _i < 2; ++_i) \
;         __builtin_amdgcn_raw_ptr_buffer_load_lds(rs_##voff, (PG8_LAS unsigned*)(lds + (bufoff) + ldsw + _i * 8192), 16, (int)(voff)[_i], so_, 0, 0); } while (0)
; #define PG8_LDA(dst, b, h) do { _Pragma("unroll") for (int m = 0; m < 4; ++m) _Pragma("unroll") for (int k = 0; k < 2; ++k) dst[m][k] = *(const PG8_LAS bf16x8*)(lds + PG8_SA(b, h) + aoff + m * 2048 + k * 1024); } while (0)
; #define PG8_LDB(dst, b, h) do { _Pragma("unroll") for (int n = 0; n < 2; ++n) _Pragma("unroll") for (int k = 0; k < 2; ++k) dst[n][k] = *(const PG8_LAS bf16x8*)(lds + PG8_SB(b, h) + boff + n * 2048 + k * 1024); } while (0)
; #define PG8_MMA(ai, bj, At, Bt) do { __builtin_amdgcn_s_setprio(1); _Pragma("unroll") for (int m = 0; m < 4; ++m) _Pragma("unroll") for (int n = 0; n < 2; ++n) _Pragma("unroll") for (int k = 0; k < 2; ++k) \
;         acc[ai][bj][m][n] = __builtin_amdgcn_mfma_f32_16x16x32_bf16(Bt[n][k], At[m][k], acc[ai][bj][m][n], 0, 0, 0); __builtin_amdgcn_s_setprio(0); } while (0)
; #define PG8_WAIT_V(n) asm volatile("s_waitcnt vmcnt(" #n ")" ::: "memory")
; #define PG8_WAIT_L(n) asm volatile("s_waitcnt lgkmcnt(" #n ")" ::: "memory")
; #define PG8_BAR __builtin_amdgcn_s_barrier()
; #define PG8_SCHED __builtin_amdgcn_sched_barrier(0)
; template <class Epi, class Sched, bool ALIGN_EPI = false, bool SP2 = false>
; __device__ __forceinline__ void gemm_phase(PG8_LAS unsigned char* lds, const Gemm g, const Sched& S, const Epi& E, int tid_in) {
;     ...
;             PG8_LDB(B0, 0, 0); PG8_LDB(B1, 0, 1); PG8_SCHED; PG8_LDA(At, 0, 0); PG8_STAGE(PG8_SA(1, 1), a1 + hstepA, voffA);
;             PG8_WAIT_V(8); PG8_WAIT_L(0); PG8_BAR; PG8_MMA(0, 0, At, B0); PG8_MMA(0, 1, At, B1); PG8_BAR; PG8_SCHED;
;             PG8_LDA(At, 0, 1); PG8_STAGE(PG8_SB(0, 0), b2, voffB); PG8_STAGE(PG8_SB(0, 1), b2 + hstepB, voffB); PG8_STAGE(PG8_SA(0, 0), a2, voffA);
;             PG8_WAIT_V(8); PG8_WAIT_L(0); PG8_BAR; PG8_MMA(1, 0, At, B0); PG8_MMA(1, 1, At, B1); PG8_BAR; PG8_SCHED;
.LBB0_312:
	ds_read_b128 v[130:133], v251
	ds_read_b128 v[134:137], v251 offset:1024
	ds_read_b128 v[138:141], v251 offset:2048
	ds_read_b128 v[142:145], v251 offset:3072
	ds_read_b128 v[146:149], v251 offset:16384
	ds_read_b128 v[150:153], v251 offset:17408
	ds_read_b128 v[154:157], v251 offset:18432
	ds_read_b128 v[158:161], v251 offset:19456
	s_add_u32 s16, s12, 0x100
	s_addc_u32 s17, s13, 0
	s_sub_i32 s12, s12, s4
	s_add_i32 s12, s12, 0x80080
	s_sub_i32 s36, s12, 0x80000
	s_cmp_eq_u32 s23, 28
	s_cselect_b32 s13, s19, s16
	s_mov_b32 m0, s69
	ds_read_b128 v[162:165], v238
	ds_read_b128 v[166:169], v238 offset:1024
	ds_read_b128 v[170:173], v238 offset:2048
	ds_read_b128 v[174:177], v238 offset:3072
	ds_read_b128 v[178:181], v238 offset:4096
	ds_read_b128 v[182:185], v238 offset:5120
	ds_read_b128 v[186:189], v238 offset:6144
	ds_read_b128 v[190:193], v238 offset:7168
	s_mov_b32 m0, s78
	s_nop 0
	buffer_load_dwordx4 v211, s[4:7], s36 offen lds
	s_mov_b32 m0, s69
	s_nop 0
	buffer_load_dwordx4 v195, s[4:7], s12 offen lds
	s_mov_b32 m0, s67
	s_nop 0
	buffer_load_dwordx4 v211, s[4:7], s12 offen lds
	s_waitcnt vmcnt(8)
	s_waitcnt lgkmcnt(0)
	s_setprio 1
	s_barrier
	v_mfma_f32_16x16x32_bf16 v[126:129], v[130:133], v[162:165], v[126:129]
	v_mfma_f32_16x16x32_bf16 v[122:125], v[138:141], v[162:165], v[122:125]
	v_mfma_f32_16x16x32_bf16 v[106:109], v[138:141], v[170:173], v[106:109]
	v_mfma_f32_16x16x32_bf16 v[110:113], v[130:133], v[170:173], v[110:113]
	v_mfma_f32_16x16x32_bf16 v[94:97], v[130:133], v[178:181], v[94:97]
	v_mfma_f32_16x16x32_bf16 v[90:93], v[138:141], v[178:181], v[90:93]
	v_mfma_f32_16x16x32_bf16 v[74:77], v[138:141], v[186:189], v[74:77]
	v_mfma_f32_16x16x32_bf16 v[78:81], v[130:133], v[186:189], v[78:81]
	v_mfma_f32_16x16x32_bf16 v[126:129], v[134:137], v[166:169], v[126:129]
	v_mfma_f32_16x16x32_bf16 v[122:125], v[142:145], v[166:169], v[122:125]
	v_mfma_f32_16x16x32_bf16 v[106:109], v[142:145], v[174:177], v[106:109]
	v_mfma_f32_16x16x32_bf16 v[110:113], v[134:137], v[174:177], v[110:113]
	v_mfma_f32_16x16x32_bf16 v[94:97], v[134:137], v[182:185], v[94:97]
	v_mfma_f32_16x16x32_bf16 v[90:93], v[142:145], v[182:185], v[90:93]
	v_mfma_f32_16x16x32_bf16 v[74:77], v[142:145], v[190:193], v[74:77]
	v_mfma_f32_16x16x32_bf16 v[78:81], v[134:137], v[190:193], v[78:81]
	v_mfma_f32_16x16x32_bf16 v[118:121], v[146:149], v[162:165], v[118:121]
	v_mfma_f32_16x16x32_bf16 v[114:117], v[154:157], v[162:165], v[114:117]
	v_mfma_f32_16x16x32_bf16 v[98:101], v[154:157], v[170:173], v[98:101]
	v_mfma_f32_16x16x32_bf16 v[102:105], v[146:149], v[170:173], v[102:105]
	v_mfma_f32_16x16x32_bf16 v[86:89], v[146:149], v[178:181], v[86:89]
	v_mfma_f32_16x16x32_bf16 v[82:85], v[154:157], v[178:181], v[82:85]
	v_mfma_f32_16x16x32_bf16 v[66:69], v[154:157], v[186:189], v[66:69]
	v_mfma_f32_16x16x32_bf16 v[70:73], v[146:149], v[186:189], v[70:73]
	v_mfma_f32_16x16x32_bf16 v[118:121], v[150:153], v[166:169], v[118:121]
	v_mfma_f32_16x16x32_bf16 v[114:117], v[158:161], v[166:169], v[114:117]
	v_mfma_f32_16x16x32_bf16 v[98:101], v[158:161], v[174:177], v[98:101]
	v_mfma_f32_16x16x32_bf16 v[102:105], v[150:153], v[174:177], v[102:105]
	v_mfma_f32_16x16x32_bf16 v[86:89], v[150:153], v[182:185], v[86:89]
	v_mfma_f32_16x16x32_bf16 v[82:85], v[158:161], v[182:185], v[82:85]
	v_mfma_f32_16x16x32_bf16 v[66:69], v[158:161], v[190:193], v[66:69]
	v_mfma_f32_16x16x32_bf16 v[70:73], v[150:153], v[190:193], v[70:73]
	s_barrier
	s_setprio 0
	s_cselect_b32 s12, s15, s20
	s_mov_b32 m0, s61
	s_mov_b32 s42, s6
	s_mov_b32 s43, s7
	s_sub_i32 s12, s12, s40
	ds_read_b128 v[162:165], v238 offset:16384
	ds_read_b128 v[166:169], v238 offset:17408
	ds_read_b128 v[170:173], v238 offset:18432
	ds_read_b128 v[174:177], v238 offset:19456
	ds_read_b128 v[178:181], v238 offset:20480
	ds_read_b128 v[182:185], v238 offset:21504
	ds_read_b128 v[186:189], v238 offset:22528
	ds_read_b128 v[190:193], v238 offset:23552
	buffer_load_dwordx4 v207, s[40:43], s12 offen lds
	s_mov_b32 m0, s62
	s_add_i32 s36, s12, 0x80000
	buffer_load_dwordx4 v224, s[40:43], s12 offen lds
	s_mov_b32 m0, s63
	s_sub_i32 s13, s13, s4
	buffer_load_dwordx4 v207, s[40:43], s36 offen lds
	s_mov_b32 m0, s71
	s_nop 0
	buffer_load_dwordx4 v224, s[40:43], s36 offen lds
	s_mov_b32 m0, s53
	s_nop 0
	buffer_load_dwordx4 v195, s[4:7], s13 offen lds
	s_waitcnt vmcnt(7)
	s_waitcnt lgkmcnt(0)
	s_setprio 1
	s_barrier
	v_mfma_f32_16x16x32_bf16 v[62:65], v[130:133], v[162:165], v[62:65]
	v_mfma_f32_16x16x32_bf16 v[58:61], v[138:141], v[162:165], v[58:61]
	v_mfma_f32_16x16x32_bf16 v[42:45], v[138:141], v[170:173], v[42:45]
	v_mfma_f32_16x16x32_bf16 v[46:49], v[130:133], v[170:173], v[46:49]
	v_mfma_f32_16x16x32_bf16 v[30:33], v[130:133], v[178:181], v[30:33]
	v_mfma_f32_16x16x32_bf16 v[26:29], v[138:141], v[178:181], v[26:29]
	v_mfma_f32_16x16x32_bf16 v[10:13], v[138:141], v[186:189], v[10:13]
	v_mfma_f32_16x16x32_bf16 v[14:17], v[130:133], v[186:189], v[14:17]
	v_mfma_f32_16x16x32_bf16 v[62:65], v[134:137], v[166:169], v[62:65]
	v_mfma_f32_16x16x32_bf16 v[58:61], v[142:145], v[166:169], v[58:61]
	v_mfma_f32_16x16x32_bf16 v[42:45], v[142:145], v[174:177], v[42:45]
	v_mfma_f32_16x16x32_bf16 v[46:49], v[134:137], v[174:177], v[46:49]
	v_mfma_f32_16x16x32_bf16 v[30:33], v[134:137], v[182:185], v[30:33]
	v_mfma_f32_16x16x32_bf16 v[26:29], v[142:145], v[182:185], v[26:29]
	v_mfma_f32_16x16x32_bf16 v[10:13], v[142:145], v[190:193], v[10:13]
	v_mfma_f32_16x16x32_bf16 v[14:17], v[134:137], v[190:193], v[14:17]
	v_mfma_f32_16x16x32_bf16 v[54:57], v[146:149], v[162:165], v[54:57]
	v_mfma_f32_16x16x32_bf16 v[50:53], v[154:157], v[162:165], v[50:53]
	v_mfma_f32_16x16x32_bf16 v[34:37], v[154:157], v[170:173], v[34:37]
	v_mfma_f32_16x16x32_bf16 v[38:41], v[146:149], v[170:173], v[38:41]
	v_mfma_f32_16x16x32_bf16 v[22:25], v[146:149], v[178:181], v[22:25]
	v_mfma_f32_16x16x32_bf16 v[18:21], v[154:157], v[178:181], v[18:21]
	v_mfma_f32_16x16x32_bf16 v[2:5], v[154:157], v[186:189], v[2:5]
	v_mfma_f32_16x16x32_bf16 v[6:9], v[146:149], v[186:189], v[6:9]
	v_mfma_f32_16x16x32_bf16 v[54:57], v[150:153], v[166:169], v[54:57]
	v_mfma_f32_16x16x32_bf16 v[50:53], v[158:161], v[166:169], v[50:53]
	v_mfma_f32_16x16x32_bf16 v[34:37], v[158:161], v[174:177], v[34:37]
	v_mfma_f32_16x16x32_bf16 v[38:41], v[150:153], v[174:177], v[38:41]
	v_mfma_f32_16x16x32_bf16 v[22:25], v[150:153], v[182:185], v[22:25]
	v_mfma_f32_16x16x32_bf16 v[18:21], v[158:161], v[182:185], v[18:21]
	v_mfma_f32_16x16x32_bf16 v[2:5], v[158:161], v[190:193], v[2:5]
	v_mfma_f32_16x16x32_bf16 v[6:9], v[150:153], v[190:193], v[6:9]
	s_barrier
; #define PG8_STAGE(bufoff, gbase, voff) do { const int so_ = (int)(unsigned)((const char*)(gbase) - base_##voff); _Pragma("unroll") for (int _i = 0; _i < 2; ++_i) \
;         __builtin_amdgcn_raw_ptr_buffer_load_lds(rs_##voff, (PG8_LAS unsigned*)(lds + (bufoff) + ldsw + _i * 8192), 16, (int)(voff)[_i], so_, 0, 0); } while (0)
; #define PG8_LDA(dst, b, h) do { _Pragma("unroll") for (int m = 0; m < 4; ++m) _Pragma("unroll") for (int k = 0; k < 2; ++k) dst[m][k] = *(const PG8_LAS bf16x8*)(lds + PG8_SA(b, h) + aoff + m * 2048 + k * 1024); } while (0)
; #define PG8_LDB(dst, b, h) do { _Pragma("unroll") for (int n = 0; n < 2; ++n) _Pragma("unroll") for (int k = 0; k < 2; ++k) dst[n][k] = *(const PG8_LAS bf16x8*)(lds + PG8_SB(b, h) + boff + n * 2048 + k * 1024); } while (0)
; #define PG8_MMA(ai, bj, At, Bt) do { __builtin_amdgcn_s_setprio(1); _Pragma("unroll") for (int m = 0; m < 4; ++m) _Pragma("unroll") for (int n = 0; n < 2; ++n) _Pragma("unroll") for (int k = 0; k < 2; ++k) \
;         acc[ai][bj][m][n] = __builtin_amdgcn_mfma_f32_16x16x32_bf16(Bt[n][k], At[m][k], acc[ai][bj][m][n], 0, 0, 0); __builtin_amdgcn_s_setprio(0); } while (0)
; #define PG8_WAIT_V(n) asm volatile("s_waitcnt vmcnt(" #n ")" ::: "memory")
; #define PG8_WAIT_L(n) asm volatile("s_waitcnt lgkmcnt(" #n ")" ::: "memory")
; #define PG8_BAR __builtin_amdgcn_s_barrier()
; #define PG8_SCHED __builtin_amdgcn_sched_barrier(0)
; template <class Epi, class Sched, bool ALIGN_EPI = false, bool SP2 = false>
; __device__ __forceinline__ void gemm_phase(PG8_LAS unsigned char* lds, const Gemm g, const Sched& S, const Epi& E, int tid_in) {
;     ...
;             PG8_LDB(B0, 1, 0); PG8_LDB(B1, 1, 1); PG8_SCHED; PG8_LDA(At, 1, 0); PG8_STAGE(PG8_SA(0, 1), a2 + hstepA, voffA);
;             PG8_WAIT_V(8); PG8_WAIT_L(0); PG8_BAR; PG8_MMA(0, 0, At, B0); PG8_MMA(0, 1, At, B1); PG8_BAR; PG8_SCHED;
;             PG8_LDA(At, 1, 1); PG8_STAGE(PG8_SB(1, 0), b3, voffB); PG8_STAGE(PG8_SB(1, 1), b3 + hstepB, voffB); PG8_STAGE(PG8_SA(1, 0), a3, voffA);
;             PG8_WAIT_V(8); PG8_WAIT_L(0); PG8_BAR; PG8_MMA(1, 0, At, B0); PG8_MMA(1, 1, At, B1); PG8_BAR; PG8_SCHED;
	s_setprio 0
	ds_read_b128 v[130:133], v251 offset:32768
	ds_read_b128 v[134:137], v251 offset:33792
	ds_read_b128 v[138:141], v251 offset:34816
	ds_read_b128 v[142:145], v251 offset:35840
	ds_read_b128 v[146:149], v251 offset:49152
	ds_read_b128 v[150:153], v251 offset:50176
	ds_read_b128 v[154:157], v251 offset:51200
	ds_read_b128 v[158:161], v251 offset:52224
	s_add_i32 s36, s13, 0x80000
	s_mov_b32 m0, s73
	ds_read_b128 v[162:165], v238 offset:32768
	ds_read_b128 v[166:169], v238 offset:33792
	ds_read_b128 v[170:173], v238 offset:34816
	ds_read_b128 v[174:177], v238 offset:35840
	ds_read_b128 v[178:181], v238 offset:36864
	ds_read_b128 v[182:185], v238 offset:37888
	ds_read_b128 v[186:189], v238 offset:38912
	ds_read_b128 v[190:193], v238 offset:39936
	s_mov_b32 m0, s72
	s_nop 0
	buffer_load_dwordx4 v211, s[4:7], s13 offen lds
	s_mov_b32 m0, s73
	s_nop 0
	buffer_load_dwordx4 v195, s[4:7], s36 offen lds
	s_mov_b32 m0, s74
	s_nop 0
	buffer_load_dwordx4 v211, s[4:7], s36 offen lds
	s_waitcnt vmcnt(8)
	s_waitcnt lgkmcnt(0)
	s_setprio 1
	s_barrier
	v_mfma_f32_16x16x32_bf16 v[126:129], v[130:133], v[162:165], v[126:129]
	v_mfma_f32_16x16x32_bf16 v[122:125], v[138:141], v[162:165], v[122:125]
	v_mfma_f32_16x16x32_bf16 v[106:109], v[138:141], v[170:173], v[106:109]
	v_mfma_f32_16x16x32_bf16 v[110:113], v[130:133], v[170:173], v[110:113]
	v_mfma_f32_16x16x32_bf16 v[94:97], v[130:133], v[178:181], v[94:97]
	v_mfma_f32_16x16x32_bf16 v[90:93], v[138:141], v[178:181], v[90:93]
	v_mfma_f32_16x16x32_bf16 v[74:77], v[138:141], v[186:189], v[74:77]
	v_mfma_f32_16x16x32_bf16 v[78:81], v[130:133], v[186:189], v[78:81]
	v_mfma_f32_16x16x32_bf16 v[126:129], v[134:137], v[166:169], v[126:129]
	v_mfma_f32_16x16x32_bf16 v[122:125], v[142:145], v[166:169], v[122:125]
	v_mfma_f32_16x16x32_bf16 v[106:109], v[142:145], v[174:177], v[106:109]
	v_mfma_f32_16x16x32_bf16 v[110:113], v[134:137], v[174:177], v[110:113]
	v_mfma_f32_16x16x32_bf16 v[94:97], v[134:137], v[182:185], v[94:97]
	v_mfma_f32_16x16x32_bf16 v[90:93], v[142:145], v[182:185], v[90:93]
	v_mfma_f32_16x16x32_bf16 v[74:77], v[142:145], v[190:193], v[74:77]
	v_mfma_f32_16x16x32_bf16 v[78:81], v[134:137], v[190:193], v[78:81]
	v_mfma_f32_16x16x32_bf16 v[118:121], v[146:149], v[162:165], v[118:121]
	v_mfma_f32_16x16x32_bf16 v[114:117], v[154:157], v[162:165], v[114:117]
	v_mfma_f32_16x16x32_bf16 v[98:101], v[154:157], v[170:173], v[98:101]
	v_mfma_f32_16x16x32_bf16 v[102:105], v[146:149], v[170:173], v[102:105]
	v_mfma_f32_16x16x32_bf16 v[86:89], v[146:149], v[178:181], v[86:89]
	v_mfma_f32_16x16x32_bf16 v[82:85], v[154:157], v[178:181], v[82:85]
	v_mfma_f32_16x16x32_bf16 v[66:69], v[154:157], v[186:189], v[66:69]
	v_mfma_f32_16x16x32_bf16 v[70:73], v[146:149], v[186:189], v[70:73]
	v_mfma_f32_16x16x32_bf16 v[118:121], v[150:153], v[166:169], v[118:121]
	v_mfma_f32_16x16x32_bf16 v[114:117], v[158:161], v[166:169], v[114:117]
	v_mfma_f32_16x16x32_bf16 v[98:101], v[158:161], v[174:177], v[98:101]
	v_mfma_f32_16x16x32_bf16 v[102:105], v[150:153], v[174:177], v[102:105]
	v_mfma_f32_16x16x32_bf16 v[86:89], v[150:153], v[182:185], v[86:89]
	v_mfma_f32_16x16x32_bf16 v[82:85], v[158:161], v[182:185], v[82:85]
	v_mfma_f32_16x16x32_bf16 v[66:69], v[158:161], v[190:193], v[66:69]
	v_mfma_f32_16x16x32_bf16 v[70:73], v[150:153], v[190:193], v[70:73]
	s_barrier
	s_setprio 0
	s_mov_b32 m0, s75
	s_add_i32 s36, s12, 0x80
	ds_read_b128 v[162:165], v238 offset:49152
	ds_read_b128 v[166:169], v238 offset:50176
	ds_read_b128 v[170:173], v238 offset:51200
	ds_read_b128 v[174:177], v238 offset:52224
	ds_read_b128 v[178:181], v238 offset:53248
	ds_read_b128 v[182:185], v238 offset:54272
	ds_read_b128 v[186:189], v238 offset:55296
	ds_read_b128 v[190:193], v238 offset:56320
	buffer_load_dwordx4 v207, s[40:43], s36 offen lds
	s_mov_b32 m0, s76
	s_add_i32 s12, s12, 0x80080
	buffer_load_dwordx4 v224, s[40:43], s36 offen lds
	s_mov_b32 m0, s79
	s_addk_i32 s13, 0x80
	buffer_load_dwordx4 v207, s[40:43], s12 offen lds
	s_mov_b32 m0, s68
	s_nop 0
	buffer_load_dwordx4 v224, s[40:43], s12 offen lds
	s_mov_b32 m0, s77
	s_nop 0
	buffer_load_dwordx4 v195, s[4:7], s13 offen lds
	s_waitcnt vmcnt(7)
	s_waitcnt lgkmcnt(0)
	s_setprio 1
	s_barrier
	v_mfma_f32_16x16x32_bf16 v[62:65], v[130:133], v[162:165], v[62:65]
	v_mfma_f32_16x16x32_bf16 v[58:61], v[138:141], v[162:165], v[58:61]
	v_mfma_f32_16x16x32_bf16 v[42:45], v[138:141], v[170:173], v[42:45]
	v_mfma_f32_16x16x32_bf16 v[46:49], v[130:133], v[170:173], v[46:49]
	v_mfma_f32_16x16x32_bf16 v[30:33], v[130:133], v[178:181], v[30:33]
	v_mfma_f32_16x16x32_bf16 v[26:29], v[138:141], v[178:181], v[26:29]
	v_mfma_f32_16x16x32_bf16 v[10:13], v[138:141], v[186:189], v[10:13]
	v_mfma_f32_16x16x32_bf16 v[14:17], v[130:133], v[186:189], v[14:17]
	v_mfma_f32_16x16x32_bf16 v[62:65], v[134:137], v[166:169], v[62:65]
	v_mfma_f32_16x16x32_bf16 v[58:61], v[142:145], v[166:169], v[58:61]
	v_mfma_f32_16x16x32_bf16 v[42:45], v[142:145], v[174:177], v[42:45]
	v_mfma_f32_16x16x32_bf16 v[46:49], v[134:137], v[174:177], v[46:49]
	v_mfma_f32_16x16x32_bf16 v[30:33], v[134:137], v[182:185], v[30:33]
	v_mfma_f32_16x16x32_bf16 v[26:29], v[142:145], v[182:185], v[26:29]
	v_mfma_f32_16x16x32_bf16 v[10:13], v[142:145], v[190:193], v[10:13]
	v_mfma_f32_16x16x32_bf16 v[14:17], v[134:137], v[190:193], v[14:17]
	v_mfma_f32_16x16x32_bf16 v[54:57], v[146:149], v[162:165], v[54:57]
	v_mfma_f32_16x16x32_bf16 v[50:53], v[154:157], v[162:165], v[50:53]
	v_mfma_f32_16x16x32_bf16 v[34:37], v[154:157], v[170:173], v[34:37]
	v_mfma_f32_16x16x32_bf16 v[38:41], v[146:149], v[170:173], v[38:41]
	v_mfma_f32_16x16x32_bf16 v[22:25], v[146:149], v[178:181], v[22:25]
	v_mfma_f32_16x16x32_bf16 v[18:21], v[154:157], v[178:181], v[18:21]
	v_mfma_f32_16x16x32_bf16 v[2:5], v[154:157], v[186:189], v[2:5]
	v_mfma_f32_16x16x32_bf16 v[6:9], v[146:149], v[186:189], v[6:9]
	v_mfma_f32_16x16x32_bf16 v[54:57], v[150:153], v[166:169], v[54:57]
	v_mfma_f32_16x16x32_bf16 v[50:53], v[158:161], v[166:169], v[50:53]
	v_mfma_f32_16x16x32_bf16 v[34:37], v[158:161], v[174:177], v[34:37]
	v_mfma_f32_16x16x32_bf16 v[38:41], v[150:153], v[174:177], v[38:41]
	v_mfma_f32_16x16x32_bf16 v[22:25], v[150:153], v[182:185], v[22:25]
	v_mfma_f32_16x16x32_bf16 v[18:21], v[158:161], v[182:185], v[18:21]
	v_mfma_f32_16x16x32_bf16 v[2:5], v[158:161], v[190:193], v[2:5]
	v_mfma_f32_16x16x32_bf16 v[6:9], v[150:153], v[190:193], v[6:9]
	s_barrier
	s_setprio 0
	s_add_i32 s23, s23, 2
	s_add_u32 s20, s20, 0x100
	s_addc_u32 s21, s21, 0
	s_cmp_gt_u32 s23, 29
	s_mov_b64 s[12:13], s[16:17]
	s_cbranch_scc0 .LBB0_312
	s_and_b64 vcc, exec, s[48:49]
	s_cbranch_vccz .LBB0_315
	s_barrier

; #define PG8_STAGE(bufoff, gbase, voff) do { const int so_ = (int)(unsigned)((const char*)(gbase) - base_##voff); _Pragma("unroll") for (int _i = 0; _i < 2; ++_i) \
;         __builtin_amdgcn_raw_ptr_buffer_load_lds(rs_##voff, (PG8_LAS unsigned*)(lds + (bufoff) + ldsw + _i * 8192), 16, (int)(voff)[_i], so_, 0, 0); } while (0)
; #define PG8_LDA(dst, b, h) do { _Pragma("unroll") for (int m = 0; m < 4; ++m) _Pragma("unroll") for (int k = 0; k < 2; ++k) dst[m][k] = *(const PG8_LAS bf16x8*)(lds + PG8_SA(b, h) + aoff + m * 2048 + k * 1024); } while (0)
; #define PG8_LDB(dst, b, h) do { _Pragma("unroll") for (int n = 0; n < 2; ++n) _Pragma("unroll") for (int k = 0; k < 2; ++k) dst[n][k] = *(const PG8_LAS bf16x8*)(lds + PG8_SB(b, h) + boff + n * 2048 + k * 1024); } while (0)
; #define PG8_WAIT_V(n) asm volatile("s_waitcnt vmcnt(" #n ")" ::: "memory")
; #define PG8_WAIT_L(n) asm volatile("s_waitcnt lgkmcnt(" #n ")" ::: "memory")
; #define PG8_BAR __builtin_amdgcn_s_barrier()
; #define PG8_SCHED __builtin_amdgcn_sched_barrier(0)
; template <class Epi, class Sched, bool ALIGN_EPI = false, bool SP2 = false>
; __device__ __forceinline__ void gemm_phase(PG8_LAS unsigned char* lds, const Gemm g, const Sched& S, const Epi& E, int tid_in) {
;     ...
;         const char* nA = has_next ? (const char*)g.A + (size_t)nxt.pm * tstepA + (g.grp ? (size_t)(nxt.pn / g.grp) * g.agrp : (size_t)0) : cA; const char* nB = has_next ? (const char*)g.Bt + (size_t)nxt.pn * tstepB : cB;
;         for (int t = 0; t < nt; t += 2) {
;             const bool last = (t == nt - 2);
;             const char* a1 = cA + (size_t)(t + 1) * kstep;
;             const char* a2 = last ? nA : cA + (size_t)(t + 2) * kstep; const char* b2 = last ? nB : cB + (size_t)(t + 2) * kstep;
;             const char* a3 = a2 + kstep; const char* b3 = b2 + kstep;
;             if (last && has_next) S.a_ready(nxt);
;             if constexpr (SP2) {
;             PG8_LDB(B0, 0, 0); PG8_LDB(B1, 0, 1); PG8_SCHED; PG8_LDA(At, 0, 0); PG8_STAGE(PG8_SA(1, 1), a1 + hstepA, voffA);
;             PG8_WAIT_V(8); PG8_WAIT_L(0); PG8_BAR; PG8_MMA(0, 0, At, B0); PG8_MMA(0, 1, At, B1); PG8_BAR; PG8_SCHED;
;             PG8_LDA(At, 0, 1); PG8_STAGE(PG8_SB(0, 0), b2, voffB); PG8_STAGE(PG8_SB(0, 1), b2 + hstepB, voffB); PG8_STAGE(PG8_SA(0, 0), a2, voffA);
.LBB0_1036:
	s_ashr_i32 s23, s22, 31
	s_lshl_b64 s[18:19], s[22:23], 19
	s_add_u32 s48, s44, s18
	s_addc_u32 s49, s20, s19
	s_and_b64 s[18:19], s[38:39], exec
	s_cselect_b32 s18, s48, s16
	s_add_u32 s19, s16, 0x100
	s_addc_u32 s23, s17, 0
	s_mov_b32 s38, -2
	v_add_u32_e32 v251, 0x10000, v236
.LBB0_1037:
	ds_read_b128 v[132:135], v251
	ds_read_b128 v[136:139], v251 offset:1024
	ds_read_b128 v[140:143], v251 offset:2048
	ds_read_b128 v[144:147], v251 offset:3072
	ds_read_b128 v[148:151], v251 offset:16384
	ds_read_b128 v[152:155], v251 offset:17408
	ds_read_b128 v[156:159], v251 offset:18432
	ds_read_b128 v[160:163], v251 offset:19456
	s_add_u32 s16, s12, 0x100
	s_addc_u32 s17, s13, 0
	s_sub_i32 s12, s12, s4
	s_add_i32 s12, s12, 0xc0080
	s_sub_i32 s39, s12, 0xc0000
	s_cmp_eq_u32 s38, 12
	s_cselect_b32 s13, s24, s16
	s_mov_b32 m0, s76
	ds_read_b128 v[164:167], v237
	ds_read_b128 v[168:171], v237 offset:1024
	ds_read_b128 v[172:175], v237 offset:2048
	ds_read_b128 v[176:179], v237 offset:3072
	ds_read_b128 v[180:183], v237 offset:4096
	ds_read_b128 v[184:187], v237 offset:5120
	ds_read_b128 v[188:191], v237 offset:6144
	ds_read_b128 v[192:195], v237 offset:7168
	s_mov_b32 m0, s73
	s_nop 0
	buffer_load_dwordx4 v222, s[4:7], s39 offen lds
	s_mov_b32 m0, s76
	s_nop 0
	buffer_load_dwordx4 v220, s[4:7], s12 offen lds
	s_mov_b32 m0, s77
	s_nop 0
	buffer_load_dwordx4 v222, s[4:7], s12 offen lds
	s_waitcnt vmcnt(8)
	s_waitcnt lgkmcnt(0)
	s_setprio 1
	s_barrier
	v_mfma_f32_16x16x32_bf16 v[128:131], v[132:135], v[164:167], v[128:131]
	v_mfma_f32_16x16x32_bf16 v[124:127], v[140:143], v[164:167], v[124:127]
	v_mfma_f32_16x16x32_bf16 v[116:119], v[140:143], v[172:175], v[116:119]
	v_mfma_f32_16x16x32_bf16 v[120:123], v[132:135], v[172:175], v[120:123]
	v_mfma_f32_16x16x32_bf16 v[112:115], v[132:135], v[180:183], v[112:115]
	v_mfma_f32_16x16x32_bf16 v[108:111], v[140:143], v[180:183], v[108:111]
	v_mfma_f32_16x16x32_bf16 v[100:103], v[140:143], v[188:191], v[100:103]
	v_mfma_f32_16x16x32_bf16 v[104:107], v[132:135], v[188:191], v[104:107]
	v_mfma_f32_16x16x32_bf16 v[128:131], v[136:139], v[168:171], v[128:131]
	v_mfma_f32_16x16x32_bf16 v[124:127], v[144:147], v[168:171], v[124:127]
	v_mfma_f32_16x16x32_bf16 v[116:119], v[144:147], v[176:179], v[116:119]
	v_mfma_f32_16x16x32_bf16 v[120:123], v[136:139], v[176:179], v[120:123]
	v_mfma_f32_16x16x32_bf16 v[112:115], v[136:139], v[184:187], v[112:115]
	v_mfma_f32_16x16x32_bf16 v[108:111], v[144:147], v[184:187], v[108:111]
	v_mfma_f32_16x16x32_bf16 v[100:103], v[144:147], v[192:195], v[100:103]
	v_mfma_f32_16x16x32_bf16 v[104:107], v[136:139], v[192:195], v[104:107]
	v_mfma_f32_16x16x32_bf16 v[96:99], v[148:151], v[164:167], v[96:99]
	v_mfma_f32_16x16x32_bf16 v[92:95], v[156:159], v[164:167], v[92:95]
	v_mfma_f32_16x16x32_bf16 v[84:87], v[156:159], v[172:175], v[84:87]
	v_mfma_f32_16x16x32_bf16 v[88:91], v[148:151], v[172:175], v[88:91]
	v_mfma_f32_16x16x32_bf16 v[80:83], v[148:151], v[180:183], v[80:83]
	v_mfma_f32_16x16x32_bf16 v[76:79], v[156:159], v[180:183], v[76:79]
	v_mfma_f32_16x16x32_bf16 v[68:71], v[156:159], v[188:191], v[68:71]
	v_mfma_f32_16x16x32_bf16 v[72:75], v[148:151], v[188:191], v[72:75]
	v_mfma_f32_16x16x32_bf16 v[96:99], v[152:155], v[168:171], v[96:99]
	v_mfma_f32_16x16x32_bf16 v[92:95], v[160:163], v[168:171], v[92:95]
	v_mfma_f32_16x16x32_bf16 v[84:87], v[160:163], v[176:179], v[84:87]
	v_mfma_f32_16x16x32_bf16 v[88:91], v[152:155], v[176:179], v[88:91]
	v_mfma_f32_16x16x32_bf16 v[80:83], v[152:155], v[184:187], v[80:83]
	v_mfma_f32_16x16x32_bf16 v[76:79], v[160:163], v[184:187], v[76:79]
	v_mfma_f32_16x16x32_bf16 v[68:71], v[160:163], v[192:195], v[68:71]
	v_mfma_f32_16x16x32_bf16 v[72:75], v[152:155], v[192:195], v[72:75]
	s_barrier
	s_setprio 0
	s_cselect_b32 s12, s18, s19
	s_mov_b32 m0, s26
	s_mov_b32 s46, s6
	s_mov_b32 s47, s7
	s_sub_i32 s12, s12, s44
	ds_read_b128 v[164:167], v237 offset:16384
	ds_read_b128 v[168:171], v237 offset:17408
	ds_read_b128 v[172:175], v237 offset:18432
	ds_read_b128 v[176:179], v237 offset:19456
	ds_read_b128 v[180:183], v237 offset:20480
	ds_read_b128 v[184:187], v237 offset:21504
	ds_read_b128 v[188:191], v237 offset:22528
	ds_read_b128 v[192:195], v237 offset:23552
	buffer_load_dwordx4 v221, s[44:47], s12 offen lds
	s_mov_b32 m0, s53
	s_add_i32 s39, s12, 0x40000
	buffer_load_dwordx4 v223, s[44:47], s12 offen lds
	s_mov_b32 m0, s60
	s_sub_i32 s13, s13, s4
	buffer_load_dwordx4 v221, s[44:47], s39 offen lds
	s_mov_b32 m0, s61
	s_nop 0
	buffer_load_dwordx4 v223, s[44:47], s39 offen lds
	s_mov_b32 m0, s21
	s_nop 0
	buffer_load_dwordx4 v220, s[4:7], s13 offen lds
	s_waitcnt vmcnt(7)
	s_waitcnt lgkmcnt(0)
	s_setprio 1
	s_barrier
; #define PG8_STAGE(bufoff, gbase, voff) do { const int so_ = (int)(unsigned)((const char*)(gbase) - base_##voff); _Pragma("unroll") for (int _i = 0; _i < 2; ++_i) \
;         __builtin_amdgcn_raw_ptr_buffer_load_lds(rs_##voff, (PG8_LAS unsigned*)(lds + (bufoff) + ldsw + _i * 8192), 16, (int)(voff)[_i], so_, 0, 0); } while (0)
; #define PG8_LDA(dst, b, h) do { _Pragma("unroll") for (int m = 0; m < 4; ++m) _Pragma("unroll") for (int k = 0; k < 2; ++k) dst[m][k] = *(const PG8_LAS bf16x8*)(lds + PG8_SA(b, h) + aoff + m * 2048 + k * 1024); } while (0)
; #define PG8_LDB(dst, b, h) do { _Pragma("unroll") for (int n = 0; n < 2; ++n) _Pragma("unroll") for (int k = 0; k < 2; ++k) dst[n][k] = *(const PG8_LAS bf16x8*)(lds + PG8_SB(b, h) + boff + n * 2048 + k * 1024); } while (0)
; #define PG8_MMA(ai, bj, At, Bt) do { __builtin_amdgcn_s_setprio(1); _Pragma("unroll") for (int m = 0; m < 4; ++m) _Pragma("unroll") for (int n = 0; n < 2; ++n) _Pragma("unroll") for (int k = 0; k < 2; ++k) \
;         acc[ai][bj][m][n] = __builtin_amdgcn_mfma_f32_16x16x32_bf16(Bt[n][k], At[m][k], acc[ai][bj][m][n], 0, 0, 0); __builtin_amdgcn_s_setprio(0); } while (0)
; #define PG8_WAIT_V(n) asm volatile("s_waitcnt vmcnt(" #n ")" ::: "memory")
; #define PG8_WAIT_L(n) asm volatile("s_waitcnt lgkmcnt(" #n ")" ::: "memory")
; #define PG8_BAR __builtin_amdgcn_s_barrier()
; #define PG8_SCHED __builtin_amdgcn_sched_barrier(0)
; template <class Epi, class Sched, bool ALIGN_EPI = false, bool SP2 = false>
; __device__ __forceinline__ void gemm_phase(PG8_LAS unsigned char* lds, const Gemm g, const Sched& S, const Epi& E, int tid_in) {
;     ...
;             PG8_WAIT_V(8); PG8_WAIT_L(0); PG8_BAR; PG8_MMA(1, 0, At, B0); PG8_MMA(1, 1, At, B1); PG8_BAR; PG8_SCHED;
;             PG8_LDB(B0, 1, 0); PG8_LDB(B1, 1, 1); PG8_SCHED; PG8_LDA(At, 1, 0); PG8_STAGE(PG8_SA(0, 1), a2 + hstepA, voffA);
;             PG8_WAIT_V(8); PG8_WAIT_L(0); PG8_BAR; PG8_MMA(0, 0, At, B0); PG8_MMA(0, 1, At, B1); PG8_BAR; PG8_SCHED;
;             PG8_LDA(At, 1, 1); PG8_STAGE(PG8_SB(1, 0), b3, voffB); PG8_STAGE(PG8_SB(1, 1), b3 + hstepB, voffB); PG8_STAGE(PG8_SA(1, 0), a3, voffA);
	v_mfma_f32_16x16x32_bf16 v[64:67], v[132:135], v[164:167], v[64:67]
	v_mfma_f32_16x16x32_bf16 v[60:63], v[140:143], v[164:167], v[60:63]
	v_mfma_f32_16x16x32_bf16 v[52:55], v[140:143], v[172:175], v[52:55]
	v_mfma_f32_16x16x32_bf16 v[56:59], v[132:135], v[172:175], v[56:59]
	v_mfma_f32_16x16x32_bf16 v[48:51], v[132:135], v[180:183], v[48:51]
	v_mfma_f32_16x16x32_bf16 v[44:47], v[140:143], v[180:183], v[44:47]
	v_mfma_f32_16x16x32_bf16 v[36:39], v[140:143], v[188:191], v[36:39]
	v_mfma_f32_16x16x32_bf16 v[40:43], v[132:135], v[188:191], v[40:43]
	v_mfma_f32_16x16x32_bf16 v[64:67], v[136:139], v[168:171], v[64:67]
	v_mfma_f32_16x16x32_bf16 v[60:63], v[144:147], v[168:171], v[60:63]
	v_mfma_f32_16x16x32_bf16 v[52:55], v[144:147], v[176:179], v[52:55]
	v_mfma_f32_16x16x32_bf16 v[56:59], v[136:139], v[176:179], v[56:59]
	v_mfma_f32_16x16x32_bf16 v[48:51], v[136:139], v[184:187], v[48:51]
	v_mfma_f32_16x16x32_bf16 v[44:47], v[144:147], v[184:187], v[44:47]
	v_mfma_f32_16x16x32_bf16 v[36:39], v[144:147], v[192:195], v[36:39]
	v_mfma_f32_16x16x32_bf16 v[40:43], v[136:139], v[192:195], v[40:43]
	v_mfma_f32_16x16x32_bf16 v[32:35], v[148:151], v[164:167], v[32:35]
	v_mfma_f32_16x16x32_bf16 v[28:31], v[156:159], v[164:167], v[28:31]
	v_mfma_f32_16x16x32_bf16 v[20:23], v[156:159], v[172:175], v[20:23]
	v_mfma_f32_16x16x32_bf16 v[24:27], v[148:151], v[172:175], v[24:27]
	v_mfma_f32_16x16x32_bf16 v[16:19], v[148:151], v[180:183], v[16:19]
	v_mfma_f32_16x16x32_bf16 v[12:15], v[156:159], v[180:183], v[12:15]
	v_mfma_f32_16x16x32_bf16 v[2:5], v[156:159], v[188:191], v[4:7]
	v_mfma_f32_16x16x32_bf16 v[8:11], v[148:151], v[188:191], v[8:11]
	v_mfma_f32_16x16x32_bf16 v[32:35], v[152:155], v[168:171], v[32:35]
	v_mfma_f32_16x16x32_bf16 v[28:31], v[160:163], v[168:171], v[28:31]
	v_mfma_f32_16x16x32_bf16 v[20:23], v[160:163], v[176:179], v[20:23]
	v_mfma_f32_16x16x32_bf16 v[24:27], v[152:155], v[176:179], v[24:27]
	v_mfma_f32_16x16x32_bf16 v[16:19], v[152:155], v[184:187], v[16:19]
	v_mfma_f32_16x16x32_bf16 v[12:15], v[160:163], v[184:187], v[12:15]
	v_mfma_f32_16x16x32_bf16 v[2:5], v[160:163], v[192:195], v[2:5]
	v_mfma_f32_16x16x32_bf16 v[8:11], v[152:155], v[192:195], v[8:11]
	s_barrier
	s_setprio 0
	ds_read_b128 v[132:135], v251 offset:32768
	ds_read_b128 v[136:139], v251 offset:33792
	ds_read_b128 v[140:143], v251 offset:34816
	ds_read_b128 v[144:147], v251 offset:35840
	ds_read_b128 v[148:151], v251 offset:49152
	ds_read_b128 v[152:155], v251 offset:50176
	ds_read_b128 v[156:159], v251 offset:51200
	ds_read_b128 v[160:163], v251 offset:52224
	s_add_i32 s39, s13, 0xc0000
	s_mov_b32 m0, s63
	ds_read_b128 v[164:167], v237 offset:32768
	ds_read_b128 v[168:171], v237 offset:33792
	ds_read_b128 v[172:175], v237 offset:34816
	ds_read_b128 v[176:179], v237 offset:35840
	ds_read_b128 v[180:183], v237 offset:36864
	ds_read_b128 v[184:187], v237 offset:37888
	ds_read_b128 v[188:191], v237 offset:38912
	ds_read_b128 v[192:195], v237 offset:39936
	s_mov_b32 m0, s62
	s_nop 0
	buffer_load_dwordx4 v222, s[4:7], s13 offen lds
	s_mov_b32 m0, s63
	s_nop 0
	buffer_load_dwordx4 v220, s[4:7], s39 offen lds
	s_mov_b32 m0, s66
	s_nop 0
	buffer_load_dwordx4 v222, s[4:7], s39 offen lds
	s_waitcnt vmcnt(8)
	s_waitcnt lgkmcnt(0)
	s_setprio 1
	s_barrier
	v_mfma_f32_16x16x32_bf16 v[128:131], v[132:135], v[164:167], v[128:131]
	v_mfma_f32_16x16x32_bf16 v[124:127], v[140:143], v[164:167], v[124:127]
	v_mfma_f32_16x16x32_bf16 v[116:119], v[140:143], v[172:175], v[116:119]
	v_mfma_f32_16x16x32_bf16 v[120:123], v[132:135], v[172:175], v[120:123]
	v_mfma_f32_16x16x32_bf16 v[112:115], v[132:135], v[180:183], v[112:115]
	v_mfma_f32_16x16x32_bf16 v[108:111], v[140:143], v[180:183], v[108:111]
	v_mfma_f32_16x16x32_bf16 v[100:103], v[140:143], v[188:191], v[100:103]
	v_mfma_f32_16x16x32_bf16 v[104:107], v[132:135], v[188:191], v[104:107]
	v_mfma_f32_16x16x32_bf16 v[128:131], v[136:139], v[168:171], v[128:131]
	v_mfma_f32_16x16x32_bf16 v[124:127], v[144:147], v[168:171], v[124:127]
	v_mfma_f32_16x16x32_bf16 v[116:119], v[144:147], v[176:179], v[116:119]
	v_mfma_f32_16x16x32_bf16 v[120:123], v[136:139], v[176:179], v[120:123]
	v_mfma_f32_16x16x32_bf16 v[112:115], v[136:139], v[184:187], v[112:115]
	v_mfma_f32_16x16x32_bf16 v[108:111], v[144:147], v[184:187], v[108:111]
	v_mfma_f32_16x16x32_bf16 v[100:103], v[144:147], v[192:195], v[100:103]
	v_mfma_f32_16x16x32_bf16 v[104:107], v[136:139], v[192:195], v[104:107]
	v_mfma_f32_16x16x32_bf16 v[96:99], v[148:151], v[164:167], v[96:99]
	v_mfma_f32_16x16x32_bf16 v[92:95], v[156:159], v[164:167], v[92:95]
	v_mfma_f32_16x16x32_bf16 v[84:87], v[156:159], v[172:175], v[84:87]
	v_mfma_f32_16x16x32_bf16 v[88:91], v[148:151], v[172:175], v[88:91]
	v_mfma_f32_16x16x32_bf16 v[80:83], v[148:151], v[180:183], v[80:83]
	v_mfma_f32_16x16x32_bf16 v[76:79], v[156:159], v[180:183], v[76:79]
	v_mfma_f32_16x16x32_bf16 v[68:71], v[156:159], v[188:191], v[68:71]
	v_mfma_f32_16x16x32_bf16 v[72:75], v[148:151], v[188:191], v[72:75]
	v_mfma_f32_16x16x32_bf16 v[96:99], v[152:155], v[168:171], v[96:99]
	v_mfma_f32_16x16x32_bf16 v[92:95], v[160:163], v[168:171], v[92:95]
	v_mfma_f32_16x16x32_bf16 v[84:87], v[160:163], v[176:179], v[84:87]
	v_mfma_f32_16x16x32_bf16 v[88:91], v[152:155], v[176:179], v[88:91]
	v_mfma_f32_16x16x32_bf16 v[80:83], v[152:155], v[184:187], v[80:83]
	v_mfma_f32_16x16x32_bf16 v[76:79], v[160:163], v[184:187], v[76:79]
	v_mfma_f32_16x16x32_bf16 v[68:71], v[160:163], v[192:195], v[68:71]
	v_mfma_f32_16x16x32_bf16 v[72:75], v[152:155], v[192:195], v[72:75]
	s_barrier
; #define PG8_STAGE(bufoff, gbase, voff) do { const int so_ = (int)(unsigned)((const char*)(gbase) - base_##voff); _Pragma("unroll") for (int _i = 0; _i < 2; ++_i) \
;         __builtin_amdgcn_raw_ptr_buffer_load_lds(rs_##voff, (PG8_LAS unsigned*)(lds + (bufoff) + ldsw + _i * 8192), 16, (int)(voff)[_i], so_, 0, 0); } while (0)
; #define PG8_LDA(dst, b, h) do { _Pragma("unroll") for (int m = 0; m < 4; ++m) _Pragma("unroll") for (int k = 0; k < 2; ++k) dst[m][k] = *(const PG8_LAS bf16x8*)(lds + PG8_SA(b, h) + aoff + m * 2048 + k * 1024); } while (0)
; #define PG8_MMA(ai, bj, At, Bt) do { __builtin_amdgcn_s_setprio(1); _Pragma("unroll") for (int m = 0; m < 4; ++m) _Pragma("unroll") for (int n = 0; n < 2; ++n) _Pragma("unroll") for (int k = 0; k < 2; ++k) \
;         acc[ai][bj][m][n] = __builtin_amdgcn_mfma_f32_16x16x32_bf16(Bt[n][k], At[m][k], acc[ai][bj][m][n], 0, 0, 0); __builtin_amdgcn_s_setprio(0); } while (0)
; #define PG8_WAIT_V(n) asm volatile("s_waitcnt vmcnt(" #n ")" ::: "memory")
; #define PG8_WAIT_L(n) asm volatile("s_waitcnt lgkmcnt(" #n ")" ::: "memory")
; #define PG8_BAR __builtin_amdgcn_s_barrier()
; #define PG8_SCHED __builtin_amdgcn_sched_barrier(0)
; template <class Epi, class Sched, bool ALIGN_EPI = false, bool SP2 = false>
; __device__ __forceinline__ void gemm_phase(PG8_LAS unsigned char* lds, const Gemm g, const Sched& S, const Epi& E, int tid_in) {
;     ...
;             PG8_LDA(At, 1, 1); PG8_STAGE(PG8_SB(1, 0), b3, voffB); PG8_STAGE(PG8_SB(1, 1), b3 + hstepB, voffB); PG8_STAGE(PG8_SA(1, 0), a3, voffA);
;             PG8_WAIT_V(8); PG8_WAIT_L(0); PG8_BAR; PG8_MMA(1, 0, At, B0); PG8_MMA(1, 1, At, B1); PG8_BAR; PG8_SCHED;
	s_setprio 0
	s_mov_b32 m0, s69
	s_add_i32 s39, s12, 0x80
	ds_read_b128 v[164:167], v237 offset:49152
	ds_read_b128 v[168:171], v237 offset:50176
	ds_read_b128 v[172:175], v237 offset:51200
	ds_read_b128 v[176:179], v237 offset:52224
	ds_read_b128 v[180:183], v237 offset:53248
	ds_read_b128 v[184:187], v237 offset:54272
	ds_read_b128 v[188:191], v237 offset:55296
	ds_read_b128 v[192:195], v237 offset:56320
	buffer_load_dwordx4 v221, s[44:47], s39 offen lds
	s_mov_b32 m0, s71
	s_add_i32 s12, s12, 0x40080
	buffer_load_dwordx4 v223, s[44:47], s39 offen lds
	s_mov_b32 m0, s74
	s_addk_i32 s13, 0x80
	buffer_load_dwordx4 v221, s[44:47], s12 offen lds
	s_mov_b32 m0, s75
	s_nop 0
	buffer_load_dwordx4 v223, s[44:47], s12 offen lds
	s_mov_b32 m0, s72
	s_nop 0
	buffer_load_dwordx4 v220, s[4:7], s13 offen lds
	s_waitcnt vmcnt(7)
	s_waitcnt lgkmcnt(0)
	s_setprio 1
	s_barrier
	v_mfma_f32_16x16x32_bf16 v[64:67], v[132:135], v[164:167], v[64:67]
	v_mfma_f32_16x16x32_bf16 v[60:63], v[140:143], v[164:167], v[60:63]
	v_mfma_f32_16x16x32_bf16 v[52:55], v[140:143], v[172:175], v[52:55]
	v_mfma_f32_16x16x32_bf16 v[56:59], v[132:135], v[172:175], v[56:59]
	v_mfma_f32_16x16x32_bf16 v[48:51], v[132:135], v[180:183], v[48:51]
	v_mfma_f32_16x16x32_bf16 v[44:47], v[140:143], v[180:183], v[44:47]
	v_mfma_f32_16x16x32_bf16 v[36:39], v[140:143], v[188:191], v[36:39]
	v_mfma_f32_16x16x32_bf16 v[40:43], v[132:135], v[188:191], v[40:43]
	v_mfma_f32_16x16x32_bf16 v[64:67], v[136:139], v[168:171], v[64:67]
	v_mfma_f32_16x16x32_bf16 v[60:63], v[144:147], v[168:171], v[60:63]
	v_mfma_f32_16x16x32_bf16 v[52:55], v[144:147], v[176:179], v[52:55]
	v_mfma_f32_16x16x32_bf16 v[56:59], v[136:139], v[176:179], v[56:59]
	v_mfma_f32_16x16x32_bf16 v[48:51], v[136:139], v[184:187], v[48:51]
	v_mfma_f32_16x16x32_bf16 v[44:47], v[144:147], v[184:187], v[44:47]
	v_mfma_f32_16x16x32_bf16 v[36:39], v[144:147], v[192:195], v[36:39]
	v_mfma_f32_16x16x32_bf16 v[40:43], v[136:139], v[192:195], v[40:43]
	v_mfma_f32_16x16x32_bf16 v[32:35], v[148:151], v[164:167], v[32:35]
	v_mfma_f32_16x16x32_bf16 v[28:31], v[156:159], v[164:167], v[28:31]
	v_mfma_f32_16x16x32_bf16 v[20:23], v[156:159], v[172:175], v[20:23]
	v_mfma_f32_16x16x32_bf16 v[24:27], v[148:151], v[172:175], v[24:27]
	v_mfma_f32_16x16x32_bf16 v[16:19], v[148:151], v[180:183], v[16:19]
	v_mfma_f32_16x16x32_bf16 v[12:15], v[156:159], v[180:183], v[12:15]
	v_mfma_f32_16x16x32_bf16 v[2:5], v[156:159], v[188:191], v[2:5]
	v_mfma_f32_16x16x32_bf16 v[6:9], v[148:151], v[188:191], v[8:11]
	v_mfma_f32_16x16x32_bf16 v[32:35], v[152:155], v[168:171], v[32:35]
	v_mfma_f32_16x16x32_bf16 v[28:31], v[160:163], v[168:171], v[28:31]
	v_mfma_f32_16x16x32_bf16 v[20:23], v[160:163], v[176:179], v[20:23]
	v_mfma_f32_16x16x32_bf16 v[24:27], v[152:155], v[176:179], v[24:27]
	v_mfma_f32_16x16x32_bf16 v[16:19], v[152:155], v[184:187], v[16:19]
	v_mfma_f32_16x16x32_bf16 v[12:15], v[160:163], v[184:187], v[12:15]
	v_mfma_f32_16x16x32_bf16 v[8:11], v[152:155], v[192:195], v[6:9]
	v_mfma_f32_16x16x32_bf16 v[4:7], v[160:163], v[192:195], v[2:5]
	s_barrier
	s_setprio 0
	s_add_i32 s38, s38, 2
	s_add_u32 s19, s19, 0x100
	s_addc_u32 s23, s23, 0
	s_cmp_gt_u32 s38, 13
	s_mov_b64 s[12:13], s[16:17]
	s_cbranch_scc0 .LBB0_1037
	s_and_b64 vcc, exec, s[14:15]
	s_cbranch_vccz .LBB0_1040
	s_barrier

; #define PG8_STAGE(bufoff, gbase, voff) do { const int so_ = (int)(unsigned)((const char*)(gbase) - base_##voff); _Pragma("unroll") for (int _i = 0; _i < 2; ++_i) \
;         __builtin_amdgcn_raw_ptr_buffer_load_lds(rs_##voff, (PG8_LAS unsigned*)(lds + (bufoff) + ldsw + _i * 8192), 16, (int)(voff)[_i], so_, 0, 0); } while (0)
; #define PG8_LDA(dst, b, h) do { _Pragma("unroll") for (int m = 0; m < 4; ++m) _Pragma("unroll") for (int k = 0; k < 2; ++k) dst[m][k] = *(const PG8_LAS bf16x8*)(lds + PG8_SA(b, h) + aoff + m * 2048 + k * 1024); } while (0)
; #define PG8_LDB(dst, b, h) do { _Pragma("unroll") for (int n = 0; n < 2; ++n) _Pragma("unroll") for (int k = 0; k < 2; ++k) dst[n][k] = *(const PG8_LAS bf16x8*)(lds + PG8_SB(b, h) + boff + n * 2048 + k * 1024); } while (0)
; #define PG8_WAIT_V(n) asm volatile("s_waitcnt vmcnt(" #n ")" ::: "memory")
; #define PG8_WAIT_L(n) asm volatile("s_waitcnt lgkmcnt(" #n ")" ::: "memory")
; #define PG8_BAR __builtin_amdgcn_s_barrier()
; #define PG8_SCHED __builtin_amdgcn_sched_barrier(0)
; template <class Epi, class Sched, bool ALIGN_EPI = false, bool SP2 = false>
; __device__ __forceinline__ void gemm_phase(PG8_LAS unsigned char* lds, const Gemm g, const Sched& S, const Epi& E, int tid_in) {
;     ...
;         const char* nA = has_next ? (const char*)g.A + (size_t)nxt.pm * tstepA + (g.grp ? (size_t)(nxt.pn / g.grp) * g.agrp : (size_t)0) : cA; const char* nB = has_next ? (const char*)g.Bt + (size_t)nxt.pn * tstepB : cB;
;         for (int t = 0; t < nt; t += 2) {
;             const bool last = (t == nt - 2);
;             const char* a1 = cA + (size_t)(t + 1) * kstep;
;             const char* a2 = last ? nA : cA + (size_t)(t + 2) * kstep; const char* b2 = last ? nB : cB + (size_t)(t + 2) * kstep;
;             const char* a3 = a2 + kstep; const char* b3 = b2 + kstep;
;             if (last && has_next) S.a_ready(nxt);
;             if constexpr (SP2) {
;             PG8_LDB(B0, 0, 0); PG8_LDB(B1, 0, 1); PG8_SCHED; PG8_LDA(At, 0, 0); PG8_STAGE(PG8_SA(1, 1), a1 + hstepA, voffA);
;             PG8_WAIT_V(8); PG8_WAIT_L(0); PG8_BAR; PG8_MMA(0, 0, At, B0); PG8_MMA(0, 1, At, B1); PG8_BAR; PG8_SCHED;
;             PG8_LDA(At, 0, 1); PG8_STAGE(PG8_SB(0, 0), b2, voffB); PG8_STAGE(PG8_SB(0, 1), b2 + hstepB, voffB); PG8_STAGE(PG8_SA(0, 0), a2, voffA);
.LBB0_1264:
	s_ashr_i32 s21, s20, 31
	s_lshl_b64 s[18:19], s[20:21], 20
	s_add_u32 s22, s4, s18
	s_addc_u32 s23, s9, s19
	s_and_b64 s[18:19], s[38:39], exec
	s_cselect_b32 s15, s22, s14
	s_ashr_i32 s17, s16, 31
	s_lshl_b64 s[18:19], s[16:17], 20
	s_add_u32 s24, s40, s18
	s_addc_u32 s25, s34, s19
	s_and_b64 s[18:19], s[38:39], exec
	s_cselect_b32 s17, s24, s12
	s_add_i32 s18, s14, s77
	s_add_i32 s18, s18, 0x80000
	s_mov_b32 s19, -2
	s_mov_b64 s[44:45], 0x100
	v_add_u32_e32 v251, 0x10000, v131
.LBB0_1265:
	ds_read_b128 v[134:137], v251
	ds_read_b128 v[138:141], v251 offset:1024
	ds_read_b128 v[142:145], v251 offset:2048
	ds_read_b128 v[146:149], v251 offset:3072
	ds_read_b128 v[150:153], v251 offset:16384
	ds_read_b128 v[154:157], v251 offset:17408
	ds_read_b128 v[158:161], v251 offset:18432
	ds_read_b128 v[166:169], v251 offset:19456
	s_add_i32 s42, s18, s44
	s_add_i32 s21, s14, s44
	s_add_i32 s79, s12, s44
	s_addk_i32 s42, 0xff80
	s_sub_i32 vcc_lo, s42, 0x80000
	s_cmp_eq_u32 s19, 28
	s_cselect_b32 s21, s15, s21
	s_mov_b32 m0, s75
	ds_read_b128 v[170:173], v132
	ds_read_b128 v[174:177], v132 offset:1024
	ds_read_b128 v[178:181], v132 offset:2048
	ds_read_b128 v[182:185], v132 offset:3072
	ds_read_b128 v[186:189], v132 offset:4096
	ds_read_b128 v[190:193], v132 offset:5120
	ds_read_b128 v[200:203], v132 offset:6144
	ds_read_b128 v[206:209], v132 offset:7168
	s_mov_b32 m0, s72
	s_nop 0
	buffer_load_dwordx4 v130, s[4:7], vcc_lo offen lds
	s_mov_b32 m0, s75
	s_nop 0
	buffer_load_dwordx4 v0, s[4:7], s42 offen lds
	s_mov_b32 m0, s76
	s_nop 0
	buffer_load_dwordx4 v130, s[4:7], s42 offen lds
	s_waitcnt vmcnt(8)
	s_waitcnt lgkmcnt(0)
	s_setprio 1
	s_barrier
	v_mfma_f32_16x16x32_bf16 v[34:37], v[134:137], v[170:173], v[34:37]
	v_mfma_f32_16x16x32_bf16 v[18:21], v[142:145], v[170:173], v[18:21]
	v_mfma_f32_16x16x32_bf16 v[78:81], v[142:145], v[178:181], v[78:81]
	v_mfma_f32_16x16x32_bf16 v[86:89], v[134:137], v[178:181], v[86:89]
	v_mfma_f32_16x16x32_bf16 v[106:109], v[134:137], v[186:189], v[106:109]
	v_mfma_f32_16x16x32_bf16 v[102:105], v[142:145], v[186:189], v[102:105]
	v_mfma_f32_16x16x32_bf16 v[122:125], v[142:145], v[200:203], v[122:125]
	v_mfma_f32_16x16x32_bf16 v[126:129], v[134:137], v[200:203], v[126:129]
	v_mfma_f32_16x16x32_bf16 v[34:37], v[138:141], v[174:177], v[34:37]
	v_mfma_f32_16x16x32_bf16 v[18:21], v[146:149], v[174:177], v[18:21]
	v_mfma_f32_16x16x32_bf16 v[78:81], v[146:149], v[182:185], v[78:81]
	v_mfma_f32_16x16x32_bf16 v[86:89], v[138:141], v[182:185], v[86:89]
	v_mfma_f32_16x16x32_bf16 v[106:109], v[138:141], v[190:193], v[106:109]
	v_mfma_f32_16x16x32_bf16 v[102:105], v[146:149], v[190:193], v[102:105]
	v_mfma_f32_16x16x32_bf16 v[122:125], v[146:149], v[206:209], v[122:125]
	v_mfma_f32_16x16x32_bf16 v[126:129], v[138:141], v[206:209], v[126:129]
	v_mfma_f32_16x16x32_bf16 v[14:17], v[150:153], v[170:173], v[14:17]
	v_mfma_f32_16x16x32_bf16 v[38:41], v[158:161], v[170:173], v[38:41]
	v_mfma_f32_16x16x32_bf16 v[90:93], v[158:161], v[178:181], v[90:93]
	v_mfma_f32_16x16x32_bf16 v[74:77], v[150:153], v[178:181], v[74:77]
	v_mfma_f32_16x16x32_bf16 v[98:101], v[150:153], v[186:189], v[98:101]
	v_mfma_f32_16x16x32_bf16 v[110:113], v[158:161], v[186:189], v[110:113]
	v_mfma_f32_16x16x32_bf16 v[114:117], v[158:161], v[200:203], v[114:117]
	v_mfma_f32_16x16x32_bf16 v[118:121], v[150:153], v[200:203], v[118:121]
	v_mfma_f32_16x16x32_bf16 v[14:17], v[154:157], v[174:177], v[14:17]
	v_mfma_f32_16x16x32_bf16 v[38:41], v[166:169], v[174:177], v[38:41]
	v_mfma_f32_16x16x32_bf16 v[90:93], v[166:169], v[182:185], v[90:93]
	v_mfma_f32_16x16x32_bf16 v[74:77], v[154:157], v[182:185], v[74:77]
	v_mfma_f32_16x16x32_bf16 v[98:101], v[154:157], v[190:193], v[98:101]
	v_mfma_f32_16x16x32_bf16 v[110:113], v[166:169], v[190:193], v[110:113]
	v_mfma_f32_16x16x32_bf16 v[114:117], v[166:169], v[206:209], v[114:117]
	v_mfma_f32_16x16x32_bf16 v[118:121], v[154:157], v[206:209], v[118:121]
	s_barrier
	s_setprio 0
	s_cselect_b32 s79, s17, s79
	s_mov_b32 m0, s49
	s_mov_b32 s42, s6
	s_mov_b32 s43, s7
	s_sub_i32 s79, s79, s40
	ds_read_b128 v[170:173], v132 offset:16384
	ds_read_b128 v[174:177], v132 offset:17408
	ds_read_b128 v[178:181], v132 offset:18432
	ds_read_b128 v[182:185], v132 offset:19456
	ds_read_b128 v[186:189], v132 offset:20480
	ds_read_b128 v[190:193], v132 offset:21504
	ds_read_b128 v[200:203], v132 offset:22528
	ds_read_b128 v[206:209], v132 offset:23552
	buffer_load_dwordx4 v0, s[40:43], s79 offen lds
	s_mov_b32 m0, s60
	s_add_i32 vcc_lo, s79, 0x80000
	buffer_load_dwordx4 v130, s[40:43], s79 offen lds
	s_mov_b32 m0, s61
	s_sub_i32 s21, s21, s4
	buffer_load_dwordx4 v0, s[40:43], vcc_lo offen lds
	s_mov_b32 m0, s62
	s_nop 0
	buffer_load_dwordx4 v130, s[40:43], vcc_lo offen lds
	s_mov_b32 m0, s35
	s_nop 0
	buffer_load_dwordx4 v0, s[4:7], s21 offen lds
	s_waitcnt vmcnt(7)
	s_waitcnt lgkmcnt(0)
	s_setprio 1
	s_barrier
; #define PG8_STAGE(bufoff, gbase, voff) do { const int so_ = (int)(unsigned)((const char*)(gbase) - base_##voff); _Pragma("unroll") for (int _i = 0; _i < 2; ++_i) \
;         __builtin_amdgcn_raw_ptr_buffer_load_lds(rs_##voff, (PG8_LAS unsigned*)(lds + (bufoff) + ldsw + _i * 8192), 16, (int)(voff)[_i], so_, 0, 0); } while (0)
; #define PG8_LDA(dst, b, h) do { _Pragma("unroll") for (int m = 0; m < 4; ++m) _Pragma("unroll") for (int k = 0; k < 2; ++k) dst[m][k] = *(const PG8_LAS bf16x8*)(lds + PG8_SA(b, h) + aoff + m * 2048 + k * 1024); } while (0)
; #define PG8_LDB(dst, b, h) do { _Pragma("unroll") for (int n = 0; n < 2; ++n) _Pragma("unroll") for (int k = 0; k < 2; ++k) dst[n][k] = *(const PG8_LAS bf16x8*)(lds + PG8_SB(b, h) + boff + n * 2048 + k * 1024); } while (0)
; #define PG8_MMA(ai, bj, At, Bt) do { __builtin_amdgcn_s_setprio(1); _Pragma("unroll") for (int m = 0; m < 4; ++m) _Pragma("unroll") for (int n = 0; n < 2; ++n) _Pragma("unroll") for (int k = 0; k < 2; ++k) \
;         acc[ai][bj][m][n] = __builtin_amdgcn_mfma_f32_16x16x32_bf16(Bt[n][k], At[m][k], acc[ai][bj][m][n], 0, 0, 0); __builtin_amdgcn_s_setprio(0); } while (0)
; #define PG8_WAIT_V(n) asm volatile("s_waitcnt vmcnt(" #n ")" ::: "memory")
; #define PG8_WAIT_L(n) asm volatile("s_waitcnt lgkmcnt(" #n ")" ::: "memory")
; #define PG8_BAR __builtin_amdgcn_s_barrier()
; #define PG8_SCHED __builtin_amdgcn_sched_barrier(0)
; template <class Epi, class Sched, bool ALIGN_EPI = false, bool SP2 = false>
; __device__ __forceinline__ void gemm_phase(PG8_LAS unsigned char* lds, const Gemm g, const Sched& S, const Epi& E, int tid_in) {
;     ...
;             PG8_WAIT_V(8); PG8_WAIT_L(0); PG8_BAR; PG8_MMA(1, 0, At, B0); PG8_MMA(1, 1, At, B1); PG8_BAR; PG8_SCHED;
;             PG8_LDB(B0, 1, 0); PG8_LDB(B1, 1, 1); PG8_SCHED; PG8_LDA(At, 1, 0); PG8_STAGE(PG8_SA(0, 1), a2 + hstepA, voffA);
;             PG8_WAIT_V(8); PG8_WAIT_L(0); PG8_BAR; PG8_MMA(0, 0, At, B0); PG8_MMA(0, 1, At, B1); PG8_BAR; PG8_SCHED;
;             PG8_LDA(At, 1, 1); PG8_STAGE(PG8_SB(1, 0), b3, voffB); PG8_STAGE(PG8_SB(1, 1), b3 + hstepB, voffB); PG8_STAGE(PG8_SA(1, 0), a3, voffA);
	v_mfma_f32_16x16x32_bf16 v[50:53], v[134:137], v[170:173], v[50:53]
	v_mfma_f32_16x16x32_bf16 v[30:33], v[142:145], v[170:173], v[30:33]
	v_mfma_f32_16x16x32_bf16 v[58:61], v[142:145], v[178:181], v[58:61]
	v_mfma_f32_16x16x32_bf16 v[62:65], v[134:137], v[178:181], v[62:65]
	v_mfma_f32_16x16x32_bf16 v[94:97], v[134:137], v[186:189], v[94:97]
	v_mfma_f32_16x16x32_bf16 v[82:85], v[142:145], v[186:189], v[82:85]
	v_mfma_f32_16x16x32_bf16 v[26:29], v[142:145], v[200:203], v[26:29]
	v_mfma_f32_16x16x32_bf16 v[46:49], v[134:137], v[200:203], v[46:49]
	v_mfma_f32_16x16x32_bf16 v[50:53], v[138:141], v[174:177], v[50:53]
	v_mfma_f32_16x16x32_bf16 v[30:33], v[146:149], v[174:177], v[30:33]
	v_mfma_f32_16x16x32_bf16 v[58:61], v[146:149], v[182:185], v[58:61]
	v_mfma_f32_16x16x32_bf16 v[62:65], v[138:141], v[182:185], v[62:65]
	v_mfma_f32_16x16x32_bf16 v[94:97], v[138:141], v[190:193], v[94:97]
	v_mfma_f32_16x16x32_bf16 v[82:85], v[146:149], v[190:193], v[82:85]
	v_mfma_f32_16x16x32_bf16 v[26:29], v[146:149], v[206:209], v[26:29]
	v_mfma_f32_16x16x32_bf16 v[46:49], v[138:141], v[206:209], v[46:49]
	v_mfma_f32_16x16x32_bf16 v[22:25], v[150:153], v[170:173], v[22:25]
	v_mfma_f32_16x16x32_bf16 v[10:13], v[158:161], v[170:173], v[10:13]
	v_mfma_f32_16x16x32_bf16 v[66:69], v[158:161], v[178:181], v[66:69]
	v_mfma_f32_16x16x32_bf16 v[54:57], v[150:153], v[178:181], v[54:57]
	v_mfma_f32_16x16x32_bf16 v[70:73], v[150:153], v[186:189], v[70:73]
	v_mfma_f32_16x16x32_bf16 v[42:45], v[158:161], v[186:189], v[42:45]
	v_mfma_f32_16x16x32_bf16 v[2:5], v[158:161], v[200:203], v[2:5]
	v_mfma_f32_16x16x32_bf16 v[6:9], v[150:153], v[200:203], v[6:9]
	v_mfma_f32_16x16x32_bf16 v[22:25], v[154:157], v[174:177], v[22:25]
	v_mfma_f32_16x16x32_bf16 v[10:13], v[166:169], v[174:177], v[10:13]
	v_mfma_f32_16x16x32_bf16 v[66:69], v[166:169], v[182:185], v[66:69]
	v_mfma_f32_16x16x32_bf16 v[54:57], v[154:157], v[182:185], v[54:57]
	v_mfma_f32_16x16x32_bf16 v[70:73], v[154:157], v[190:193], v[70:73]
	v_mfma_f32_16x16x32_bf16 v[42:45], v[166:169], v[190:193], v[42:45]
	v_mfma_f32_16x16x32_bf16 v[2:5], v[166:169], v[206:209], v[2:5]
	v_mfma_f32_16x16x32_bf16 v[6:9], v[154:157], v[206:209], v[6:9]
	s_barrier
	s_setprio 0
	ds_read_b128 v[134:137], v251 offset:32768
	ds_read_b128 v[138:141], v251 offset:33792
	ds_read_b128 v[142:145], v251 offset:34816
	ds_read_b128 v[146:149], v251 offset:35840
	ds_read_b128 v[150:153], v251 offset:49152
	ds_read_b128 v[154:157], v251 offset:50176
	ds_read_b128 v[158:161], v251 offset:51200
	ds_read_b128 v[166:169], v251 offset:52224
	s_add_i32 vcc_lo, s21, 0x80000
	s_mov_b32 m0, s66
	ds_read_b128 v[170:173], v132 offset:32768
	ds_read_b128 v[174:177], v132 offset:33792
	ds_read_b128 v[178:181], v132 offset:34816
	ds_read_b128 v[182:185], v132 offset:35840
	ds_read_b128 v[186:189], v132 offset:36864
	ds_read_b128 v[190:193], v132 offset:37888
	ds_read_b128 v[200:203], v132 offset:38912
	ds_read_b128 v[206:209], v132 offset:39936
	s_mov_b32 m0, s63
	s_nop 0
	buffer_load_dwordx4 v130, s[4:7], s21 offen lds
	s_mov_b32 m0, s66
	s_nop 0
	buffer_load_dwordx4 v0, s[4:7], vcc_lo offen lds
	s_mov_b32 m0, s67
	s_nop 0
	buffer_load_dwordx4 v130, s[4:7], vcc_lo offen lds
	s_waitcnt vmcnt(8)
	s_waitcnt lgkmcnt(0)
	s_setprio 1
	s_barrier
	v_mfma_f32_16x16x32_bf16 v[34:37], v[134:137], v[170:173], v[34:37]
	v_mfma_f32_16x16x32_bf16 v[18:21], v[142:145], v[170:173], v[18:21]
	v_mfma_f32_16x16x32_bf16 v[78:81], v[142:145], v[178:181], v[78:81]
	v_mfma_f32_16x16x32_bf16 v[86:89], v[134:137], v[178:181], v[86:89]
	v_mfma_f32_16x16x32_bf16 v[106:109], v[134:137], v[186:189], v[106:109]
	v_mfma_f32_16x16x32_bf16 v[102:105], v[142:145], v[186:189], v[102:105]
	v_mfma_f32_16x16x32_bf16 v[122:125], v[142:145], v[200:203], v[122:125]
	v_mfma_f32_16x16x32_bf16 v[126:129], v[134:137], v[200:203], v[126:129]
	v_mfma_f32_16x16x32_bf16 v[34:37], v[138:141], v[174:177], v[34:37]
	v_mfma_f32_16x16x32_bf16 v[18:21], v[146:149], v[174:177], v[18:21]
	v_mfma_f32_16x16x32_bf16 v[78:81], v[146:149], v[182:185], v[78:81]
	v_mfma_f32_16x16x32_bf16 v[86:89], v[138:141], v[182:185], v[86:89]
	v_mfma_f32_16x16x32_bf16 v[106:109], v[138:141], v[190:193], v[106:109]
	v_mfma_f32_16x16x32_bf16 v[102:105], v[146:149], v[190:193], v[102:105]
	v_mfma_f32_16x16x32_bf16 v[122:125], v[146:149], v[206:209], v[122:125]
	v_mfma_f32_16x16x32_bf16 v[126:129], v[138:141], v[206:209], v[126:129]
	v_mfma_f32_16x16x32_bf16 v[14:17], v[150:153], v[170:173], v[14:17]
	v_mfma_f32_16x16x32_bf16 v[38:41], v[158:161], v[170:173], v[38:41]
	v_mfma_f32_16x16x32_bf16 v[90:93], v[158:161], v[178:181], v[90:93]
	v_mfma_f32_16x16x32_bf16 v[74:77], v[150:153], v[178:181], v[74:77]
	v_mfma_f32_16x16x32_bf16 v[98:101], v[150:153], v[186:189], v[98:101]
	v_mfma_f32_16x16x32_bf16 v[110:113], v[158:161], v[186:189], v[110:113]
	v_mfma_f32_16x16x32_bf16 v[114:117], v[158:161], v[200:203], v[114:117]
	v_mfma_f32_16x16x32_bf16 v[118:121], v[150:153], v[200:203], v[118:121]
	v_mfma_f32_16x16x32_bf16 v[14:17], v[154:157], v[174:177], v[14:17]
	v_mfma_f32_16x16x32_bf16 v[38:41], v[166:169], v[174:177], v[38:41]
	v_mfma_f32_16x16x32_bf16 v[90:93], v[166:169], v[182:185], v[90:93]
	v_mfma_f32_16x16x32_bf16 v[74:77], v[154:157], v[182:185], v[74:77]
	v_mfma_f32_16x16x32_bf16 v[98:101], v[154:157], v[190:193], v[98:101]
	v_mfma_f32_16x16x32_bf16 v[110:113], v[166:169], v[190:193], v[110:113]
	v_mfma_f32_16x16x32_bf16 v[114:117], v[166:169], v[206:209], v[114:117]
	v_mfma_f32_16x16x32_bf16 v[118:121], v[154:157], v[206:209], v[118:121]
	s_barrier
;     static __device__ __forceinline__ bool last_of_chain(const Unit& u) { return (u.pn >> 3) == 2; }
; #define PG8_STAGE(bufoff, gbase, voff) do { const int so_ = (int)(unsigned)((const char*)(gbase) - base_##voff); _Pragma("unroll") for (int _i = 0; _i < 2; ++_i) \
;         __builtin_amdgcn_raw_ptr_buffer_load_lds(rs_##voff, (PG8_LAS unsigned*)(lds + (bufoff) + ldsw + _i * 8192), 16, (int)(voff)[_i], so_, 0, 0); } while (0)
; #define PG8_LDA(dst, b, h) do { _Pragma("unroll") for (int m = 0; m < 4; ++m) _Pragma("unroll") for (int k = 0; k < 2; ++k) dst[m][k] = *(const PG8_LAS bf16x8*)(lds + PG8_SA(b, h) + aoff + m * 2048 + k * 1024); } while (0)
; #define PG8_MMA(ai, bj, At, Bt) do { __builtin_amdgcn_s_setprio(1); _Pragma("unroll") for (int m = 0; m < 4; ++m) _Pragma("unroll") for (int n = 0; n < 2; ++n) _Pragma("unroll") for (int k = 0; k < 2; ++k) \
;         acc[ai][bj][m][n] = __builtin_amdgcn_mfma_f32_16x16x32_bf16(Bt[n][k], At[m][k], acc[ai][bj][m][n], 0, 0, 0); __builtin_amdgcn_s_setprio(0); } while (0)
; #define PG8_WAIT_V(n) asm volatile("s_waitcnt vmcnt(" #n ")" ::: "memory")
; #define PG8_WAIT_L(n) asm volatile("s_waitcnt lgkmcnt(" #n ")" ::: "memory")
; #define PG8_BAR __builtin_amdgcn_s_barrier()
; #define PG8_SCHED __builtin_amdgcn_sched_barrier(0)
; template <class Epi, class Sched, bool ALIGN_EPI = false, bool SP2 = false>
; __device__ __forceinline__ void gemm_phase(PG8_LAS unsigned char* lds, const Gemm g, const Sched& S, const Epi& E, int tid_in) {
;     ...
;             PG8_LDA(At, 1, 1); PG8_STAGE(PG8_SB(1, 0), b3, voffB); PG8_STAGE(PG8_SB(1, 1), b3 + hstepB, voffB); PG8_STAGE(PG8_SA(1, 0), a3, voffA);
;             PG8_WAIT_V(8); PG8_WAIT_L(0); PG8_BAR; PG8_MMA(1, 0, At, B0); PG8_MMA(1, 1, At, B1); PG8_BAR; PG8_SCHED;
;     ...
;         bool zero_acc = true; if constexpr (Epi::CHAIN) zero_acc = Epi::last_of_chain(cur);
;         if (zero_acc) {
; #pragma unroll
;         for (int a = 0; a < 2; ++a)
; #pragma unroll
;             for (int b = 0; b < 2; ++b)
; #pragma unroll
;                 for (int m = 0; m < 4; ++m)
; #pragma unroll
;                     for (int n = 0; n < 2; ++n) acc[a][b][m][n] = (f32x4){0.f, 0.f, 0.f, 0.f};
;         }
	s_setprio 0
	s_mov_b32 m0, s68
	s_add_i32 vcc_lo, s79, 0x80
	ds_read_b128 v[170:173], v132 offset:49152
	ds_read_b128 v[174:177], v132 offset:50176
	ds_read_b128 v[178:181], v132 offset:51200
	ds_read_b128 v[182:185], v132 offset:52224
	ds_read_b128 v[186:189], v132 offset:53248
	ds_read_b128 v[190:193], v132 offset:54272
	ds_read_b128 v[200:203], v132 offset:55296
	ds_read_b128 v[206:209], v132 offset:56320
	buffer_load_dwordx4 v0, s[40:43], vcc_lo offen lds
	s_mov_b32 m0, s69
	s_add_i32 s79, s79, 0x80080
	buffer_load_dwordx4 v130, s[40:43], vcc_lo offen lds
	s_mov_b32 m0, s73
	s_addk_i32 s21, 0x80
	buffer_load_dwordx4 v0, s[40:43], s79 offen lds
	s_mov_b32 m0, s74
	s_nop 0
	buffer_load_dwordx4 v130, s[40:43], s79 offen lds
	s_mov_b32 m0, s71
	s_nop 0
	buffer_load_dwordx4 v0, s[4:7], s21 offen lds
	s_waitcnt vmcnt(7)
	s_waitcnt lgkmcnt(0)
	s_setprio 1
	s_barrier
	v_mfma_f32_16x16x32_bf16 v[50:53], v[134:137], v[170:173], v[50:53]
	v_mfma_f32_16x16x32_bf16 v[30:33], v[142:145], v[170:173], v[30:33]
	v_mfma_f32_16x16x32_bf16 v[58:61], v[142:145], v[178:181], v[58:61]
	v_mfma_f32_16x16x32_bf16 v[62:65], v[134:137], v[178:181], v[62:65]
	v_mfma_f32_16x16x32_bf16 v[94:97], v[134:137], v[186:189], v[94:97]
	v_mfma_f32_16x16x32_bf16 v[82:85], v[142:145], v[186:189], v[82:85]
	v_mfma_f32_16x16x32_bf16 v[26:29], v[142:145], v[200:203], v[26:29]
	v_mfma_f32_16x16x32_bf16 v[46:49], v[134:137], v[200:203], v[46:49]
	v_mfma_f32_16x16x32_bf16 v[50:53], v[138:141], v[174:177], v[50:53]
	v_mfma_f32_16x16x32_bf16 v[30:33], v[146:149], v[174:177], v[30:33]
	v_mfma_f32_16x16x32_bf16 v[58:61], v[146:149], v[182:185], v[58:61]
	v_mfma_f32_16x16x32_bf16 v[62:65], v[138:141], v[182:185], v[62:65]
	v_mfma_f32_16x16x32_bf16 v[94:97], v[138:141], v[190:193], v[94:97]
	v_mfma_f32_16x16x32_bf16 v[82:85], v[146:149], v[190:193], v[82:85]
	v_mfma_f32_16x16x32_bf16 v[26:29], v[146:149], v[206:209], v[26:29]
	v_mfma_f32_16x16x32_bf16 v[46:49], v[138:141], v[206:209], v[46:49]
	v_mfma_f32_16x16x32_bf16 v[22:25], v[150:153], v[170:173], v[22:25]
	v_mfma_f32_16x16x32_bf16 v[10:13], v[158:161], v[170:173], v[10:13]
	v_mfma_f32_16x16x32_bf16 v[66:69], v[158:161], v[178:181], v[66:69]
	v_mfma_f32_16x16x32_bf16 v[54:57], v[150:153], v[178:181], v[54:57]
	v_mfma_f32_16x16x32_bf16 v[70:73], v[150:153], v[186:189], v[70:73]
	v_mfma_f32_16x16x32_bf16 v[42:45], v[158:161], v[186:189], v[42:45]
	v_mfma_f32_16x16x32_bf16 v[2:5], v[158:161], v[200:203], v[2:5]
	v_mfma_f32_16x16x32_bf16 v[6:9], v[150:153], v[200:203], v[6:9]
	v_mfma_f32_16x16x32_bf16 v[22:25], v[154:157], v[174:177], v[22:25]
	v_mfma_f32_16x16x32_bf16 v[10:13], v[166:169], v[174:177], v[10:13]
	v_mfma_f32_16x16x32_bf16 v[66:69], v[166:169], v[182:185], v[66:69]
	v_mfma_f32_16x16x32_bf16 v[54:57], v[154:157], v[182:185], v[54:57]
	v_mfma_f32_16x16x32_bf16 v[70:73], v[154:157], v[190:193], v[70:73]
	v_mfma_f32_16x16x32_bf16 v[42:45], v[166:169], v[190:193], v[42:45]
	v_mfma_f32_16x16x32_bf16 v[2:5], v[166:169], v[206:209], v[2:5]
	v_mfma_f32_16x16x32_bf16 v[6:9], v[154:157], v[206:209], v[6:9]
	s_barrier
	s_setprio 0
	s_add_i32 s19, s19, 2
	s_add_u32 s44, s44, 0x100
	s_addc_u32 s45, s45, 0
	s_cmp_gt_u32 s19, 29
	s_cbranch_scc0 .LBB0_1265
	s_andn2_b64 vcc, exec, s[38:39]
	s_cbranch_vccnz .LBB0_1257
	v_mov_b32_e32 v2, 0
	s_mov_b64 s[12:13], s[24:25]
	s_mov_b32 s10, s16
	s_mov_b32 s48, s20
	s_mov_b64 s[14:15], s[22:23]
	s_mov_b32 s13, s78
	v_mov_b32_e32 v3, v2
	v_mov_b32_e32 v4, v2
	v_mov_b32_e32 v5, v2
	v_mov_b32_e32 v6, v2
	v_mov_b32_e32 v7, v2
	v_mov_b32_e32 v8, v2
	v_mov_b32_e32 v9, v2
	v_mov_b32_e32 v42, v2
	v_mov_b32_e32 v43, v2
	v_mov_b32_e32 v44, v2
	v_mov_b32_e32 v45, v2
	v_mov_b32_e32 v70, v2
	v_mov_b32_e32 v71, v2
	v_mov_b32_e32 v72, v2
	v_mov_b32_e32 v73, v2
	v_mov_b32_e32 v66, v2
	v_mov_b32_e32 v67, v2
	v_mov_b32_e32 v68, v2
	v_mov_b32_e32 v69, v2
	v_mov_b32_e32 v54, v2
	v_mov_b32_e32 v55, v2
	v_mov_b32_e32 v56, v2
	v_mov_b32_e32 v57, v2
	v_mov_b32_e32 v10, v2
	v_mov_b32_e32 v11, v2
	v_mov_b32_e32 v12, v2
	v_mov_b32_e32 v13, v2
	v_mov_b32_e32 v22, v2
	v_mov_b32_e32 v23, v2
	v_mov_b32_e32 v24, v2
	v_mov_b32_e32 v25, v2
	v_mov_b32_e32 v26, v2
	v_mov_b32_e32 v27, v2
	v_mov_b32_e32 v28, v2
	v_mov_b32_e32 v29, v2
	v_mov_b32_e32 v46, v2
	v_mov_b32_e32 v47, v2
	v_mov_b32_e32 v48, v2
	v_mov_b32_e32 v49, v2
	v_mov_b32_e32 v82, v2
	v_mov_b32_e32 v83, v2
	v_mov_b32_e32 v84, v2
	v_mov_b32_e32 v85, v2
	v_mov_b32_e32 v94, v2
	v_mov_b32_e32 v95, v2
	v_mov_b32_e32 v96, v2
	v_mov_b32_e32 v97, v2
	v_mov_b32_e32 v58, v2
	v_mov_b32_e32 v59, v2
	v_mov_b32_e32 v60, v2
	v_mov_b32_e32 v61, v2
	v_mov_b32_e32 v62, v2
	v_mov_b32_e32 v63, v2
	v_mov_b32_e32 v64, v2
	v_mov_b32_e32 v65, v2
	v_mov_b32_e32 v30, v2
	v_mov_b32_e32 v31, v2
	v_mov_b32_e32 v32, v2
	v_mov_b32_e32 v33, v2
	v_mov_b32_e32 v50, v2
	v_mov_b32_e32 v51, v2
	v_mov_b32_e32 v52, v2
	v_mov_b32_e32 v53, v2
	v_mov_b32_e32 v114, v2
	v_mov_b32_e32 v115, v2
	v_mov_b32_e32 v116, v2
	v_mov_b32_e32 v117, v2
	v_mov_b32_e32 v118, v2
	v_mov_b32_e32 v119, v2
	v_mov_b32_e32 v120, v2
	v_mov_b32_e32 v121, v2
	v_mov_b32_e32 v110, v2
	v_mov_b32_e32 v111, v2
	v_mov_b32_e32 v112, v2
	v_mov_b32_e32 v113, v2
	v_mov_b32_e32 v98, v2
	v_mov_b32_e32 v99, v2
	v_mov_b32_e32 v100, v2
	v_mov_b32_e32 v101, v2
	v_mov_b32_e32 v90, v2
	v_mov_b32_e32 v91, v2
	v_mov_b32_e32 v92, v2
	v_mov_b32_e32 v93, v2
	v_mov_b32_e32 v74, v2
	v_mov_b32_e32 v75, v2
	v_mov_b32_e32 v76, v2
	v_mov_b32_e32 v77, v2
	v_mov_b32_e32 v38, v2
	v_mov_b32_e32 v39, v2
	v_mov_b32_e32 v40, v2
	v_mov_b32_e32 v41, v2
	v_mov_b32_e32 v14, v2
	v_mov_b32_e32 v15, v2
	v_mov_b32_e32 v16, v2
	v_mov_b32_e32 v17, v2
	v_mov_b32_e32 v122, v2
	v_mov_b32_e32 v123, v2
	v_mov_b32_e32 v124, v2
	v_mov_b32_e32 v125, v2
	v_mov_b32_e32 v126, v2
	v_mov_b32_e32 v127, v2
	v_mov_b32_e32 v128, v2
	v_mov_b32_e32 v129, v2
	v_mov_b32_e32 v102, v2
	v_mov_b32_e32 v103, v2
	v_mov_b32_e32 v104, v2
	v_mov_b32_e32 v105, v2
	v_mov_b32_e32 v106, v2
	v_mov_b32_e32 v107, v2
	v_mov_b32_e32 v108, v2
	v_mov_b32_e32 v109, v2
	v_mov_b32_e32 v78, v2
	v_mov_b32_e32 v79, v2
	v_mov_b32_e32 v80, v2
	v_mov_b32_e32 v81, v2
	v_mov_b32_e32 v86, v2
	v_mov_b32_e32 v87, v2
	v_mov_b32_e32 v88, v2
	v_mov_b32_e32 v89, v2
	v_mov_b32_e32 v18, v2
	v_mov_b32_e32 v19, v2
	v_mov_b32_e32 v20, v2
	v_mov_b32_e32 v21, v2
	v_mov_b32_e32 v34, v2
	v_mov_b32_e32 v35, v2
	v_mov_b32_e32 v36, v2
	v_mov_b32_e32 v37, v2
	s_branch .LBB0_1257

;     __host__ __device__ bool next(int i, Unit& u) const { const int t = i / 3, b = i - 3 * t; Unit v; if (!StaticOrder::next(t, v)) return false; u.pm = v.pm; u.pn = 8 * b + v.pn; return true; }
; #define PG8_STAGE(bufoff, gbase, voff) do { const int so_ = (int)(unsigned)((const char*)(gbase) - base_##voff); _Pragma("unroll") for (int _i = 0; _i < 2; ++_i) \
;         __builtin_amdgcn_raw_ptr_buffer_load_lds(rs_##voff, (PG8_LAS unsigned*)(lds + (bufoff) + ldsw + _i * 8192), 16, (int)(voff)[_i], so_, 0, 0); } while (0)
; #define PG8_LDA(dst, b, h) do { _Pragma("unroll") for (int m = 0; m < 4; ++m) _Pragma("unroll") for (int k = 0; k < 2; ++k) dst[m][k] = *(const PG8_LAS bf16x8*)(lds + PG8_SA(b, h) + aoff + m * 2048 + k * 1024); } while (0)
; #define PG8_LDB(dst, b, h) do { _Pragma("unroll") for (int n = 0; n < 2; ++n) _Pragma("unroll") for (int k = 0; k < 2; ++k) dst[n][k] = *(const PG8_LAS bf16x8*)(lds + PG8_SB(b, h) + boff + n * 2048 + k * 1024); } while (0)
; #define PG8_SCHED __builtin_amdgcn_sched_barrier(0)
; template <class Epi, class Sched, bool ALIGN_EPI = false, bool SP2 = false>
; __device__ __forceinline__ void gemm_phase(PG8_LAS unsigned char* lds, const Gemm g, const Sched& S, const Epi& E, int tid_in) {
;     ...
;         const bool has_next = S.next(ui + 1, nxt);
;         const char* nA = has_next ? (const char*)g.A + (size_t)nxt.pm * tstepA + (g.grp ? (size_t)(nxt.pn / g.grp) * g.agrp : (size_t)0) : cA; const char* nB = has_next ? (const char*)g.Bt + (size_t)nxt.pn * tstepB : cB;
;         for (int t = 0; t < nt; t += 2) {
;             const bool last = (t == nt - 2);
;             const char* a1 = cA + (size_t)(t + 1) * kstep;
;             const char* a2 = last ? nA : cA + (size_t)(t + 2) * kstep; const char* b2 = last ? nB : cB + (size_t)(t + 2) * kstep;
;             const char* a3 = a2 + kstep; const char* b3 = b2 + kstep;
;             if (last && has_next) S.a_ready(nxt);
;             if constexpr (SP2) {
;             PG8_LDB(B0, 0, 0); PG8_LDB(B1, 0, 1); PG8_SCHED; PG8_LDA(At, 0, 0); PG8_STAGE(PG8_SA(1, 1), a1 + hstepA, voffA);
.LBB0_1513:
	s_ashr_i32 s21, s20, 31
	s_lshl_b64 s[18:19], s[20:21], 20
	s_add_u32 s22, s4, s18
	s_addc_u32 s23, s9, s19
	s_and_b64 s[18:19], s[36:37], exec
	s_cselect_b32 s18, s22, s16
	s_ashr_i32 s15, s14, 31
	s_lshl_b64 s[24:25], s[14:15], 20
	s_add_u32 s24, s40, s24
	s_addc_u32 s25, s26, s25
	s_and_b64 s[42:43], s[36:37], exec
	s_cselect_b32 s15, s24, s38
	s_add_u32 s19, s38, 0x100
	v_mov_b32_e32 v2, 0
	s_addc_u32 s21, s39, 0
	s_mov_b32 s73, -2
	v_add_u32_e32 v251, 0x10000, v139

; #define PG8_STAGE(bufoff, gbase, voff) do { const int so_ = (int)(unsigned)((const char*)(gbase) - base_##voff); _Pragma("unroll") for (int _i = 0; _i < 2; ++_i) \
;         __builtin_amdgcn_raw_ptr_buffer_load_lds(rs_##voff, (PG8_LAS unsigned*)(lds + (bufoff) + ldsw + _i * 8192), 16, (int)(voff)[_i], so_, 0, 0); } while (0)
; #define PG8_LDA(dst, b, h) do { _Pragma("unroll") for (int m = 0; m < 4; ++m) _Pragma("unroll") for (int k = 0; k < 2; ++k) dst[m][k] = *(const PG8_LAS bf16x8*)(lds + PG8_SA(b, h) + aoff + m * 2048 + k * 1024); } while (0)
; #define PG8_LDB(dst, b, h) do { _Pragma("unroll") for (int n = 0; n < 2; ++n) _Pragma("unroll") for (int k = 0; k < 2; ++k) dst[n][k] = *(const PG8_LAS bf16x8*)(lds + PG8_SB(b, h) + boff + n * 2048 + k * 1024); } while (0)
; #define PG8_MMA(ai, bj, At, Bt) do { __builtin_amdgcn_s_setprio(1); _Pragma("unroll") for (int m = 0; m < 4; ++m) _Pragma("unroll") for (int n = 0; n < 2; ++n) _Pragma("unroll") for (int k = 0; k < 2; ++k) \
;         acc[ai][bj][m][n] = __builtin_amdgcn_mfma_f32_16x16x32_bf16(Bt[n][k], At[m][k], acc[ai][bj][m][n], 0, 0, 0); __builtin_amdgcn_s_setprio(0); } while (0)
; #define PG8_WAIT_V(n) asm volatile("s_waitcnt vmcnt(" #n ")" ::: "memory")
; #define PG8_WAIT_L(n) asm volatile("s_waitcnt lgkmcnt(" #n ")" ::: "memory")
; #define PG8_BAR __builtin_amdgcn_s_barrier()
; #define PG8_SCHED __builtin_amdgcn_sched_barrier(0)
; template <class Epi, class Sched, bool ALIGN_EPI = false, bool SP2 = false>
; __device__ __forceinline__ void gemm_phase(PG8_LAS unsigned char* lds, const Gemm g, const Sched& S, const Epi& E, int tid_in) {
;     ...
;             PG8_LDB(B0, 0, 0); PG8_LDB(B1, 0, 1); PG8_SCHED; PG8_LDA(At, 0, 0); PG8_STAGE(PG8_SA(1, 1), a1 + hstepA, voffA);
;             PG8_WAIT_V(8); PG8_WAIT_L(0); PG8_BAR; PG8_MMA(0, 0, At, B0); PG8_MMA(0, 1, At, B1); PG8_BAR; PG8_SCHED;
;             PG8_LDA(At, 0, 1); PG8_STAGE(PG8_SB(0, 0), b2, voffB); PG8_STAGE(PG8_SB(0, 1), b2 + hstepB, voffB); PG8_STAGE(PG8_SA(0, 0), a2, voffA);
;             PG8_WAIT_V(8); PG8_WAIT_L(0); PG8_BAR; PG8_MMA(1, 0, At, B0); PG8_MMA(1, 1, At, B1); PG8_BAR; PG8_SCHED;
	ds_read_b128 v[130:133], v251
	ds_read_b128 v[142:145], v251 offset:1024
	ds_read_b128 v[146:149], v251 offset:2048
	ds_read_b128 v[150:153], v251 offset:3072
	ds_read_b128 v[154:157], v251 offset:16384
	ds_read_b128 v[158:161], v251 offset:17408
	ds_read_b128 v[162:165], v251 offset:18432
	ds_read_b128 v[166:169], v251 offset:19456
	s_add_u32 s38, s16, 0x100
	s_addc_u32 s39, s17, 0
	s_sub_i32 s16, s16, s4
	s_add_i32 s16, s16, 0x80080
	s_sub_i32 s74, s16, 0x80000
	s_cmp_eq_u32 s73, 28
	s_cselect_b32 s17, s18, s38
	s_mov_b32 m0, s67
	ds_read_b128 v[170:173], v140
	ds_read_b128 v[174:177], v140 offset:1024
	ds_read_b128 v[178:181], v140 offset:2048
	ds_read_b128 v[182:185], v140 offset:3072
	ds_read_b128 v[186:189], v140 offset:4096
	ds_read_b128 v[190:193], v140 offset:5120
	ds_read_b128 v[200:203], v140 offset:6144
	ds_read_b128 v[206:209], v140 offset:7168
	s_mov_b32 m0, s62
	s_nop 0
	buffer_load_dwordx4 v135, s[4:7], s74 offen lds
	s_mov_b32 m0, s67
	s_nop 0
	buffer_load_dwordx4 v0, s[4:7], s16 offen lds
	s_mov_b32 m0, s68
	s_nop 0
	buffer_load_dwordx4 v135, s[4:7], s16 offen lds
	s_waitcnt vmcnt(8)
	s_waitcnt lgkmcnt(0)
	s_setprio 1
	s_barrier
	v_mfma_f32_16x16x32_bf16 v[126:129], v[130:133], v[170:173], 0
	v_mfma_f32_16x16x32_bf16 v[122:125], v[146:149], v[170:173], 0
	v_mfma_f32_16x16x32_bf16 v[106:109], v[146:149], v[178:181], 0
	v_mfma_f32_16x16x32_bf16 v[110:113], v[130:133], v[178:181], 0
	v_mfma_f32_16x16x32_bf16 v[94:97], v[130:133], v[186:189], 0
	v_mfma_f32_16x16x32_bf16 v[90:93], v[146:149], v[186:189], 0
	v_mfma_f32_16x16x32_bf16 v[74:77], v[146:149], v[200:203], 0
	v_mfma_f32_16x16x32_bf16 v[78:81], v[130:133], v[200:203], 0
	v_mfma_f32_16x16x32_bf16 v[126:129], v[142:145], v[174:177], v[126:129]
	v_mfma_f32_16x16x32_bf16 v[122:125], v[150:153], v[174:177], v[122:125]
	v_mfma_f32_16x16x32_bf16 v[106:109], v[150:153], v[182:185], v[106:109]
	v_mfma_f32_16x16x32_bf16 v[110:113], v[142:145], v[182:185], v[110:113]
	v_mfma_f32_16x16x32_bf16 v[94:97], v[142:145], v[190:193], v[94:97]
	v_mfma_f32_16x16x32_bf16 v[90:93], v[150:153], v[190:193], v[90:93]
	v_mfma_f32_16x16x32_bf16 v[74:77], v[150:153], v[206:209], v[74:77]
	v_mfma_f32_16x16x32_bf16 v[78:81], v[142:145], v[206:209], v[78:81]
	v_mfma_f32_16x16x32_bf16 v[118:121], v[154:157], v[170:173], 0
	v_mfma_f32_16x16x32_bf16 v[114:117], v[162:165], v[170:173], 0
	v_mfma_f32_16x16x32_bf16 v[98:101], v[162:165], v[178:181], 0
	v_mfma_f32_16x16x32_bf16 v[102:105], v[154:157], v[178:181], 0
	v_mfma_f32_16x16x32_bf16 v[86:89], v[154:157], v[186:189], 0
	v_mfma_f32_16x16x32_bf16 v[82:85], v[162:165], v[186:189], 0
	v_mfma_f32_16x16x32_bf16 v[66:69], v[162:165], v[200:203], 0
	v_mfma_f32_16x16x32_bf16 v[70:73], v[154:157], v[200:203], 0
	v_mfma_f32_16x16x32_bf16 v[118:121], v[158:161], v[174:177], v[118:121]
	v_mfma_f32_16x16x32_bf16 v[114:117], v[166:169], v[174:177], v[114:117]
	v_mfma_f32_16x16x32_bf16 v[98:101], v[166:169], v[182:185], v[98:101]
	v_mfma_f32_16x16x32_bf16 v[102:105], v[158:161], v[182:185], v[102:105]
	v_mfma_f32_16x16x32_bf16 v[86:89], v[158:161], v[190:193], v[86:89]
	v_mfma_f32_16x16x32_bf16 v[82:85], v[166:169], v[190:193], v[82:85]
	v_mfma_f32_16x16x32_bf16 v[66:69], v[166:169], v[206:209], v[66:69]
	v_mfma_f32_16x16x32_bf16 v[70:73], v[158:161], v[206:209], v[70:73]
	s_barrier
	s_setprio 0
	s_cselect_b32 s16, s15, s19
	s_mov_b32 m0, s35
	s_mov_b32 s42, s6
	s_mov_b32 s43, s7
	s_sub_i32 s16, s16, s40
	ds_read_b128 v[170:173], v140 offset:16384
	ds_read_b128 v[174:177], v140 offset:17408
	ds_read_b128 v[178:181], v140 offset:18432
	ds_read_b128 v[182:185], v140 offset:19456
	ds_read_b128 v[186:189], v140 offset:20480
	ds_read_b128 v[190:193], v140 offset:21504
	ds_read_b128 v[200:203], v140 offset:22528
	ds_read_b128 v[206:209], v140 offset:23552
	buffer_load_dwordx4 v134, s[40:43], s16 offen lds
	s_mov_b32 m0, s44
	s_add_i32 s74, s16, 0x80000
	buffer_load_dwordx4 v136, s[40:43], s16 offen lds
	s_mov_b32 m0, s45
	s_sub_i32 s17, s17, s4
	buffer_load_dwordx4 v134, s[40:43], s74 offen lds
	s_mov_b32 m0, s46
	s_nop 0
	buffer_load_dwordx4 v136, s[40:43], s74 offen lds
	s_mov_b32 m0, s34
	s_nop 0
	buffer_load_dwordx4 v0, s[4:7], s17 offen lds
	s_waitcnt vmcnt(7)
	s_waitcnt lgkmcnt(0)
	s_setprio 1
	s_barrier
	v_mfma_f32_16x16x32_bf16 v[62:65], v[130:133], v[170:173], 0
	v_mfma_f32_16x16x32_bf16 v[58:61], v[146:149], v[170:173], 0
	v_mfma_f32_16x16x32_bf16 v[42:45], v[146:149], v[178:181], 0
	v_mfma_f32_16x16x32_bf16 v[46:49], v[130:133], v[178:181], 0
	v_mfma_f32_16x16x32_bf16 v[30:33], v[130:133], v[186:189], 0
	v_mfma_f32_16x16x32_bf16 v[26:29], v[146:149], v[186:189], 0
	v_mfma_f32_16x16x32_bf16 v[10:13], v[146:149], v[200:203], 0
	v_mfma_f32_16x16x32_bf16 v[14:17], v[130:133], v[200:203], 0
	v_mfma_f32_16x16x32_bf16 v[62:65], v[142:145], v[174:177], v[62:65]
	v_mfma_f32_16x16x32_bf16 v[58:61], v[150:153], v[174:177], v[58:61]
	v_mfma_f32_16x16x32_bf16 v[42:45], v[150:153], v[182:185], v[42:45]
	v_mfma_f32_16x16x32_bf16 v[46:49], v[142:145], v[182:185], v[46:49]
	v_mfma_f32_16x16x32_bf16 v[30:33], v[142:145], v[190:193], v[30:33]
	v_mfma_f32_16x16x32_bf16 v[26:29], v[150:153], v[190:193], v[26:29]
	v_mfma_f32_16x16x32_bf16 v[10:13], v[150:153], v[206:209], v[10:13]
	v_mfma_f32_16x16x32_bf16 v[14:17], v[142:145], v[206:209], v[14:17]
	v_mfma_f32_16x16x32_bf16 v[54:57], v[154:157], v[170:173], 0
	v_mfma_f32_16x16x32_bf16 v[50:53], v[162:165], v[170:173], 0
	v_mfma_f32_16x16x32_bf16 v[34:37], v[162:165], v[178:181], 0
	v_mfma_f32_16x16x32_bf16 v[38:41], v[154:157], v[178:181], 0
	v_mfma_f32_16x16x32_bf16 v[22:25], v[154:157], v[186:189], 0
	v_mfma_f32_16x16x32_bf16 v[18:21], v[162:165], v[186:189], 0
	v_mfma_f32_16x16x32_bf16 v[2:5], v[162:165], v[200:203], 0
	v_mfma_f32_16x16x32_bf16 v[6:9], v[154:157], v[200:203], 0
	v_mfma_f32_16x16x32_bf16 v[54:57], v[158:161], v[174:177], v[54:57]
	v_mfma_f32_16x16x32_bf16 v[50:53], v[166:169], v[174:177], v[50:53]
	v_mfma_f32_16x16x32_bf16 v[34:37], v[166:169], v[182:185], v[34:37]
	v_mfma_f32_16x16x32_bf16 v[38:41], v[158:161], v[182:185], v[38:41]
	v_mfma_f32_16x16x32_bf16 v[22:25], v[158:161], v[190:193], v[22:25]
	v_mfma_f32_16x16x32_bf16 v[18:21], v[166:169], v[190:193], v[18:21]
	v_mfma_f32_16x16x32_bf16 v[2:5], v[166:169], v[206:209], v[2:5]
	v_mfma_f32_16x16x32_bf16 v[6:9], v[158:161], v[206:209], v[6:9]
	s_barrier
; #define PG8_STAGE(bufoff, gbase, voff) do { const int so_ = (int)(unsigned)((const char*)(gbase) - base_##voff); _Pragma("unroll") for (int _i = 0; _i < 2; ++_i) \
;         __builtin_amdgcn_raw_ptr_buffer_load_lds(rs_##voff, (PG8_LAS unsigned*)(lds + (bufoff) + ldsw + _i * 8192), 16, (int)(voff)[_i], so_, 0, 0); } while (0)
; #define PG8_LDA(dst, b, h) do { _Pragma("unroll") for (int m = 0; m < 4; ++m) _Pragma("unroll") for (int k = 0; k < 2; ++k) dst[m][k] = *(const PG8_LAS bf16x8*)(lds + PG8_SA(b, h) + aoff + m * 2048 + k * 1024); } while (0)
; #define PG8_LDB(dst, b, h) do { _Pragma("unroll") for (int n = 0; n < 2; ++n) _Pragma("unroll") for (int k = 0; k < 2; ++k) dst[n][k] = *(const PG8_LAS bf16x8*)(lds + PG8_SB(b, h) + boff + n * 2048 + k * 1024); } while (0)
; #define PG8_MMA(ai, bj, At, Bt) do { __builtin_amdgcn_s_setprio(1); _Pragma("unroll") for (int m = 0; m < 4; ++m) _Pragma("unroll") for (int n = 0; n < 2; ++n) _Pragma("unroll") for (int k = 0; k < 2; ++k) \
;         acc[ai][bj][m][n] = __builtin_amdgcn_mfma_f32_16x16x32_bf16(Bt[n][k], At[m][k], acc[ai][bj][m][n], 0, 0, 0); __builtin_amdgcn_s_setprio(0); } while (0)
; #define PG8_WAIT_V(n) asm volatile("s_waitcnt vmcnt(" #n ")" ::: "memory")
; #define PG8_WAIT_L(n) asm volatile("s_waitcnt lgkmcnt(" #n ")" ::: "memory")
; #define PG8_BAR __builtin_amdgcn_s_barrier()
; #define PG8_SCHED __builtin_amdgcn_sched_barrier(0)
; template <class Epi, class Sched, bool ALIGN_EPI = false, bool SP2 = false>
; __device__ __forceinline__ void gemm_phase(PG8_LAS unsigned char* lds, const Gemm g, const Sched& S, const Epi& E, int tid_in) {
;     ...
;             PG8_LDB(B0, 1, 0); PG8_LDB(B1, 1, 1); PG8_SCHED; PG8_LDA(At, 1, 0); PG8_STAGE(PG8_SA(0, 1), a2 + hstepA, voffA);
;             PG8_WAIT_V(8); PG8_WAIT_L(0); PG8_BAR; PG8_MMA(0, 0, At, B0); PG8_MMA(0, 1, At, B1); PG8_BAR; PG8_SCHED;
;             PG8_LDA(At, 1, 1); PG8_STAGE(PG8_SB(1, 0), b3, voffB); PG8_STAGE(PG8_SB(1, 1), b3 + hstepB, voffB); PG8_STAGE(PG8_SA(1, 0), a3, voffA);
;             PG8_WAIT_V(8); PG8_WAIT_L(0); PG8_BAR; PG8_MMA(1, 0, At, B0); PG8_MMA(1, 1, At, B1); PG8_BAR; PG8_SCHED;
	s_setprio 0
	ds_read_b128 v[130:133], v251 offset:32768
	ds_read_b128 v[142:145], v251 offset:33792
	ds_read_b128 v[146:149], v251 offset:34816
	ds_read_b128 v[150:153], v251 offset:35840
	ds_read_b128 v[154:157], v251 offset:49152
	ds_read_b128 v[158:161], v251 offset:50176
	ds_read_b128 v[162:165], v251 offset:51200
	ds_read_b128 v[166:169], v251 offset:52224
	s_add_i32 s74, s17, 0x80000
	s_mov_b32 m0, s48
	ds_read_b128 v[170:173], v140 offset:32768
	ds_read_b128 v[174:177], v140 offset:33792
	ds_read_b128 v[178:181], v140 offset:34816
	ds_read_b128 v[182:185], v140 offset:35840
	ds_read_b128 v[186:189], v140 offset:36864
	ds_read_b128 v[190:193], v140 offset:37888
	ds_read_b128 v[200:203], v140 offset:38912
	ds_read_b128 v[206:209], v140 offset:39936
	s_mov_b32 m0, s47
	s_nop 0
	buffer_load_dwordx4 v135, s[4:7], s17 offen lds
	s_mov_b32 m0, s48
	s_nop 0
	buffer_load_dwordx4 v0, s[4:7], s74 offen lds
	s_mov_b32 m0, s49
	s_nop 0
	buffer_load_dwordx4 v135, s[4:7], s74 offen lds
	s_waitcnt vmcnt(8)
	s_waitcnt lgkmcnt(0)
	s_setprio 1
	s_barrier
	v_mfma_f32_16x16x32_bf16 v[126:129], v[130:133], v[170:173], v[126:129]
	v_mfma_f32_16x16x32_bf16 v[122:125], v[146:149], v[170:173], v[122:125]
	v_mfma_f32_16x16x32_bf16 v[106:109], v[146:149], v[178:181], v[106:109]
	v_mfma_f32_16x16x32_bf16 v[110:113], v[130:133], v[178:181], v[110:113]
	v_mfma_f32_16x16x32_bf16 v[94:97], v[130:133], v[186:189], v[94:97]
	v_mfma_f32_16x16x32_bf16 v[90:93], v[146:149], v[186:189], v[90:93]
	v_mfma_f32_16x16x32_bf16 v[74:77], v[146:149], v[200:203], v[74:77]
	v_mfma_f32_16x16x32_bf16 v[78:81], v[130:133], v[200:203], v[78:81]
	v_mfma_f32_16x16x32_bf16 v[126:129], v[142:145], v[174:177], v[126:129]
	v_mfma_f32_16x16x32_bf16 v[122:125], v[150:153], v[174:177], v[122:125]
	v_mfma_f32_16x16x32_bf16 v[106:109], v[150:153], v[182:185], v[106:109]
	v_mfma_f32_16x16x32_bf16 v[110:113], v[142:145], v[182:185], v[110:113]
	v_mfma_f32_16x16x32_bf16 v[94:97], v[142:145], v[190:193], v[94:97]
	v_mfma_f32_16x16x32_bf16 v[90:93], v[150:153], v[190:193], v[90:93]
	v_mfma_f32_16x16x32_bf16 v[74:77], v[150:153], v[206:209], v[74:77]
	v_mfma_f32_16x16x32_bf16 v[78:81], v[142:145], v[206:209], v[78:81]
	v_mfma_f32_16x16x32_bf16 v[118:121], v[154:157], v[170:173], v[118:121]
	v_mfma_f32_16x16x32_bf16 v[114:117], v[162:165], v[170:173], v[114:117]
	v_mfma_f32_16x16x32_bf16 v[98:101], v[162:165], v[178:181], v[98:101]
	v_mfma_f32_16x16x32_bf16 v[102:105], v[154:157], v[178:181], v[102:105]
	v_mfma_f32_16x16x32_bf16 v[86:89], v[154:157], v[186:189], v[86:89]
	v_mfma_f32_16x16x32_bf16 v[82:85], v[162:165], v[186:189], v[82:85]
	v_mfma_f32_16x16x32_bf16 v[66:69], v[162:165], v[200:203], v[66:69]
	v_mfma_f32_16x16x32_bf16 v[70:73], v[154:157], v[200:203], v[70:73]
	v_mfma_f32_16x16x32_bf16 v[118:121], v[158:161], v[174:177], v[118:121]
	v_mfma_f32_16x16x32_bf16 v[114:117], v[166:169], v[174:177], v[114:117]
	v_mfma_f32_16x16x32_bf16 v[98:101], v[166:169], v[182:185], v[98:101]
	v_mfma_f32_16x16x32_bf16 v[102:105], v[158:161], v[182:185], v[102:105]
	v_mfma_f32_16x16x32_bf16 v[86:89], v[158:161], v[190:193], v[86:89]
	v_mfma_f32_16x16x32_bf16 v[82:85], v[166:169], v[190:193], v[82:85]
	v_mfma_f32_16x16x32_bf16 v[66:69], v[166:169], v[206:209], v[66:69]
	v_mfma_f32_16x16x32_bf16 v[70:73], v[158:161], v[206:209], v[70:73]
	s_barrier
	s_setprio 0
	s_mov_b32 m0, s53
	s_add_i32 s74, s16, 0x80
	ds_read_b128 v[170:173], v140 offset:49152
	ds_read_b128 v[174:177], v140 offset:50176
	ds_read_b128 v[178:181], v140 offset:51200
	ds_read_b128 v[182:185], v140 offset:52224
	ds_read_b128 v[186:189], v140 offset:53248
	ds_read_b128 v[190:193], v140 offset:54272
	ds_read_b128 v[200:203], v140 offset:55296
	ds_read_b128 v[206:209], v140 offset:56320
	buffer_load_dwordx4 v134, s[40:43], s74 offen lds
	s_mov_b32 m0, s60
	s_add_i32 s16, s16, 0x80080
	buffer_load_dwordx4 v136, s[40:43], s74 offen lds
	s_mov_b32 m0, s63
	s_addk_i32 s17, 0x80
	buffer_load_dwordx4 v134, s[40:43], s16 offen lds
	s_mov_b32 m0, s66
	s_nop 0
	buffer_load_dwordx4 v136, s[40:43], s16 offen lds
	s_mov_b32 m0, s61
	s_nop 0
	buffer_load_dwordx4 v0, s[4:7], s17 offen lds
	s_waitcnt vmcnt(7)
	s_waitcnt lgkmcnt(0)
	s_setprio 1
	s_barrier
	v_mfma_f32_16x16x32_bf16 v[62:65], v[130:133], v[170:173], v[62:65]
	v_mfma_f32_16x16x32_bf16 v[58:61], v[146:149], v[170:173], v[58:61]
	v_mfma_f32_16x16x32_bf16 v[42:45], v[146:149], v[178:181], v[42:45]
	v_mfma_f32_16x16x32_bf16 v[46:49], v[130:133], v[178:181], v[46:49]
	v_mfma_f32_16x16x32_bf16 v[30:33], v[130:133], v[186:189], v[30:33]
	v_mfma_f32_16x16x32_bf16 v[26:29], v[146:149], v[186:189], v[26:29]
	v_mfma_f32_16x16x32_bf16 v[10:13], v[146:149], v[200:203], v[10:13]
	v_mfma_f32_16x16x32_bf16 v[14:17], v[130:133], v[200:203], v[14:17]
	v_mfma_f32_16x16x32_bf16 v[62:65], v[142:145], v[174:177], v[62:65]
	v_mfma_f32_16x16x32_bf16 v[58:61], v[150:153], v[174:177], v[58:61]
	v_mfma_f32_16x16x32_bf16 v[42:45], v[150:153], v[182:185], v[42:45]
	v_mfma_f32_16x16x32_bf16 v[46:49], v[142:145], v[182:185], v[46:49]
	v_mfma_f32_16x16x32_bf16 v[30:33], v[142:145], v[190:193], v[30:33]
	v_mfma_f32_16x16x32_bf16 v[26:29], v[150:153], v[190:193], v[26:29]
	v_mfma_f32_16x16x32_bf16 v[10:13], v[150:153], v[206:209], v[10:13]
	v_mfma_f32_16x16x32_bf16 v[14:17], v[142:145], v[206:209], v[14:17]
	v_mfma_f32_16x16x32_bf16 v[54:57], v[154:157], v[170:173], v[54:57]
	v_mfma_f32_16x16x32_bf16 v[50:53], v[162:165], v[170:173], v[50:53]
	v_mfma_f32_16x16x32_bf16 v[34:37], v[162:165], v[178:181], v[34:37]
	v_mfma_f32_16x16x32_bf16 v[38:41], v[154:157], v[178:181], v[38:41]
	v_mfma_f32_16x16x32_bf16 v[22:25], v[154:157], v[186:189], v[22:25]
	v_mfma_f32_16x16x32_bf16 v[18:21], v[162:165], v[186:189], v[18:21]
	v_mfma_f32_16x16x32_bf16 v[2:5], v[162:165], v[200:203], v[2:5]
	v_mfma_f32_16x16x32_bf16 v[6:9], v[154:157], v[200:203], v[6:9]
	v_mfma_f32_16x16x32_bf16 v[54:57], v[158:161], v[174:177], v[54:57]
	v_mfma_f32_16x16x32_bf16 v[50:53], v[166:169], v[174:177], v[50:53]
	v_mfma_f32_16x16x32_bf16 v[34:37], v[166:169], v[182:185], v[34:37]
	v_mfma_f32_16x16x32_bf16 v[38:41], v[158:161], v[182:185], v[38:41]
	v_mfma_f32_16x16x32_bf16 v[22:25], v[158:161], v[190:193], v[22:25]
	v_mfma_f32_16x16x32_bf16 v[18:21], v[166:169], v[190:193], v[18:21]
	v_mfma_f32_16x16x32_bf16 v[2:5], v[166:169], v[206:209], v[2:5]
	v_mfma_f32_16x16x32_bf16 v[6:9], v[158:161], v[206:209], v[6:9]
	s_barrier
	s_setprio 0
	s_add_i32 s73, s73, 2
	s_add_u32 s19, s19, 0x100
	s_addc_u32 s21, s21, 0
	s_cmp_gt_u32 s73, 29
	s_mov_b64 s[16:17], s[38:39]
; #define PG8_STAGE(bufoff, gbase, voff) do { const int so_ = (int)(unsigned)((const char*)(gbase) - base_##voff); _Pragma("unroll") for (int _i = 0; _i < 2; ++_i) \
;         __builtin_amdgcn_raw_ptr_buffer_load_lds(rs_##voff, (PG8_LAS unsigned*)(lds + (bufoff) + ldsw + _i * 8192), 16, (int)(voff)[_i], so_, 0, 0); } while (0)
; #define PG8_LDA(dst, b, h) do { _Pragma("unroll") for (int m = 0; m < 4; ++m) _Pragma("unroll") for (int k = 0; k < 2; ++k) dst[m][k] = *(const PG8_LAS bf16x8*)(lds + PG8_SA(b, h) + aoff + m * 2048 + k * 1024); } while (0)
; #define PG8_LDB(dst, b, h) do { _Pragma("unroll") for (int n = 0; n < 2; ++n) _Pragma("unroll") for (int k = 0; k < 2; ++k) dst[n][k] = *(const PG8_LAS bf16x8*)(lds + PG8_SB(b, h) + boff + n * 2048 + k * 1024); } while (0)
; #define PG8_MMA(ai, bj, At, Bt) do { __builtin_amdgcn_s_setprio(1); _Pragma("unroll") for (int m = 0; m < 4; ++m) _Pragma("unroll") for (int n = 0; n < 2; ++n) _Pragma("unroll") for (int k = 0; k < 2; ++k) \
;         acc[ai][bj][m][n] = __builtin_amdgcn_mfma_f32_16x16x32_bf16(Bt[n][k], At[m][k], acc[ai][bj][m][n], 0, 0, 0); __builtin_amdgcn_s_setprio(0); } while (0)
; #define PG8_WAIT_V(n) asm volatile("s_waitcnt vmcnt(" #n ")" ::: "memory")
; #define PG8_WAIT_L(n) asm volatile("s_waitcnt lgkmcnt(" #n ")" ::: "memory")
; #define PG8_BAR __builtin_amdgcn_s_barrier()
; #define PG8_SCHED __builtin_amdgcn_sched_barrier(0)
; template <class Epi, class Sched, bool ALIGN_EPI = false, bool SP2 = false>
; __device__ __forceinline__ void gemm_phase(PG8_LAS unsigned char* lds, const Gemm g, const Sched& S, const Epi& E, int tid_in) {
;     ...
;             PG8_LDB(B0, 0, 0); PG8_LDB(B1, 0, 1); PG8_SCHED; PG8_LDA(At, 0, 0); PG8_STAGE(PG8_SA(1, 1), a1 + hstepA, voffA);
;             PG8_WAIT_V(8); PG8_WAIT_L(0); PG8_BAR; PG8_MMA(0, 0, At, B0); PG8_MMA(0, 1, At, B1); PG8_BAR; PG8_SCHED;
;             PG8_LDA(At, 0, 1); PG8_STAGE(PG8_SB(0, 0), b2, voffB); PG8_STAGE(PG8_SB(0, 1), b2 + hstepB, voffB); PG8_STAGE(PG8_SA(0, 0), a2, voffA);
;             PG8_WAIT_V(8); PG8_WAIT_L(0); PG8_BAR; PG8_MMA(1, 0, At, B0); PG8_MMA(1, 1, At, B1); PG8_BAR; PG8_SCHED;
.LBB0_1514:
	ds_read_b128 v[130:133], v251
	ds_read_b128 v[142:145], v251 offset:1024
	ds_read_b128 v[146:149], v251 offset:2048
	ds_read_b128 v[150:153], v251 offset:3072
	ds_read_b128 v[154:157], v251 offset:16384
	ds_read_b128 v[158:161], v251 offset:17408
	ds_read_b128 v[162:165], v251 offset:18432
	ds_read_b128 v[166:169], v251 offset:19456
	s_add_u32 s38, s16, 0x100
	s_addc_u32 s39, s17, 0
	s_sub_i32 s16, s16, s4
	s_add_i32 s16, s16, 0x80080
	s_sub_i32 s74, s16, 0x80000
	s_cmp_eq_u32 s73, 28
	s_cselect_b32 s17, s18, s38
	s_mov_b32 m0, s67
	ds_read_b128 v[170:173], v140
	ds_read_b128 v[174:177], v140 offset:1024
	ds_read_b128 v[178:181], v140 offset:2048
	ds_read_b128 v[182:185], v140 offset:3072
	ds_read_b128 v[186:189], v140 offset:4096
	ds_read_b128 v[190:193], v140 offset:5120
	ds_read_b128 v[200:203], v140 offset:6144
	ds_read_b128 v[206:209], v140 offset:7168
	s_mov_b32 m0, s62
	s_nop 0
	buffer_load_dwordx4 v135, s[4:7], s74 offen lds
	s_mov_b32 m0, s67
	s_nop 0
	buffer_load_dwordx4 v0, s[4:7], s16 offen lds
	s_mov_b32 m0, s68
	s_nop 0
	buffer_load_dwordx4 v135, s[4:7], s16 offen lds
	s_waitcnt vmcnt(8)
	s_waitcnt lgkmcnt(0)
	s_setprio 1
	s_barrier
	v_mfma_f32_16x16x32_bf16 v[126:129], v[130:133], v[170:173], v[126:129]
	v_mfma_f32_16x16x32_bf16 v[122:125], v[146:149], v[170:173], v[122:125]
	v_mfma_f32_16x16x32_bf16 v[106:109], v[146:149], v[178:181], v[106:109]
	v_mfma_f32_16x16x32_bf16 v[110:113], v[130:133], v[178:181], v[110:113]
	v_mfma_f32_16x16x32_bf16 v[94:97], v[130:133], v[186:189], v[94:97]
	v_mfma_f32_16x16x32_bf16 v[90:93], v[146:149], v[186:189], v[90:93]
	v_mfma_f32_16x16x32_bf16 v[74:77], v[146:149], v[200:203], v[74:77]
	v_mfma_f32_16x16x32_bf16 v[78:81], v[130:133], v[200:203], v[78:81]
	v_mfma_f32_16x16x32_bf16 v[126:129], v[142:145], v[174:177], v[126:129]
	v_mfma_f32_16x16x32_bf16 v[122:125], v[150:153], v[174:177], v[122:125]
	v_mfma_f32_16x16x32_bf16 v[106:109], v[150:153], v[182:185], v[106:109]
	v_mfma_f32_16x16x32_bf16 v[110:113], v[142:145], v[182:185], v[110:113]
	v_mfma_f32_16x16x32_bf16 v[94:97], v[142:145], v[190:193], v[94:97]
	v_mfma_f32_16x16x32_bf16 v[90:93], v[150:153], v[190:193], v[90:93]
	v_mfma_f32_16x16x32_bf16 v[74:77], v[150:153], v[206:209], v[74:77]
	v_mfma_f32_16x16x32_bf16 v[78:81], v[142:145], v[206:209], v[78:81]
	v_mfma_f32_16x16x32_bf16 v[118:121], v[154:157], v[170:173], v[118:121]
	v_mfma_f32_16x16x32_bf16 v[114:117], v[162:165], v[170:173], v[114:117]
	v_mfma_f32_16x16x32_bf16 v[98:101], v[162:165], v[178:181], v[98:101]
	v_mfma_f32_16x16x32_bf16 v[102:105], v[154:157], v[178:181], v[102:105]
	v_mfma_f32_16x16x32_bf16 v[86:89], v[154:157], v[186:189], v[86:89]
	v_mfma_f32_16x16x32_bf16 v[82:85], v[162:165], v[186:189], v[82:85]
	v_mfma_f32_16x16x32_bf16 v[66:69], v[162:165], v[200:203], v[66:69]
	v_mfma_f32_16x16x32_bf16 v[70:73], v[154:157], v[200:203], v[70:73]
	v_mfma_f32_16x16x32_bf16 v[118:121], v[158:161], v[174:177], v[118:121]
	v_mfma_f32_16x16x32_bf16 v[114:117], v[166:169], v[174:177], v[114:117]
	v_mfma_f32_16x16x32_bf16 v[98:101], v[166:169], v[182:185], v[98:101]
	v_mfma_f32_16x16x32_bf16 v[102:105], v[158:161], v[182:185], v[102:105]
	v_mfma_f32_16x16x32_bf16 v[86:89], v[158:161], v[190:193], v[86:89]
	v_mfma_f32_16x16x32_bf16 v[82:85], v[166:169], v[190:193], v[82:85]
	v_mfma_f32_16x16x32_bf16 v[66:69], v[166:169], v[206:209], v[66:69]
	v_mfma_f32_16x16x32_bf16 v[70:73], v[158:161], v[206:209], v[70:73]
	s_barrier
	s_setprio 0
	s_cselect_b32 s16, s15, s19
	s_mov_b32 m0, s35
	s_mov_b32 s42, s6
	s_mov_b32 s43, s7
	s_sub_i32 s16, s16, s40
	ds_read_b128 v[170:173], v140 offset:16384
	ds_read_b128 v[174:177], v140 offset:17408
	ds_read_b128 v[178:181], v140 offset:18432
	ds_read_b128 v[182:185], v140 offset:19456
	ds_read_b128 v[186:189], v140 offset:20480
	ds_read_b128 v[190:193], v140 offset:21504
	ds_read_b128 v[200:203], v140 offset:22528
	ds_read_b128 v[206:209], v140 offset:23552
	buffer_load_dwordx4 v134, s[40:43], s16 offen lds
	s_mov_b32 m0, s44
	s_add_i32 s74, s16, 0x80000
	buffer_load_dwordx4 v136, s[40:43], s16 offen lds
	s_mov_b32 m0, s45
	s_sub_i32 s17, s17, s4
	buffer_load_dwordx4 v134, s[40:43], s74 offen lds
	s_mov_b32 m0, s46
	s_nop 0
	buffer_load_dwordx4 v136, s[40:43], s74 offen lds
	s_mov_b32 m0, s34
	s_nop 0
	buffer_load_dwordx4 v0, s[4:7], s17 offen lds
	s_waitcnt vmcnt(7)
	s_waitcnt lgkmcnt(0)
	s_setprio 1
	s_barrier
	v_mfma_f32_16x16x32_bf16 v[62:65], v[130:133], v[170:173], v[62:65]
	v_mfma_f32_16x16x32_bf16 v[58:61], v[146:149], v[170:173], v[58:61]
	v_mfma_f32_16x16x32_bf16 v[42:45], v[146:149], v[178:181], v[42:45]
	v_mfma_f32_16x16x32_bf16 v[46:49], v[130:133], v[178:181], v[46:49]
	v_mfma_f32_16x16x32_bf16 v[30:33], v[130:133], v[186:189], v[30:33]
	v_mfma_f32_16x16x32_bf16 v[26:29], v[146:149], v[186:189], v[26:29]
	v_mfma_f32_16x16x32_bf16 v[10:13], v[146:149], v[200:203], v[10:13]
	v_mfma_f32_16x16x32_bf16 v[14:17], v[130:133], v[200:203], v[14:17]
	v_mfma_f32_16x16x32_bf16 v[62:65], v[142:145], v[174:177], v[62:65]
	v_mfma_f32_16x16x32_bf16 v[58:61], v[150:153], v[174:177], v[58:61]
	v_mfma_f32_16x16x32_bf16 v[42:45], v[150:153], v[182:185], v[42:45]
	v_mfma_f32_16x16x32_bf16 v[46:49], v[142:145], v[182:185], v[46:49]
	v_mfma_f32_16x16x32_bf16 v[30:33], v[142:145], v[190:193], v[30:33]
	v_mfma_f32_16x16x32_bf16 v[26:29], v[150:153], v[190:193], v[26:29]
	v_mfma_f32_16x16x32_bf16 v[10:13], v[150:153], v[206:209], v[10:13]
	v_mfma_f32_16x16x32_bf16 v[14:17], v[142:145], v[206:209], v[14:17]
	v_mfma_f32_16x16x32_bf16 v[54:57], v[154:157], v[170:173], v[54:57]
	v_mfma_f32_16x16x32_bf16 v[50:53], v[162:165], v[170:173], v[50:53]
	v_mfma_f32_16x16x32_bf16 v[34:37], v[162:165], v[178:181], v[34:37]
	v_mfma_f32_16x16x32_bf16 v[38:41], v[154:157], v[178:181], v[38:41]
	v_mfma_f32_16x16x32_bf16 v[22:25], v[154:157], v[186:189], v[22:25]
	v_mfma_f32_16x16x32_bf16 v[18:21], v[162:165], v[186:189], v[18:21]
	v_mfma_f32_16x16x32_bf16 v[2:5], v[162:165], v[200:203], v[2:5]
	v_mfma_f32_16x16x32_bf16 v[6:9], v[154:157], v[200:203], v[6:9]
	v_mfma_f32_16x16x32_bf16 v[54:57], v[158:161], v[174:177], v[54:57]
	v_mfma_f32_16x16x32_bf16 v[50:53], v[166:169], v[174:177], v[50:53]
	v_mfma_f32_16x16x32_bf16 v[34:37], v[166:169], v[182:185], v[34:37]
	v_mfma_f32_16x16x32_bf16 v[38:41], v[158:161], v[182:185], v[38:41]
	v_mfma_f32_16x16x32_bf16 v[22:25], v[158:161], v[190:193], v[22:25]
	v_mfma_f32_16x16x32_bf16 v[18:21], v[166:169], v[190:193], v[18:21]
	v_mfma_f32_16x16x32_bf16 v[2:5], v[166:169], v[206:209], v[2:5]
	v_mfma_f32_16x16x32_bf16 v[6:9], v[158:161], v[206:209], v[6:9]
	s_barrier
; #define PG8_STAGE(bufoff, gbase, voff) do { const int so_ = (int)(unsigned)((const char*)(gbase) - base_##voff); _Pragma("unroll") for (int _i = 0; _i < 2; ++_i) \
;         __builtin_amdgcn_raw_ptr_buffer_load_lds(rs_##voff, (PG8_LAS unsigned*)(lds + (bufoff) + ldsw + _i * 8192), 16, (int)(voff)[_i], so_, 0, 0); } while (0)
; #define PG8_LDA(dst, b, h) do { _Pragma("unroll") for (int m = 0; m < 4; ++m) _Pragma("unroll") for (int k = 0; k < 2; ++k) dst[m][k] = *(const PG8_LAS bf16x8*)(lds + PG8_SA(b, h) + aoff + m * 2048 + k * 1024); } while (0)
; #define PG8_LDB(dst, b, h) do { _Pragma("unroll") for (int n = 0; n < 2; ++n) _Pragma("unroll") for (int k = 0; k < 2; ++k) dst[n][k] = *(const PG8_LAS bf16x8*)(lds + PG8_SB(b, h) + boff + n * 2048 + k * 1024); } while (0)
; #define PG8_MMA(ai, bj, At, Bt) do { __builtin_amdgcn_s_setprio(1); _Pragma("unroll") for (int m = 0; m < 4; ++m) _Pragma("unroll") for (int n = 0; n < 2; ++n) _Pragma("unroll") for (int k = 0; k < 2; ++k) \
;         acc[ai][bj][m][n] = __builtin_amdgcn_mfma_f32_16x16x32_bf16(Bt[n][k], At[m][k], acc[ai][bj][m][n], 0, 0, 0); __builtin_amdgcn_s_setprio(0); } while (0)
; #define PG8_WAIT_V(n) asm volatile("s_waitcnt vmcnt(" #n ")" ::: "memory")
; #define PG8_WAIT_L(n) asm volatile("s_waitcnt lgkmcnt(" #n ")" ::: "memory")
; #define PG8_BAR __builtin_amdgcn_s_barrier()
; #define PG8_SCHED __builtin_amdgcn_sched_barrier(0)
; template <class Epi, class Sched, bool ALIGN_EPI = false, bool SP2 = false>
; __device__ __forceinline__ void gemm_phase(PG8_LAS unsigned char* lds, const Gemm g, const Sched& S, const Epi& E, int tid_in) {
;     ...
;             PG8_LDB(B0, 1, 0); PG8_LDB(B1, 1, 1); PG8_SCHED; PG8_LDA(At, 1, 0); PG8_STAGE(PG8_SA(0, 1), a2 + hstepA, voffA);
;             PG8_WAIT_V(8); PG8_WAIT_L(0); PG8_BAR; PG8_MMA(0, 0, At, B0); PG8_MMA(0, 1, At, B1); PG8_BAR; PG8_SCHED;
;             PG8_LDA(At, 1, 1); PG8_STAGE(PG8_SB(1, 0), b3, voffB); PG8_STAGE(PG8_SB(1, 1), b3 + hstepB, voffB); PG8_STAGE(PG8_SA(1, 0), a3, voffA);
;             PG8_WAIT_V(8); PG8_WAIT_L(0); PG8_BAR; PG8_MMA(1, 0, At, B0); PG8_MMA(1, 1, At, B1); PG8_BAR; PG8_SCHED;
	s_setprio 0
	ds_read_b128 v[130:133], v251 offset:32768
	ds_read_b128 v[142:145], v251 offset:33792
	ds_read_b128 v[146:149], v251 offset:34816
	ds_read_b128 v[150:153], v251 offset:35840
	ds_read_b128 v[154:157], v251 offset:49152
	ds_read_b128 v[158:161], v251 offset:50176
	ds_read_b128 v[162:165], v251 offset:51200
	ds_read_b128 v[166:169], v251 offset:52224
	s_add_i32 s74, s17, 0x80000
	s_mov_b32 m0, s48
	ds_read_b128 v[170:173], v140 offset:32768
	ds_read_b128 v[174:177], v140 offset:33792
	ds_read_b128 v[178:181], v140 offset:34816
	ds_read_b128 v[182:185], v140 offset:35840
	ds_read_b128 v[186:189], v140 offset:36864
	ds_read_b128 v[190:193], v140 offset:37888
	ds_read_b128 v[200:203], v140 offset:38912
	ds_read_b128 v[206:209], v140 offset:39936
	s_mov_b32 m0, s47
	s_nop 0
	buffer_load_dwordx4 v135, s[4:7], s17 offen lds
	s_mov_b32 m0, s48
	s_nop 0
	buffer_load_dwordx4 v0, s[4:7], s74 offen lds
	s_mov_b32 m0, s49
	s_nop 0
	buffer_load_dwordx4 v135, s[4:7], s74 offen lds
	s_waitcnt vmcnt(8)
	s_waitcnt lgkmcnt(0)
	s_setprio 1
	s_barrier
	v_mfma_f32_16x16x32_bf16 v[126:129], v[130:133], v[170:173], v[126:129]
	v_mfma_f32_16x16x32_bf16 v[122:125], v[146:149], v[170:173], v[122:125]
	v_mfma_f32_16x16x32_bf16 v[106:109], v[146:149], v[178:181], v[106:109]
	v_mfma_f32_16x16x32_bf16 v[110:113], v[130:133], v[178:181], v[110:113]
	v_mfma_f32_16x16x32_bf16 v[94:97], v[130:133], v[186:189], v[94:97]
	v_mfma_f32_16x16x32_bf16 v[90:93], v[146:149], v[186:189], v[90:93]
	v_mfma_f32_16x16x32_bf16 v[74:77], v[146:149], v[200:203], v[74:77]
	v_mfma_f32_16x16x32_bf16 v[78:81], v[130:133], v[200:203], v[78:81]
	v_mfma_f32_16x16x32_bf16 v[126:129], v[142:145], v[174:177], v[126:129]
	v_mfma_f32_16x16x32_bf16 v[122:125], v[150:153], v[174:177], v[122:125]
	v_mfma_f32_16x16x32_bf16 v[106:109], v[150:153], v[182:185], v[106:109]
	v_mfma_f32_16x16x32_bf16 v[110:113], v[142:145], v[182:185], v[110:113]
	v_mfma_f32_16x16x32_bf16 v[94:97], v[142:145], v[190:193], v[94:97]
	v_mfma_f32_16x16x32_bf16 v[90:93], v[150:153], v[190:193], v[90:93]
	v_mfma_f32_16x16x32_bf16 v[74:77], v[150:153], v[206:209], v[74:77]
	v_mfma_f32_16x16x32_bf16 v[78:81], v[142:145], v[206:209], v[78:81]
	v_mfma_f32_16x16x32_bf16 v[118:121], v[154:157], v[170:173], v[118:121]
	v_mfma_f32_16x16x32_bf16 v[114:117], v[162:165], v[170:173], v[114:117]
	v_mfma_f32_16x16x32_bf16 v[98:101], v[162:165], v[178:181], v[98:101]
	v_mfma_f32_16x16x32_bf16 v[102:105], v[154:157], v[178:181], v[102:105]
	v_mfma_f32_16x16x32_bf16 v[86:89], v[154:157], v[186:189], v[86:89]
	v_mfma_f32_16x16x32_bf16 v[82:85], v[162:165], v[186:189], v[82:85]
	v_mfma_f32_16x16x32_bf16 v[66:69], v[162:165], v[200:203], v[66:69]
	v_mfma_f32_16x16x32_bf16 v[70:73], v[154:157], v[200:203], v[70:73]
	v_mfma_f32_16x16x32_bf16 v[118:121], v[158:161], v[174:177], v[118:121]
	v_mfma_f32_16x16x32_bf16 v[114:117], v[166:169], v[174:177], v[114:117]
	v_mfma_f32_16x16x32_bf16 v[98:101], v[166:169], v[182:185], v[98:101]
	v_mfma_f32_16x16x32_bf16 v[102:105], v[158:161], v[182:185], v[102:105]
	v_mfma_f32_16x16x32_bf16 v[86:89], v[158:161], v[190:193], v[86:89]
	v_mfma_f32_16x16x32_bf16 v[82:85], v[166:169], v[190:193], v[82:85]
	v_mfma_f32_16x16x32_bf16 v[66:69], v[166:169], v[206:209], v[66:69]
	v_mfma_f32_16x16x32_bf16 v[70:73], v[158:161], v[206:209], v[70:73]
	s_barrier
	s_setprio 0
	s_mov_b32 m0, s53
	s_add_i32 s74, s16, 0x80
	ds_read_b128 v[170:173], v140 offset:49152
	ds_read_b128 v[174:177], v140 offset:50176
	ds_read_b128 v[178:181], v140 offset:51200
	ds_read_b128 v[182:185], v140 offset:52224
	ds_read_b128 v[186:189], v140 offset:53248
	ds_read_b128 v[190:193], v140 offset:54272
	ds_read_b128 v[200:203], v140 offset:55296
	ds_read_b128 v[206:209], v140 offset:56320
	buffer_load_dwordx4 v134, s[40:43], s74 offen lds
	s_mov_b32 m0, s60
	s_add_i32 s16, s16, 0x80080
	buffer_load_dwordx4 v136, s[40:43], s74 offen lds
	s_mov_b32 m0, s63
	s_addk_i32 s17, 0x80
	buffer_load_dwordx4 v134, s[40:43], s16 offen lds
	s_mov_b32 m0, s66
	s_nop 0
	buffer_load_dwordx4 v136, s[40:43], s16 offen lds
	s_mov_b32 m0, s61
	s_nop 0
	buffer_load_dwordx4 v0, s[4:7], s17 offen lds
	s_waitcnt vmcnt(7)
	s_waitcnt lgkmcnt(0)
	s_setprio 1
	s_barrier
	v_mfma_f32_16x16x32_bf16 v[62:65], v[130:133], v[170:173], v[62:65]
	v_mfma_f32_16x16x32_bf16 v[58:61], v[146:149], v[170:173], v[58:61]
	v_mfma_f32_16x16x32_bf16 v[42:45], v[146:149], v[178:181], v[42:45]
	v_mfma_f32_16x16x32_bf16 v[46:49], v[130:133], v[178:181], v[46:49]
	v_mfma_f32_16x16x32_bf16 v[30:33], v[130:133], v[186:189], v[30:33]
	v_mfma_f32_16x16x32_bf16 v[26:29], v[146:149], v[186:189], v[26:29]
	v_mfma_f32_16x16x32_bf16 v[10:13], v[146:149], v[200:203], v[10:13]
	v_mfma_f32_16x16x32_bf16 v[14:17], v[130:133], v[200:203], v[14:17]
	v_mfma_f32_16x16x32_bf16 v[62:65], v[142:145], v[174:177], v[62:65]
	v_mfma_f32_16x16x32_bf16 v[58:61], v[150:153], v[174:177], v[58:61]
	v_mfma_f32_16x16x32_bf16 v[42:45], v[150:153], v[182:185], v[42:45]
	v_mfma_f32_16x16x32_bf16 v[46:49], v[142:145], v[182:185], v[46:49]
	v_mfma_f32_16x16x32_bf16 v[30:33], v[142:145], v[190:193], v[30:33]
	v_mfma_f32_16x16x32_bf16 v[26:29], v[150:153], v[190:193], v[26:29]
	v_mfma_f32_16x16x32_bf16 v[10:13], v[150:153], v[206:209], v[10:13]
	v_mfma_f32_16x16x32_bf16 v[14:17], v[142:145], v[206:209], v[14:17]
	v_mfma_f32_16x16x32_bf16 v[54:57], v[154:157], v[170:173], v[54:57]
	v_mfma_f32_16x16x32_bf16 v[50:53], v[162:165], v[170:173], v[50:53]
	v_mfma_f32_16x16x32_bf16 v[34:37], v[162:165], v[178:181], v[34:37]
	v_mfma_f32_16x16x32_bf16 v[38:41], v[154:157], v[178:181], v[38:41]
	v_mfma_f32_16x16x32_bf16 v[22:25], v[154:157], v[186:189], v[22:25]
	v_mfma_f32_16x16x32_bf16 v[18:21], v[162:165], v[186:189], v[18:21]
	v_mfma_f32_16x16x32_bf16 v[2:5], v[162:165], v[200:203], v[2:5]
	v_mfma_f32_16x16x32_bf16 v[6:9], v[154:157], v[200:203], v[6:9]
	v_mfma_f32_16x16x32_bf16 v[54:57], v[158:161], v[174:177], v[54:57]
	v_mfma_f32_16x16x32_bf16 v[50:53], v[166:169], v[174:177], v[50:53]
	v_mfma_f32_16x16x32_bf16 v[34:37], v[166:169], v[182:185], v[34:37]
	v_mfma_f32_16x16x32_bf16 v[38:41], v[158:161], v[182:185], v[38:41]
	v_mfma_f32_16x16x32_bf16 v[22:25], v[158:161], v[190:193], v[22:25]
	v_mfma_f32_16x16x32_bf16 v[18:21], v[166:169], v[190:193], v[18:21]
	v_mfma_f32_16x16x32_bf16 v[2:5], v[166:169], v[206:209], v[2:5]
	v_mfma_f32_16x16x32_bf16 v[6:9], v[158:161], v[206:209], v[6:9]
	s_barrier
	s_setprio 0
	s_add_i32 s73, s73, 2
	s_add_u32 s19, s19, 0x100
	s_addc_u32 s21, s21, 0
	s_cmp_gt_u32 s73, 29
	s_mov_b64 s[16:17], s[38:39]
	s_cbranch_scc0 .LBB0_1514
	s_and_b64 vcc, exec, s[12:13]
	s_cbranch_vccz .LBB0_1517
	s_barrier

; #define PG8_STAGE(bufoff, gbase, voff) do { const int so_ = (int)(unsigned)((const char*)(gbase) - base_##voff); _Pragma("unroll") for (int _i = 0; _i < 2; ++_i) \
;         __builtin_amdgcn_raw_ptr_buffer_load_lds(rs_##voff, (PG8_LAS unsigned*)(lds + (bufoff) + ldsw + _i * 8192), 16, (int)(voff)[_i], so_, 0, 0); } while (0)
; #define PG8_LDA(dst, b, h) do { _Pragma("unroll") for (int m = 0; m < 4; ++m) _Pragma("unroll") for (int k = 0; k < 2; ++k) dst[m][k] = *(const PG8_LAS bf16x8*)(lds + PG8_SA(b, h) + aoff + m * 2048 + k * 1024); } while (0)
; #define PG8_LDB(dst, b, h) do { _Pragma("unroll") for (int n = 0; n < 2; ++n) _Pragma("unroll") for (int k = 0; k < 2; ++k) dst[n][k] = *(const PG8_LAS bf16x8*)(lds + PG8_SB(b, h) + boff + n * 2048 + k * 1024); } while (0)
; #define PG8_MMA(ai, bj, At, Bt) do { __builtin_amdgcn_s_setprio(1); _Pragma("unroll") for (int m = 0; m < 4; ++m) _Pragma("unroll") for (int n = 0; n < 2; ++n) _Pragma("unroll") for (int k = 0; k < 2; ++k) \
;         acc[ai][bj][m][n] = __builtin_amdgcn_mfma_f32_16x16x32_bf16(Bt[n][k], At[m][k], acc[ai][bj][m][n], 0, 0, 0); __builtin_amdgcn_s_setprio(0); } while (0)
; #define PG8_WAIT_V(n) asm volatile("s_waitcnt vmcnt(" #n ")" ::: "memory")
; #define PG8_WAIT_L(n) asm volatile("s_waitcnt lgkmcnt(" #n ")" ::: "memory")
; #define PG8_BAR __builtin_amdgcn_s_barrier()
; template <class Epi, class Sched, bool ALIGN_EPI = false, bool SP2 = false>
; __device__ __forceinline__ void gemm_phase(PG8_LAS unsigned char* lds, const Gemm g, const Sched& S, const Epi& E, int tid_in) {
;     ...
;             const char* a2 = last ? nA : cA + (size_t)(t + 2) * kstep; const char* b2 = last ? nB : cB + (size_t)(t + 2) * kstep;
;             const char* a3 = a2 + kstep; const char* b3 = b2 + kstep;
;             if (last && has_next) S.a_ready(nxt);
;             if constexpr (SP2) {
;             PG8_LDB(B0, 0, 0); PG8_LDB(B1, 0, 1); PG8_SCHED; PG8_LDA(At, 0, 0); PG8_STAGE(PG8_SA(1, 1), a1 + hstepA, voffA);
;             PG8_WAIT_V(8); PG8_WAIT_L(0); PG8_BAR; PG8_MMA(0, 0, At, B0); PG8_MMA(0, 1, At, B1); PG8_BAR; PG8_SCHED;
;             PG8_LDA(At, 0, 1); PG8_STAGE(PG8_SB(0, 0), b2, voffB); PG8_STAGE(PG8_SB(0, 1), b2 + hstepB, voffB); PG8_STAGE(PG8_SA(0, 0), a2, voffA);
;             PG8_WAIT_V(8); PG8_WAIT_L(0); PG8_BAR; PG8_MMA(1, 0, At, B0); PG8_MMA(1, 1, At, B1); PG8_BAR; PG8_SCHED;
.LBB0_1583:
	s_add_i32 s22, s14, s71
	s_add_i32 s38, s22, 0x160000
	s_mov_b32 s39, -2
	s_mov_b64 s[22:23], 0x100
	v_add_u32_e32 v251, 0x10000, v131
.LBB0_1584:
	ds_read_b128 v[134:137], v251
	ds_read_b128 v[138:141], v251 offset:1024
	ds_read_b128 v[142:145], v251 offset:2048
	ds_read_b128 v[146:149], v251 offset:3072
	ds_read_b128 v[150:153], v251 offset:16384
	ds_read_b128 v[154:157], v251 offset:17408
	ds_read_b128 v[158:161], v251 offset:18432
	ds_read_b128 v[166:169], v251 offset:19456
	s_add_i32 s43, s38, s22
	s_add_i32 s42, s14, s22
	s_add_i32 s76, s12, s22
	s_addk_i32 s43, 0xff80
	s_sub_i32 s78, s43, 0x160000
	s_cmpk_eq_i32 s39, 0x54
	s_cselect_b32 s77, s16, s42
	s_mov_b32 m0, s68
	ds_read_b128 v[170:173], v132
	ds_read_b128 v[174:177], v132 offset:1024
	ds_read_b128 v[178:181], v132 offset:2048
	ds_read_b128 v[182:185], v132 offset:3072
	ds_read_b128 v[186:189], v132 offset:4096
	ds_read_b128 v[190:193], v132 offset:5120
	ds_read_b128 v[200:203], v132 offset:6144
	ds_read_b128 v[206:209], v132 offset:7168
	s_mov_b32 m0, s63
	s_nop 0
	buffer_load_dwordx4 v130, s[4:7], s78 offen lds
	s_mov_b32 m0, s68
	s_nop 0
	buffer_load_dwordx4 v0, s[4:7], s43 offen lds
	s_mov_b32 m0, s69
	s_nop 0
	buffer_load_dwordx4 v130, s[4:7], s43 offen lds
	s_waitcnt vmcnt(8)
	s_waitcnt lgkmcnt(0)
	s_setprio 1
	s_barrier
	v_mfma_f32_16x16x32_bf16 v[22:25], v[134:137], v[170:173], v[22:25]
	v_mfma_f32_16x16x32_bf16 v[14:17], v[142:145], v[170:173], v[14:17]
	v_mfma_f32_16x16x32_bf16 v[54:57], v[142:145], v[178:181], v[54:57]
	v_mfma_f32_16x16x32_bf16 v[74:77], v[134:137], v[178:181], v[74:77]
	v_mfma_f32_16x16x32_bf16 v[106:109], v[134:137], v[186:189], v[106:109]
	v_mfma_f32_16x16x32_bf16 v[102:105], v[142:145], v[186:189], v[102:105]
	v_mfma_f32_16x16x32_bf16 v[118:121], v[142:145], v[200:203], v[118:121]
	v_mfma_f32_16x16x32_bf16 v[122:125], v[134:137], v[200:203], v[122:125]
	v_mfma_f32_16x16x32_bf16 v[22:25], v[138:141], v[174:177], v[22:25]
	v_mfma_f32_16x16x32_bf16 v[14:17], v[146:149], v[174:177], v[14:17]
	v_mfma_f32_16x16x32_bf16 v[54:57], v[146:149], v[182:185], v[54:57]
	v_mfma_f32_16x16x32_bf16 v[74:77], v[138:141], v[182:185], v[74:77]
	v_mfma_f32_16x16x32_bf16 v[106:109], v[138:141], v[190:193], v[106:109]
	v_mfma_f32_16x16x32_bf16 v[102:105], v[146:149], v[190:193], v[102:105]
	v_mfma_f32_16x16x32_bf16 v[118:121], v[146:149], v[206:209], v[118:121]
	v_mfma_f32_16x16x32_bf16 v[122:125], v[138:141], v[206:209], v[122:125]
	v_mfma_f32_16x16x32_bf16 v[6:9], v[150:153], v[170:173], v[6:9]
	v_mfma_f32_16x16x32_bf16 v[18:21], v[158:161], v[170:173], v[18:21]
	v_mfma_f32_16x16x32_bf16 v[78:81], v[158:161], v[178:181], v[78:81]
	v_mfma_f32_16x16x32_bf16 v[50:53], v[150:153], v[178:181], v[50:53]
	v_mfma_f32_16x16x32_bf16 v[98:101], v[150:153], v[186:189], v[98:101]
	v_mfma_f32_16x16x32_bf16 v[110:113], v[158:161], v[186:189], v[110:113]
	v_mfma_f32_16x16x32_bf16 v[126:129], v[158:161], v[200:203], v[126:129]
	v_mfma_f32_16x16x32_bf16 v[114:117], v[150:153], v[200:203], v[114:117]
	v_mfma_f32_16x16x32_bf16 v[6:9], v[154:157], v[174:177], v[6:9]
	v_mfma_f32_16x16x32_bf16 v[18:21], v[166:169], v[174:177], v[18:21]
	v_mfma_f32_16x16x32_bf16 v[78:81], v[166:169], v[182:185], v[78:81]
	v_mfma_f32_16x16x32_bf16 v[50:53], v[154:157], v[182:185], v[50:53]
	v_mfma_f32_16x16x32_bf16 v[98:101], v[154:157], v[190:193], v[98:101]
	v_mfma_f32_16x16x32_bf16 v[110:113], v[166:169], v[190:193], v[110:113]
	v_mfma_f32_16x16x32_bf16 v[126:129], v[166:169], v[206:209], v[126:129]
	v_mfma_f32_16x16x32_bf16 v[114:117], v[154:157], v[206:209], v[114:117]
	s_barrier
	s_setprio 0
	s_cselect_b32 s76, s20, s76
	s_mov_b32 m0, s26
	s_mov_b32 s42, s6
	s_mov_b32 s43, s7
	s_sub_i32 s76, s76, s40
	ds_read_b128 v[170:173], v132 offset:16384
	ds_read_b128 v[174:177], v132 offset:17408
	ds_read_b128 v[178:181], v132 offset:18432
	ds_read_b128 v[182:185], v132 offset:19456
	ds_read_b128 v[186:189], v132 offset:20480
	ds_read_b128 v[190:193], v132 offset:21504
	ds_read_b128 v[200:203], v132 offset:22528
	ds_read_b128 v[206:209], v132 offset:23552
	buffer_load_dwordx4 v0, s[40:43], s76 offen lds
	s_mov_b32 m0, s44
	s_add_i32 s78, s76, 0x160000
	buffer_load_dwordx4 v130, s[40:43], s76 offen lds
	s_mov_b32 m0, s45
	s_sub_i32 s77, s77, s4
	buffer_load_dwordx4 v0, s[40:43], s78 offen lds
	s_mov_b32 m0, s46
	s_nop 0
	buffer_load_dwordx4 v130, s[40:43], s78 offen lds
	s_mov_b32 m0, s19
	s_nop 0
	buffer_load_dwordx4 v0, s[4:7], s77 offen lds
	s_waitcnt vmcnt(7)
	s_waitcnt lgkmcnt(0)
	s_setprio 1
	s_barrier
	v_mfma_f32_16x16x32_bf16 v[62:65], v[134:137], v[170:173], v[62:65]
	v_mfma_f32_16x16x32_bf16 v[46:49], v[142:145], v[170:173], v[46:49]
	v_mfma_f32_16x16x32_bf16 v[70:73], v[142:145], v[178:181], v[70:73]
	v_mfma_f32_16x16x32_bf16 v[82:85], v[134:137], v[178:181], v[82:85]
	v_mfma_f32_16x16x32_bf16 v[94:97], v[134:137], v[186:189], v[94:97]
	v_mfma_f32_16x16x32_bf16 v[90:93], v[142:145], v[186:189], v[90:93]
	v_mfma_f32_16x16x32_bf16 v[26:29], v[142:145], v[200:203], v[26:29]
	v_mfma_f32_16x16x32_bf16 v[38:41], v[134:137], v[200:203], v[38:41]
	v_mfma_f32_16x16x32_bf16 v[62:65], v[138:141], v[174:177], v[62:65]
	v_mfma_f32_16x16x32_bf16 v[46:49], v[146:149], v[174:177], v[46:49]
	v_mfma_f32_16x16x32_bf16 v[70:73], v[146:149], v[182:185], v[70:73]
	v_mfma_f32_16x16x32_bf16 v[82:85], v[138:141], v[182:185], v[82:85]
	v_mfma_f32_16x16x32_bf16 v[94:97], v[138:141], v[190:193], v[94:97]
	v_mfma_f32_16x16x32_bf16 v[90:93], v[146:149], v[190:193], v[90:93]
	v_mfma_f32_16x16x32_bf16 v[26:29], v[146:149], v[206:209], v[26:29]
	v_mfma_f32_16x16x32_bf16 v[38:41], v[138:141], v[206:209], v[38:41]
	v_mfma_f32_16x16x32_bf16 v[42:45], v[150:153], v[170:173], v[42:45]
	v_mfma_f32_16x16x32_bf16 v[30:33], v[158:161], v[170:173], v[30:33]
	v_mfma_f32_16x16x32_bf16 v[86:89], v[158:161], v[178:181], v[86:89]
	v_mfma_f32_16x16x32_bf16 v[66:69], v[150:153], v[178:181], v[66:69]
	v_mfma_f32_16x16x32_bf16 v[58:61], v[150:153], v[186:189], v[58:61]
	v_mfma_f32_16x16x32_bf16 v[34:37], v[158:161], v[186:189], v[34:37]
	v_mfma_f32_16x16x32_bf16 v[2:5], v[158:161], v[200:203], v[2:5]
	v_mfma_f32_16x16x32_bf16 v[10:13], v[150:153], v[200:203], v[10:13]
	v_mfma_f32_16x16x32_bf16 v[42:45], v[154:157], v[174:177], v[42:45]
	v_mfma_f32_16x16x32_bf16 v[30:33], v[166:169], v[174:177], v[30:33]
	v_mfma_f32_16x16x32_bf16 v[86:89], v[166:169], v[182:185], v[86:89]
	v_mfma_f32_16x16x32_bf16 v[66:69], v[154:157], v[182:185], v[66:69]
	v_mfma_f32_16x16x32_bf16 v[58:61], v[154:157], v[190:193], v[58:61]
	v_mfma_f32_16x16x32_bf16 v[34:37], v[166:169], v[190:193], v[34:37]
	v_mfma_f32_16x16x32_bf16 v[2:5], v[166:169], v[206:209], v[2:5]
	v_mfma_f32_16x16x32_bf16 v[10:13], v[154:157], v[206:209], v[10:13]
	s_barrier
; #define PG8_STAGE(bufoff, gbase, voff) do { const int so_ = (int)(unsigned)((const char*)(gbase) - base_##voff); _Pragma("unroll") for (int _i = 0; _i < 2; ++_i) \
;         __builtin_amdgcn_raw_ptr_buffer_load_lds(rs_##voff, (PG8_LAS unsigned*)(lds + (bufoff) + ldsw + _i * 8192), 16, (int)(voff)[_i], so_, 0, 0); } while (0)
; #define PG8_LDA(dst, b, h) do { _Pragma("unroll") for (int m = 0; m < 4; ++m) _Pragma("unroll") for (int k = 0; k < 2; ++k) dst[m][k] = *(const PG8_LAS bf16x8*)(lds + PG8_SA(b, h) + aoff + m * 2048 + k * 1024); } while (0)
; #define PG8_LDB(dst, b, h) do { _Pragma("unroll") for (int n = 0; n < 2; ++n) _Pragma("unroll") for (int k = 0; k < 2; ++k) dst[n][k] = *(const PG8_LAS bf16x8*)(lds + PG8_SB(b, h) + boff + n * 2048 + k * 1024); } while (0)
; #define PG8_MMA(ai, bj, At, Bt) do { __builtin_amdgcn_s_setprio(1); _Pragma("unroll") for (int m = 0; m < 4; ++m) _Pragma("unroll") for (int n = 0; n < 2; ++n) _Pragma("unroll") for (int k = 0; k < 2; ++k) \
;         acc[ai][bj][m][n] = __builtin_amdgcn_mfma_f32_16x16x32_bf16(Bt[n][k], At[m][k], acc[ai][bj][m][n], 0, 0, 0); __builtin_amdgcn_s_setprio(0); } while (0)
; #define PG8_WAIT_V(n) asm volatile("s_waitcnt vmcnt(" #n ")" ::: "memory")
; #define PG8_WAIT_L(n) asm volatile("s_waitcnt lgkmcnt(" #n ")" ::: "memory")
; #define PG8_BAR __builtin_amdgcn_s_barrier()
; #define PG8_SCHED __builtin_amdgcn_sched_barrier(0)
; template <class Epi, class Sched, bool ALIGN_EPI = false, bool SP2 = false>
; __device__ __forceinline__ void gemm_phase(PG8_LAS unsigned char* lds, const Gemm g, const Sched& S, const Epi& E, int tid_in) {
;     ...
;             PG8_LDB(B0, 1, 0); PG8_LDB(B1, 1, 1); PG8_SCHED; PG8_LDA(At, 1, 0); PG8_STAGE(PG8_SA(0, 1), a2 + hstepA, voffA);
;             PG8_WAIT_V(8); PG8_WAIT_L(0); PG8_BAR; PG8_MMA(0, 0, At, B0); PG8_MMA(0, 1, At, B1); PG8_BAR; PG8_SCHED;
;             PG8_LDA(At, 1, 1); PG8_STAGE(PG8_SB(1, 0), b3, voffB); PG8_STAGE(PG8_SB(1, 1), b3 + hstepB, voffB); PG8_STAGE(PG8_SA(1, 0), a3, voffA);
	s_setprio 0
	ds_read_b128 v[134:137], v251 offset:32768
	ds_read_b128 v[138:141], v251 offset:33792
	ds_read_b128 v[142:145], v251 offset:34816
	ds_read_b128 v[146:149], v251 offset:35840
	ds_read_b128 v[150:153], v251 offset:49152
	ds_read_b128 v[154:157], v251 offset:50176
	ds_read_b128 v[158:161], v251 offset:51200
	ds_read_b128 v[166:169], v251 offset:52224
	s_add_i32 s78, s77, 0x160000
	s_mov_b32 m0, s48
	ds_read_b128 v[170:173], v132 offset:32768
	ds_read_b128 v[174:177], v132 offset:33792
	ds_read_b128 v[178:181], v132 offset:34816
	ds_read_b128 v[182:185], v132 offset:35840
	ds_read_b128 v[186:189], v132 offset:36864
	ds_read_b128 v[190:193], v132 offset:37888
	ds_read_b128 v[200:203], v132 offset:38912
	ds_read_b128 v[206:209], v132 offset:39936
	s_mov_b32 m0, s47
	s_nop 0
	buffer_load_dwordx4 v130, s[4:7], s77 offen lds
	s_mov_b32 m0, s48
	s_nop 0
	buffer_load_dwordx4 v0, s[4:7], s78 offen lds
	s_mov_b32 m0, s49
	s_nop 0
	buffer_load_dwordx4 v130, s[4:7], s78 offen lds
	s_waitcnt vmcnt(8)
	s_waitcnt lgkmcnt(0)
	s_setprio 1
	s_barrier
	v_mfma_f32_16x16x32_bf16 v[22:25], v[134:137], v[170:173], v[22:25]
	v_mfma_f32_16x16x32_bf16 v[14:17], v[142:145], v[170:173], v[14:17]
	v_mfma_f32_16x16x32_bf16 v[54:57], v[142:145], v[178:181], v[54:57]
	v_mfma_f32_16x16x32_bf16 v[74:77], v[134:137], v[178:181], v[74:77]
	v_mfma_f32_16x16x32_bf16 v[106:109], v[134:137], v[186:189], v[106:109]
	v_mfma_f32_16x16x32_bf16 v[102:105], v[142:145], v[186:189], v[102:105]
	v_mfma_f32_16x16x32_bf16 v[118:121], v[142:145], v[200:203], v[118:121]
	v_mfma_f32_16x16x32_bf16 v[122:125], v[134:137], v[200:203], v[122:125]
	v_mfma_f32_16x16x32_bf16 v[22:25], v[138:141], v[174:177], v[22:25]
	v_mfma_f32_16x16x32_bf16 v[14:17], v[146:149], v[174:177], v[14:17]
	v_mfma_f32_16x16x32_bf16 v[54:57], v[146:149], v[182:185], v[54:57]
	v_mfma_f32_16x16x32_bf16 v[74:77], v[138:141], v[182:185], v[74:77]
	v_mfma_f32_16x16x32_bf16 v[106:109], v[138:141], v[190:193], v[106:109]
	v_mfma_f32_16x16x32_bf16 v[102:105], v[146:149], v[190:193], v[102:105]
	v_mfma_f32_16x16x32_bf16 v[118:121], v[146:149], v[206:209], v[118:121]
	v_mfma_f32_16x16x32_bf16 v[122:125], v[138:141], v[206:209], v[122:125]
	v_mfma_f32_16x16x32_bf16 v[6:9], v[150:153], v[170:173], v[6:9]
	v_mfma_f32_16x16x32_bf16 v[18:21], v[158:161], v[170:173], v[18:21]
	v_mfma_f32_16x16x32_bf16 v[78:81], v[158:161], v[178:181], v[78:81]
	v_mfma_f32_16x16x32_bf16 v[50:53], v[150:153], v[178:181], v[50:53]
	v_mfma_f32_16x16x32_bf16 v[98:101], v[150:153], v[186:189], v[98:101]
	v_mfma_f32_16x16x32_bf16 v[110:113], v[158:161], v[186:189], v[110:113]
	v_mfma_f32_16x16x32_bf16 v[126:129], v[158:161], v[200:203], v[126:129]
	v_mfma_f32_16x16x32_bf16 v[114:117], v[150:153], v[200:203], v[114:117]
	v_mfma_f32_16x16x32_bf16 v[6:9], v[154:157], v[174:177], v[6:9]
	v_mfma_f32_16x16x32_bf16 v[18:21], v[166:169], v[174:177], v[18:21]
	v_mfma_f32_16x16x32_bf16 v[78:81], v[166:169], v[182:185], v[78:81]
	v_mfma_f32_16x16x32_bf16 v[50:53], v[154:157], v[182:185], v[50:53]
	v_mfma_f32_16x16x32_bf16 v[98:101], v[154:157], v[190:193], v[98:101]
	v_mfma_f32_16x16x32_bf16 v[110:113], v[166:169], v[190:193], v[110:113]
	v_mfma_f32_16x16x32_bf16 v[126:129], v[166:169], v[206:209], v[126:129]
	v_mfma_f32_16x16x32_bf16 v[114:117], v[154:157], v[206:209], v[114:117]
	s_barrier
	s_setprio 0
	s_mov_b32 m0, s60
	s_add_i32 s78, s76, 0x80
	ds_read_b128 v[170:173], v132 offset:49152
	ds_read_b128 v[174:177], v132 offset:50176
	ds_read_b128 v[178:181], v132 offset:51200
	ds_read_b128 v[182:185], v132 offset:52224
	ds_read_b128 v[186:189], v132 offset:53248
	ds_read_b128 v[190:193], v132 offset:54272
	ds_read_b128 v[200:203], v132 offset:55296
	ds_read_b128 v[206:209], v132 offset:56320
	buffer_load_dwordx4 v0, s[40:43], s78 offen lds
	s_mov_b32 m0, s61
	s_add_i32 s76, s76, 0x160080
	buffer_load_dwordx4 v130, s[40:43], s78 offen lds
	s_mov_b32 m0, s66
	s_addk_i32 s77, 0x80
	buffer_load_dwordx4 v0, s[40:43], s76 offen lds
	s_mov_b32 m0, s67
	s_nop 0
	buffer_load_dwordx4 v130, s[40:43], s76 offen lds
	s_mov_b32 m0, s62
	s_nop 0
	buffer_load_dwordx4 v0, s[4:7], s77 offen lds
	s_waitcnt vmcnt(7)
	s_waitcnt lgkmcnt(0)
	s_setprio 1
	s_barrier
;     static __device__ __forceinline__ bool last_of_chain(const Unit& u) { return (u.pn >> 3) == 2; }
; #define PG8_STAGE(bufoff, gbase, voff) do { const int so_ = (int)(unsigned)((const char*)(gbase) - base_##voff); _Pragma("unroll") for (int _i = 0; _i < 2; ++_i) \
;         __builtin_amdgcn_raw_ptr_buffer_load_lds(rs_##voff, (PG8_LAS unsigned*)(lds + (bufoff) + ldsw + _i * 8192), 16, (int)(voff)[_i], so_, 0, 0); } while (0)
; #define PG8_LDA(dst, b, h) do { _Pragma("unroll") for (int m = 0; m < 4; ++m) _Pragma("unroll") for (int k = 0; k < 2; ++k) dst[m][k] = *(const PG8_LAS bf16x8*)(lds + PG8_SA(b, h) + aoff + m * 2048 + k * 1024); } while (0)
; #define PG8_MMA(ai, bj, At, Bt) do { __builtin_amdgcn_s_setprio(1); _Pragma("unroll") for (int m = 0; m < 4; ++m) _Pragma("unroll") for (int n = 0; n < 2; ++n) _Pragma("unroll") for (int k = 0; k < 2; ++k) \
;         acc[ai][bj][m][n] = __builtin_amdgcn_mfma_f32_16x16x32_bf16(Bt[n][k], At[m][k], acc[ai][bj][m][n], 0, 0, 0); __builtin_amdgcn_s_setprio(0); } while (0)
; #define PG8_WAIT_V(n) asm volatile("s_waitcnt vmcnt(" #n ")" ::: "memory")
; #define PG8_WAIT_L(n) asm volatile("s_waitcnt lgkmcnt(" #n ")" ::: "memory")
; #define PG8_BAR __builtin_amdgcn_s_barrier()
; #define PG8_SCHED __builtin_amdgcn_sched_barrier(0)
; template <class Epi, class Sched, bool ALIGN_EPI = false, bool SP2 = false>
; __device__ __forceinline__ void gemm_phase(PG8_LAS unsigned char* lds, const Gemm g, const Sched& S, const Epi& E, int tid_in) {
;     ...
;             PG8_WAIT_V(8); PG8_WAIT_L(0); PG8_BAR; PG8_MMA(0, 0, At, B0); PG8_MMA(0, 1, At, B1); PG8_BAR; PG8_SCHED;
;             PG8_LDA(At, 1, 1); PG8_STAGE(PG8_SB(1, 0), b3, voffB); PG8_STAGE(PG8_SB(1, 1), b3 + hstepB, voffB); PG8_STAGE(PG8_SA(1, 0), a3, voffA);
;             PG8_WAIT_V(8); PG8_WAIT_L(0); PG8_BAR; PG8_MMA(1, 0, At, B0); PG8_MMA(1, 1, At, B1); PG8_BAR; PG8_SCHED;
;     ...
;         bool zero_acc = true; if constexpr (Epi::CHAIN) zero_acc = Epi::last_of_chain(cur);
;         if (zero_acc) {
; #pragma unroll
;         for (int a = 0; a < 2; ++a)
; #pragma unroll
;             for (int b = 0; b < 2; ++b)
; #pragma unroll
;                 for (int m = 0; m < 4; ++m)
; #pragma unroll
;                     for (int n = 0; n < 2; ++n) acc[a][b][m][n] = (f32x4){0.f, 0.f, 0.f, 0.f};
;         }
	v_mfma_f32_16x16x32_bf16 v[62:65], v[134:137], v[170:173], v[62:65]
	v_mfma_f32_16x16x32_bf16 v[46:49], v[142:145], v[170:173], v[46:49]
	v_mfma_f32_16x16x32_bf16 v[70:73], v[142:145], v[178:181], v[70:73]
	v_mfma_f32_16x16x32_bf16 v[82:85], v[134:137], v[178:181], v[82:85]
	v_mfma_f32_16x16x32_bf16 v[94:97], v[134:137], v[186:189], v[94:97]
	v_mfma_f32_16x16x32_bf16 v[90:93], v[142:145], v[186:189], v[90:93]
	v_mfma_f32_16x16x32_bf16 v[26:29], v[142:145], v[200:203], v[26:29]
	v_mfma_f32_16x16x32_bf16 v[38:41], v[134:137], v[200:203], v[38:41]
	v_mfma_f32_16x16x32_bf16 v[62:65], v[138:141], v[174:177], v[62:65]
	v_mfma_f32_16x16x32_bf16 v[46:49], v[146:149], v[174:177], v[46:49]
	v_mfma_f32_16x16x32_bf16 v[70:73], v[146:149], v[182:185], v[70:73]
	v_mfma_f32_16x16x32_bf16 v[82:85], v[138:141], v[182:185], v[82:85]
	v_mfma_f32_16x16x32_bf16 v[94:97], v[138:141], v[190:193], v[94:97]
	v_mfma_f32_16x16x32_bf16 v[90:93], v[146:149], v[190:193], v[90:93]
	v_mfma_f32_16x16x32_bf16 v[26:29], v[146:149], v[206:209], v[26:29]
	v_mfma_f32_16x16x32_bf16 v[38:41], v[138:141], v[206:209], v[38:41]
	v_mfma_f32_16x16x32_bf16 v[42:45], v[150:153], v[170:173], v[42:45]
	v_mfma_f32_16x16x32_bf16 v[30:33], v[158:161], v[170:173], v[30:33]
	v_mfma_f32_16x16x32_bf16 v[86:89], v[158:161], v[178:181], v[86:89]
	v_mfma_f32_16x16x32_bf16 v[66:69], v[150:153], v[178:181], v[66:69]
	v_mfma_f32_16x16x32_bf16 v[58:61], v[150:153], v[186:189], v[58:61]
	v_mfma_f32_16x16x32_bf16 v[34:37], v[158:161], v[186:189], v[34:37]
	v_mfma_f32_16x16x32_bf16 v[2:5], v[158:161], v[200:203], v[2:5]
	v_mfma_f32_16x16x32_bf16 v[10:13], v[150:153], v[200:203], v[10:13]
	v_mfma_f32_16x16x32_bf16 v[42:45], v[154:157], v[174:177], v[42:45]
	v_mfma_f32_16x16x32_bf16 v[30:33], v[166:169], v[174:177], v[30:33]
	v_mfma_f32_16x16x32_bf16 v[86:89], v[166:169], v[182:185], v[86:89]
	v_mfma_f32_16x16x32_bf16 v[66:69], v[154:157], v[182:185], v[66:69]
	v_mfma_f32_16x16x32_bf16 v[58:61], v[154:157], v[190:193], v[58:61]
	v_mfma_f32_16x16x32_bf16 v[34:37], v[166:169], v[190:193], v[34:37]
	v_mfma_f32_16x16x32_bf16 v[2:5], v[166:169], v[206:209], v[2:5]
	v_mfma_f32_16x16x32_bf16 v[10:13], v[154:157], v[206:209], v[10:13]
	s_barrier
	s_setprio 0
	s_add_i32 s39, s39, 2
	s_add_u32 s22, s22, 0x100
	s_addc_u32 s23, s23, 0
	s_cmpk_gt_u32 s39, 0x55
	s_cbranch_scc0 .LBB0_1584
	s_and_b64 vcc, exec, s[36:37]
	s_cbranch_vccnz .LBB0_1572
	v_mov_b32_e32 v2, 0
	s_mov_b32 s10, s73
	s_mov_b32 s25, s74
	s_mov_b64 s[12:13], s[20:21]
	s_mov_b64 s[14:15], s[16:17]
	s_mov_b32 s72, s75
	v_mov_b32_e32 v3, v2
	v_mov_b32_e32 v4, v2
	v_mov_b32_e32 v5, v2
	v_mov_b32_e32 v10, v2
	v_mov_b32_e32 v11, v2
	v_mov_b32_e32 v12, v2
	v_mov_b32_e32 v13, v2
	v_mov_b32_e32 v34, v2
	v_mov_b32_e32 v35, v2
	v_mov_b32_e32 v36, v2
	v_mov_b32_e32 v37, v2
	v_mov_b32_e32 v58, v2
	v_mov_b32_e32 v59, v2
	v_mov_b32_e32 v60, v2
	v_mov_b32_e32 v61, v2
	v_mov_b32_e32 v86, v2
	v_mov_b32_e32 v87, v2
	v_mov_b32_e32 v88, v2
	v_mov_b32_e32 v89, v2
	v_mov_b32_e32 v66, v2
	v_mov_b32_e32 v67, v2
	v_mov_b32_e32 v68, v2
	v_mov_b32_e32 v69, v2
	v_mov_b32_e32 v30, v2
	v_mov_b32_e32 v31, v2
	v_mov_b32_e32 v32, v2
	v_mov_b32_e32 v33, v2
	v_mov_b32_e32 v42, v2
	v_mov_b32_e32 v43, v2
	v_mov_b32_e32 v44, v2
	v_mov_b32_e32 v45, v2
	v_mov_b32_e32 v26, v2
	v_mov_b32_e32 v27, v2
	v_mov_b32_e32 v28, v2
	v_mov_b32_e32 v29, v2
	v_mov_b32_e32 v38, v2
	v_mov_b32_e32 v39, v2
	v_mov_b32_e32 v40, v2
	v_mov_b32_e32 v41, v2
	v_mov_b32_e32 v90, v2
	v_mov_b32_e32 v91, v2
	v_mov_b32_e32 v92, v2
	v_mov_b32_e32 v93, v2
	v_mov_b32_e32 v94, v2
	v_mov_b32_e32 v95, v2
	v_mov_b32_e32 v96, v2
	v_mov_b32_e32 v97, v2
	v_mov_b32_e32 v70, v2
	v_mov_b32_e32 v71, v2
	v_mov_b32_e32 v72, v2
	v_mov_b32_e32 v73, v2
	v_mov_b32_e32 v82, v2
	v_mov_b32_e32 v83, v2
	v_mov_b32_e32 v84, v2
	v_mov_b32_e32 v85, v2
	v_mov_b32_e32 v46, v2
	v_mov_b32_e32 v47, v2
	v_mov_b32_e32 v48, v2
	v_mov_b32_e32 v49, v2
	v_mov_b32_e32 v62, v2
	v_mov_b32_e32 v63, v2
	v_mov_b32_e32 v64, v2
	v_mov_b32_e32 v65, v2
	v_mov_b32_e32 v126, v2
	v_mov_b32_e32 v127, v2
	v_mov_b32_e32 v128, v2
	v_mov_b32_e32 v129, v2
	v_mov_b32_e32 v114, v2
	v_mov_b32_e32 v115, v2
	v_mov_b32_e32 v116, v2
	v_mov_b32_e32 v117, v2
	v_mov_b32_e32 v110, v2
	v_mov_b32_e32 v111, v2
	v_mov_b32_e32 v112, v2
	v_mov_b32_e32 v113, v2
	v_mov_b32_e32 v98, v2
	v_mov_b32_e32 v99, v2
	v_mov_b32_e32 v100, v2
	v_mov_b32_e32 v101, v2
	v_mov_b32_e32 v78, v2
	v_mov_b32_e32 v79, v2
	v_mov_b32_e32 v80, v2
	v_mov_b32_e32 v81, v2
	v_mov_b32_e32 v50, v2
	v_mov_b32_e32 v51, v2
	v_mov_b32_e32 v52, v2
	v_mov_b32_e32 v53, v2
	v_mov_b32_e32 v18, v2
	v_mov_b32_e32 v19, v2
	v_mov_b32_e32 v20, v2
	v_mov_b32_e32 v21, v2
	v_mov_b32_e32 v6, v2
	v_mov_b32_e32 v7, v2
	v_mov_b32_e32 v8, v2
	v_mov_b32_e32 v9, v2
	v_mov_b32_e32 v118, v2
	v_mov_b32_e32 v119, v2
	v_mov_b32_e32 v120, v2
	v_mov_b32_e32 v121, v2
	v_mov_b32_e32 v122, v2
	v_mov_b32_e32 v123, v2
	v_mov_b32_e32 v124, v2
	v_mov_b32_e32 v125, v2
	v_mov_b32_e32 v102, v2
	v_mov_b32_e32 v103, v2
	v_mov_b32_e32 v104, v2
	v_mov_b32_e32 v105, v2
	v_mov_b32_e32 v106, v2
	v_mov_b32_e32 v107, v2
	v_mov_b32_e32 v108, v2
	v_mov_b32_e32 v109, v2
	v_mov_b32_e32 v54, v2
	v_mov_b32_e32 v55, v2
	v_mov_b32_e32 v56, v2
	v_mov_b32_e32 v57, v2
	v_mov_b32_e32 v74, v2
	v_mov_b32_e32 v75, v2
	v_mov_b32_e32 v76, v2
	v_mov_b32_e32 v77, v2
	v_mov_b32_e32 v14, v2
	v_mov_b32_e32 v15, v2
	v_mov_b32_e32 v16, v2
	v_mov_b32_e32 v17, v2
	v_mov_b32_e32 v22, v2
	v_mov_b32_e32 v23, v2
	v_mov_b32_e32 v24, v2
	v_mov_b32_e32 v25, v2
	s_branch .LBB0_1572
